# handoff N=1 prio2 + loader raises prio before its closing barrier, first no-op lgkmcnt wait removed
# speedup vs baseline: 1.0054x; 1.0054x over previous
; #define PG8_STAGE(bufoff, gbase, voff) do { _Pragma("unroll") for (int _i = 0; _i < 2; ++_i) \
;         asm volatile("s_mov_b32 m0, %2\n\ts_nop 0\n\tglobal_load_lds_dwordx4 %0, %1" :: "v"((voff)[_i]), "s"((const char*)(gbase)), "s"(ldsbase + (unsigned)(bufoff) + ldsw + (unsigned)_i * 8192u) : "memory", "m0"); } while (0)
; #define PG8_LDA(dst, b, h) do { _Pragma("unroll") for (int m = 0; m < 4; ++m) _Pragma("unroll") for (int k = 0; k < 2; ++k) dst[m][k] = *(const PG8_LAS bf16x8*)(lds + PG8_SA(b, h) + aoff + m * 2048 + k * 1024); } while (0)
; #define PG8_WAIT_V(n) asm volatile("s_waitcnt vmcnt(" #n ")" ::: "memory")
; template <class Epi, class Sched, bool ALIGN_EPI = false, bool SP2 = false>
; __device__ __forceinline__ void gemm_phase(PG8_LAS unsigned char* lds, const Gemm g, const Sched& S, const Epi& E) {
;     ...
;             const bool last = (t == nt - 2);
;             const char* a1 = cA + (size_t)(t + 1) * kstep;
;             const char* a2 = last ? nA : cA + (size_t)(t + 2) * kstep; const char* b2 = last ? nB : cB + (size_t)(t + 2) * kstep;
;             const char* a3 = a2 + kstep; const char* b3 = b2 + kstep;
;             if (last && has_next) S.a_ready(nxt);
;             if constexpr (epi_has_mid<Epi>::value) { if (t == Epi::MID_T) E.mid(acc, cur, wr, wc, fr, fq); }
;             if constexpr (SP2) {
;             PG8_LDB(B0, 0, 0); PG8_LDB(B1, 0, 1); PG8_SCHED; PG8_LDA(At, 0, 0); PG8_STAGE(PG8_SA(1, 1), a1 + hstep, voffA);
;             PG8_WAIT_V(8); PG8_WAIT_L(0); PG8_BAR; PG8_MMA(0, 0, At, B0); PG8_MMA(0, 1, At, B1); PG8_BAR; PG8_SCHED;
;             PG8_LDA(At, 0, 1); PG8_STAGE(PG8_SB(0, 0), b2, voffB); PG8_STAGE(PG8_SB(0, 1), b2 + hstep, voffB); PG8_STAGE(PG8_SA(0, 0), a2, voffA);
;             PG8_WAIT_V(8); PG8_WAIT_L(0); PG8_BAR; PG8_MMA(1, 0, At, B0); PG8_MMA(1, 1, At, B1); PG8_BAR; PG8_SCHED;
;             PG8_LDB(B0, 1, 0); PG8_LDB(B1, 1, 1); PG8_SCHED; PG8_LDA(At, 1, 0); PG8_STAGE(PG8_SA(0, 1), a2 + hstep, voffA);
;             PG8_WAIT_V(8); PG8_WAIT_L(0); PG8_BAR; PG8_MMA(0, 0, At, B0); PG8_MMA(0, 1, At, B1); PG8_BAR; PG8_SCHED;
;             PG8_LDA(At, 1, 1); PG8_STAGE(PG8_SB(1, 0), b3, voffB); PG8_STAGE(PG8_SB(1, 1), b3 + hstep, voffB); PG8_STAGE(PG8_SA(1, 0), a3, voffA);
;             PG8_WAIT_V(8); PG8_WAIT_L(0); PG8_BAR; PG8_MMA(1, 0, At, B0); PG8_MMA(1, 1, At, B1); PG8_BAR; PG8_SCHED;
.LBB0_138:
	ds_read_b128 v[148:151], v142
	ds_read_b128 v[152:155], v142 offset:1024
	ds_read_b128 v[156:159], v142 offset:2048
	ds_read_b128 v[160:163], v142 offset:3072
	ds_read_b128 v[164:167], v143
	ds_read_b128 v[168:171], v143 offset:1024
	ds_read_b128 v[172:175], v143 offset:2048
	ds_read_b128 v[176:179], v143 offset:3072
	s_add_u32 s62, s66, 0x100
	s_addc_u32 s63, s67, 0
	s_cmp_eq_u32 s96, 60
	s_cselect_b32 s86, s92, s62
	s_cselect_b32 s87, s13, s63
	s_cselect_b32 s84, s93, s94
	s_cselect_b32 s85, s11, s95
	s_add_u32 s76, s86, 0x80
	s_addc_u32 s77, s87, 0
	ds_read_b128 v[180:183], v144
	ds_read_b128 v[184:187], v144 offset:1024
	ds_read_b128 v[188:191], v144 offset:2048
	ds_read_b128 v[192:195], v144 offset:3072
	ds_read_b128 v[196:199], v144 offset:4096
	ds_read_b128 v[200:203], v144 offset:5120
	ds_read_b128 v[204:207], v144 offset:6144
	ds_read_b128 v[208:211], v144 offset:7168
	s_add_u32 s66, s66, 0x100080
	s_addc_u32 s67, s67, 0
	s_mov_b32 m0, s83
	s_nop 0
	global_load_lds_dwordx4 v136, s[66:67]
	s_nop 0
	s_mov_b32 m0, s88
	s_nop 0
	global_load_lds_dwordx4 v138, s[66:67]
	s_waitcnt vmcnt(8)
	s_waitcnt lgkmcnt(0)
	s_setprio 1
	s_barrier
	v_mfma_f32_16x16x32_bf16 v[126:129], v[148:151], v[180:183], v[126:129]
	v_mfma_f32_16x16x32_bf16 v[122:125], v[156:159], v[180:183], v[122:125]
	s_waitcnt lgkmcnt(5)
	v_mfma_f32_16x16x32_bf16 v[110:113], v[148:151], v[188:191], v[110:113]
	v_mfma_f32_16x16x32_bf16 v[106:109], v[156:159], v[188:191], v[106:109]
	s_waitcnt lgkmcnt(3)
	v_mfma_f32_16x16x32_bf16 v[94:97], v[148:151], v[196:199], v[94:97]
	v_mfma_f32_16x16x32_bf16 v[90:93], v[156:159], v[196:199], v[90:93]
	s_waitcnt lgkmcnt(1)
	v_mfma_f32_16x16x32_bf16 v[78:81], v[148:151], v[204:207], v[78:81]
	v_mfma_f32_16x16x32_bf16 v[74:77], v[156:159], v[204:207], v[74:77]
	v_mfma_f32_16x16x32_bf16 v[126:129], v[152:155], v[184:187], v[126:129]
	v_mfma_f32_16x16x32_bf16 v[122:125], v[160:163], v[184:187], v[122:125]
	v_mfma_f32_16x16x32_bf16 v[110:113], v[152:155], v[192:195], v[110:113]
	v_mfma_f32_16x16x32_bf16 v[106:109], v[160:163], v[192:195], v[106:109]
	v_mfma_f32_16x16x32_bf16 v[94:97], v[152:155], v[200:203], v[94:97]
	v_mfma_f32_16x16x32_bf16 v[90:93], v[160:163], v[200:203], v[90:93]
	s_waitcnt lgkmcnt(0)
	v_mfma_f32_16x16x32_bf16 v[78:81], v[152:155], v[208:211], v[78:81]
	v_mfma_f32_16x16x32_bf16 v[74:77], v[160:163], v[208:211], v[74:77]
	s_setprio 0
	s_setprio 1
	v_mfma_f32_16x16x32_bf16 v[118:121], v[164:167], v[180:183], v[118:121]
	v_mfma_f32_16x16x32_bf16 v[114:117], v[172:175], v[180:183], v[114:117]
	v_mfma_f32_16x16x32_bf16 v[102:105], v[164:167], v[188:191], v[102:105]
	v_mfma_f32_16x16x32_bf16 v[98:101], v[172:175], v[188:191], v[98:101]
	v_mfma_f32_16x16x32_bf16 v[86:89], v[164:167], v[196:199], v[86:89]
	v_mfma_f32_16x16x32_bf16 v[82:85], v[172:175], v[196:199], v[82:85]
	v_mfma_f32_16x16x32_bf16 v[70:73], v[164:167], v[204:207], v[70:73]
	v_mfma_f32_16x16x32_bf16 v[66:69], v[172:175], v[204:207], v[66:69]
	v_mfma_f32_16x16x32_bf16 v[118:121], v[168:171], v[184:187], v[118:121]
	v_mfma_f32_16x16x32_bf16 v[114:117], v[176:179], v[184:187], v[114:117]
	v_mfma_f32_16x16x32_bf16 v[102:105], v[168:171], v[192:195], v[102:105]
	v_mfma_f32_16x16x32_bf16 v[98:101], v[176:179], v[192:195], v[98:101]
	v_mfma_f32_16x16x32_bf16 v[86:89], v[168:171], v[200:203], v[86:89]
	v_mfma_f32_16x16x32_bf16 v[82:85], v[176:179], v[200:203], v[82:85]
	v_mfma_f32_16x16x32_bf16 v[70:73], v[168:171], v[208:211], v[70:73]
	s_setprio 2
	s_barrier
	v_mfma_f32_16x16x32_bf16 v[66:69], v[176:179], v[208:211], v[66:69]
	s_setprio 0
	ds_read_b128 v[180:183], v144 offset:16384
	ds_read_b128 v[184:187], v144 offset:17408
	ds_read_b128 v[188:191], v144 offset:18432
	ds_read_b128 v[192:195], v144 offset:19456
	ds_read_b128 v[196:199], v144 offset:20480
	ds_read_b128 v[200:203], v144 offset:21504
	ds_read_b128 v[204:207], v144 offset:22528
	ds_read_b128 v[208:211], v144 offset:23552
	s_mov_b32 m0, s55
	s_nop 0
	global_load_lds_dwordx4 v137, s[84:85]
	s_add_u32 s66, s84, 0x100000
	s_mov_b32 m0, s56
	s_nop 0
	global_load_lds_dwordx4 v139, s[84:85]
	s_addc_u32 s67, s85, 0
	s_mov_b32 m0, s57
	s_nop 0
	global_load_lds_dwordx4 v137, s[66:67]
	s_nop 0
	s_mov_b32 m0, s58
	s_nop 0
	global_load_lds_dwordx4 v139, s[66:67]
	s_nop 0
	s_mov_b32 m0, s54
	s_nop 0
	global_load_lds_dwordx4 v136, s[86:87]
	s_nop 0
	s_mov_b32 m0, s59
	s_nop 0
	global_load_lds_dwordx4 v138, s[86:87]
	s_waitcnt vmcnt(8)
	s_waitcnt lgkmcnt(0)
	s_setprio 1
	s_barrier
	v_mfma_f32_16x16x32_bf16 v[62:65], v[148:151], v[180:183], v[62:65]
	v_mfma_f32_16x16x32_bf16 v[58:61], v[156:159], v[180:183], v[58:61]
	s_waitcnt lgkmcnt(5)
	v_mfma_f32_16x16x32_bf16 v[46:49], v[148:151], v[188:191], v[46:49]
	v_mfma_f32_16x16x32_bf16 v[42:45], v[156:159], v[188:191], v[42:45]
	s_waitcnt lgkmcnt(3)
	v_mfma_f32_16x16x32_bf16 v[30:33], v[148:151], v[196:199], v[30:33]
	v_mfma_f32_16x16x32_bf16 v[26:29], v[156:159], v[196:199], v[26:29]
	s_waitcnt lgkmcnt(1)
	v_mfma_f32_16x16x32_bf16 v[14:17], v[148:151], v[204:207], v[14:17]
	v_mfma_f32_16x16x32_bf16 v[10:13], v[156:159], v[204:207], v[10:13]
	v_mfma_f32_16x16x32_bf16 v[62:65], v[152:155], v[184:187], v[62:65]
	v_mfma_f32_16x16x32_bf16 v[58:61], v[160:163], v[184:187], v[58:61]
	v_mfma_f32_16x16x32_bf16 v[46:49], v[152:155], v[192:195], v[46:49]
	v_mfma_f32_16x16x32_bf16 v[42:45], v[160:163], v[192:195], v[42:45]
	v_mfma_f32_16x16x32_bf16 v[30:33], v[152:155], v[200:203], v[30:33]
	v_mfma_f32_16x16x32_bf16 v[26:29], v[160:163], v[200:203], v[26:29]
	s_waitcnt lgkmcnt(0)
	v_mfma_f32_16x16x32_bf16 v[14:17], v[152:155], v[208:211], v[14:17]
	v_mfma_f32_16x16x32_bf16 v[10:13], v[160:163], v[208:211], v[10:13]
	s_setprio 0
	s_setprio 1
	v_mfma_f32_16x16x32_bf16 v[54:57], v[164:167], v[180:183], v[54:57]
	v_mfma_f32_16x16x32_bf16 v[50:53], v[172:175], v[180:183], v[50:53]
	v_mfma_f32_16x16x32_bf16 v[38:41], v[164:167], v[188:191], v[38:41]
	v_mfma_f32_16x16x32_bf16 v[34:37], v[172:175], v[188:191], v[34:37]
	v_mfma_f32_16x16x32_bf16 v[22:25], v[164:167], v[196:199], v[22:25]
	v_mfma_f32_16x16x32_bf16 v[18:21], v[172:175], v[196:199], v[18:21]
	v_mfma_f32_16x16x32_bf16 v[6:9], v[164:167], v[204:207], v[6:9]
	v_mfma_f32_16x16x32_bf16 v[2:5], v[172:175], v[204:207], v[2:5]
	v_mfma_f32_16x16x32_bf16 v[54:57], v[168:171], v[184:187], v[54:57]
	v_mfma_f32_16x16x32_bf16 v[50:53], v[176:179], v[184:187], v[50:53]
	v_mfma_f32_16x16x32_bf16 v[38:41], v[168:171], v[192:195], v[38:41]
	v_mfma_f32_16x16x32_bf16 v[34:37], v[176:179], v[192:195], v[34:37]
	v_mfma_f32_16x16x32_bf16 v[22:25], v[168:171], v[200:203], v[22:25]
	v_mfma_f32_16x16x32_bf16 v[18:21], v[176:179], v[200:203], v[18:21]
	v_mfma_f32_16x16x32_bf16 v[6:9], v[168:171], v[208:211], v[6:9]
	s_setprio 2
	s_barrier
; #define PG8_STAGE(bufoff, gbase, voff) do { _Pragma("unroll") for (int _i = 0; _i < 2; ++_i) \
;         asm volatile("s_mov_b32 m0, %2\n\ts_nop 0\n\tglobal_load_lds_dwordx4 %0, %1" :: "v"((voff)[_i]), "s"((const char*)(gbase)), "s"(ldsbase + (unsigned)(bufoff) + ldsw + (unsigned)_i * 8192u) : "memory", "m0"); } while (0)
; #define PG8_LDA(dst, b, h) do { _Pragma("unroll") for (int m = 0; m < 4; ++m) _Pragma("unroll") for (int k = 0; k < 2; ++k) dst[m][k] = *(const PG8_LAS bf16x8*)(lds + PG8_SA(b, h) + aoff + m * 2048 + k * 1024); } while (0)
; #define PG8_LDB(dst, b, h) do { _Pragma("unroll") for (int n = 0; n < 2; ++n) _Pragma("unroll") for (int k = 0; k < 2; ++k) dst[n][k] = *(const PG8_LAS bf16x8*)(lds + PG8_SB(b, h) + boff + n * 2048 + k * 1024); } while (0)
; #define PG8_MMA(ai, bj, At, Bt) do { __builtin_amdgcn_s_setprio(1); _Pragma("unroll") for (int m = 0; m < 4; ++m) _Pragma("unroll") for (int n = 0; n < 2; ++n) _Pragma("unroll") for (int k = 0; k < 2; ++k) \
;         acc[ai][bj][m][n] = __builtin_amdgcn_mfma_f32_16x16x32_bf16(Bt[n][k], At[m][k], acc[ai][bj][m][n], 0, 0, 0); __builtin_amdgcn_s_setprio(0); } while (0)
; template <class Epi, class Sched, bool ALIGN_EPI = false, bool SP2 = false>
; __device__ __forceinline__ void gemm_phase(PG8_LAS unsigned char* lds, const Gemm g, const Sched& S, const Epi& E) {
;     ...
;             PG8_LDB(B0, 0, 0); PG8_LDB(B1, 0, 1); PG8_SCHED; PG8_LDA(At, 0, 0); PG8_STAGE(PG8_SA(1, 1), a1 + hstep, voffA);
;             PG8_WAIT_V(8); PG8_WAIT_L(0); PG8_BAR; PG8_MMA(0, 0, At, B0); PG8_MMA(0, 1, At, B1); PG8_BAR; PG8_SCHED;
;             PG8_LDA(At, 0, 1); PG8_STAGE(PG8_SB(0, 0), b2, voffB); PG8_STAGE(PG8_SB(0, 1), b2 + hstep, voffB); PG8_STAGE(PG8_SA(0, 0), a2, voffA);
;             PG8_WAIT_V(8); PG8_WAIT_L(0); PG8_BAR; PG8_MMA(1, 0, At, B0); PG8_MMA(1, 1, At, B1); PG8_BAR; PG8_SCHED;
;             PG8_LDB(B0, 1, 0); PG8_LDB(B1, 1, 1); PG8_SCHED; PG8_LDA(At, 1, 0); PG8_STAGE(PG8_SA(0, 1), a2 + hstep, voffA);
;             PG8_WAIT_V(8); PG8_WAIT_L(0); PG8_BAR; PG8_MMA(0, 0, At, B0); PG8_MMA(0, 1, At, B1); PG8_BAR; PG8_SCHED;
;             PG8_LDA(At, 1, 1); PG8_STAGE(PG8_SB(1, 0), b3, voffB); PG8_STAGE(PG8_SB(1, 1), b3 + hstep, voffB); PG8_STAGE(PG8_SA(1, 0), a3, voffA);
;             PG8_WAIT_V(8); PG8_WAIT_L(0); PG8_BAR; PG8_MMA(1, 0, At, B0); PG8_MMA(1, 1, At, B1); PG8_BAR; PG8_SCHED;
	v_mfma_f32_16x16x32_bf16 v[2:5], v[176:179], v[208:211], v[2:5]
	s_setprio 0
	ds_read_b128 v[148:151], v145
	ds_read_b128 v[152:155], v145 offset:1024
	ds_read_b128 v[156:159], v145 offset:2048
	ds_read_b128 v[160:163], v145 offset:3072
	ds_read_b128 v[164:167], v146
	ds_read_b128 v[168:171], v146 offset:1024
	ds_read_b128 v[172:175], v146 offset:2048
	ds_read_b128 v[176:179], v146 offset:3072
	ds_read_b128 v[180:183], v144 offset:32768
	ds_read_b128 v[184:187], v144 offset:33792
	ds_read_b128 v[188:191], v144 offset:34816
	ds_read_b128 v[192:195], v144 offset:35840
	ds_read_b128 v[196:199], v144 offset:36864
	ds_read_b128 v[200:203], v144 offset:37888
	ds_read_b128 v[204:207], v144 offset:38912
	ds_read_b128 v[208:211], v144 offset:39936
	s_add_u32 s66, s86, 0x100000
	s_addc_u32 s67, s87, 0
	s_mov_b32 m0, s60
	s_nop 0
	global_load_lds_dwordx4 v136, s[66:67]
	s_nop 0
	s_mov_b32 m0, s61
	s_nop 0
	global_load_lds_dwordx4 v138, s[66:67]
	s_waitcnt vmcnt(8)
	s_waitcnt lgkmcnt(0)
	s_setprio 1
	s_barrier
	v_mfma_f32_16x16x32_bf16 v[126:129], v[148:151], v[180:183], v[126:129]
	v_mfma_f32_16x16x32_bf16 v[122:125], v[156:159], v[180:183], v[122:125]
	s_waitcnt lgkmcnt(5)
	v_mfma_f32_16x16x32_bf16 v[110:113], v[148:151], v[188:191], v[110:113]
	v_mfma_f32_16x16x32_bf16 v[106:109], v[156:159], v[188:191], v[106:109]
	s_waitcnt lgkmcnt(3)
	v_mfma_f32_16x16x32_bf16 v[94:97], v[148:151], v[196:199], v[94:97]
	v_mfma_f32_16x16x32_bf16 v[90:93], v[156:159], v[196:199], v[90:93]
	s_waitcnt lgkmcnt(1)
	v_mfma_f32_16x16x32_bf16 v[78:81], v[148:151], v[204:207], v[78:81]
	v_mfma_f32_16x16x32_bf16 v[74:77], v[156:159], v[204:207], v[74:77]
	v_mfma_f32_16x16x32_bf16 v[126:129], v[152:155], v[184:187], v[126:129]
	v_mfma_f32_16x16x32_bf16 v[122:125], v[160:163], v[184:187], v[122:125]
	v_mfma_f32_16x16x32_bf16 v[110:113], v[152:155], v[192:195], v[110:113]
	v_mfma_f32_16x16x32_bf16 v[106:109], v[160:163], v[192:195], v[106:109]
	v_mfma_f32_16x16x32_bf16 v[94:97], v[152:155], v[200:203], v[94:97]
	v_mfma_f32_16x16x32_bf16 v[90:93], v[160:163], v[200:203], v[90:93]
	s_waitcnt lgkmcnt(0)
	v_mfma_f32_16x16x32_bf16 v[78:81], v[152:155], v[208:211], v[78:81]
	v_mfma_f32_16x16x32_bf16 v[74:77], v[160:163], v[208:211], v[74:77]
	s_setprio 0
	s_setprio 1
	v_mfma_f32_16x16x32_bf16 v[118:121], v[164:167], v[180:183], v[118:121]
	v_mfma_f32_16x16x32_bf16 v[114:117], v[172:175], v[180:183], v[114:117]
	v_mfma_f32_16x16x32_bf16 v[102:105], v[164:167], v[188:191], v[102:105]
	v_mfma_f32_16x16x32_bf16 v[98:101], v[172:175], v[188:191], v[98:101]
	v_mfma_f32_16x16x32_bf16 v[86:89], v[164:167], v[196:199], v[86:89]
	v_mfma_f32_16x16x32_bf16 v[82:85], v[172:175], v[196:199], v[82:85]
	v_mfma_f32_16x16x32_bf16 v[70:73], v[164:167], v[204:207], v[70:73]
	v_mfma_f32_16x16x32_bf16 v[66:69], v[172:175], v[204:207], v[66:69]
	v_mfma_f32_16x16x32_bf16 v[118:121], v[168:171], v[184:187], v[118:121]
	v_mfma_f32_16x16x32_bf16 v[114:117], v[176:179], v[184:187], v[114:117]
	v_mfma_f32_16x16x32_bf16 v[102:105], v[168:171], v[192:195], v[102:105]
	v_mfma_f32_16x16x32_bf16 v[98:101], v[176:179], v[192:195], v[98:101]
	v_mfma_f32_16x16x32_bf16 v[86:89], v[168:171], v[200:203], v[86:89]
	v_mfma_f32_16x16x32_bf16 v[82:85], v[176:179], v[200:203], v[82:85]
	v_mfma_f32_16x16x32_bf16 v[70:73], v[168:171], v[208:211], v[70:73]
	s_setprio 2
	s_barrier
	v_mfma_f32_16x16x32_bf16 v[66:69], v[176:179], v[208:211], v[66:69]
	s_setprio 0
	ds_read_b128 v[180:183], v144 offset:49152
	ds_read_b128 v[184:187], v144 offset:50176
	ds_read_b128 v[188:191], v144 offset:51200
	ds_read_b128 v[192:195], v144 offset:52224
	ds_read_b128 v[196:199], v144 offset:53248
	ds_read_b128 v[200:203], v144 offset:54272
	ds_read_b128 v[204:207], v144 offset:55296
	ds_read_b128 v[208:211], v144 offset:56320
	s_add_u32 s66, s84, 0x80
	s_addc_u32 s67, s85, 0
	s_mov_b32 m0, s64
	s_nop 0
	global_load_lds_dwordx4 v137, s[66:67]
	s_nop 0
	s_mov_b32 m0, s65
	s_nop 0
	global_load_lds_dwordx4 v139, s[66:67]
	s_add_u32 s66, s84, 0x100080
	s_addc_u32 s67, s85, 0
	s_mov_b32 m0, s70
	s_nop 0
	global_load_lds_dwordx4 v137, s[66:67]
	s_nop 0
	s_mov_b32 m0, s71
	s_nop 0
	global_load_lds_dwordx4 v139, s[66:67]
	s_nop 0
	s_mov_b32 m0, s68
	s_nop 0
	global_load_lds_dwordx4 v136, s[76:77]
	s_nop 0
	s_mov_b32 m0, s69
	s_nop 0
	global_load_lds_dwordx4 v138, s[76:77]
	s_waitcnt vmcnt(8)
	s_waitcnt lgkmcnt(0)
	s_setprio 1
	s_barrier
	v_mfma_f32_16x16x32_bf16 v[62:65], v[148:151], v[180:183], v[62:65]
	v_mfma_f32_16x16x32_bf16 v[58:61], v[156:159], v[180:183], v[58:61]
	s_waitcnt lgkmcnt(5)
	v_mfma_f32_16x16x32_bf16 v[46:49], v[148:151], v[188:191], v[46:49]
	v_mfma_f32_16x16x32_bf16 v[42:45], v[156:159], v[188:191], v[42:45]
	s_waitcnt lgkmcnt(3)
	v_mfma_f32_16x16x32_bf16 v[30:33], v[148:151], v[196:199], v[30:33]
	v_mfma_f32_16x16x32_bf16 v[26:29], v[156:159], v[196:199], v[26:29]
	s_waitcnt lgkmcnt(1)
	v_mfma_f32_16x16x32_bf16 v[14:17], v[148:151], v[204:207], v[14:17]
	v_mfma_f32_16x16x32_bf16 v[10:13], v[156:159], v[204:207], v[10:13]
	v_mfma_f32_16x16x32_bf16 v[62:65], v[152:155], v[184:187], v[62:65]
	v_mfma_f32_16x16x32_bf16 v[58:61], v[160:163], v[184:187], v[58:61]
	v_mfma_f32_16x16x32_bf16 v[46:49], v[152:155], v[192:195], v[46:49]
	v_mfma_f32_16x16x32_bf16 v[42:45], v[160:163], v[192:195], v[42:45]
	v_mfma_f32_16x16x32_bf16 v[30:33], v[152:155], v[200:203], v[30:33]
	v_mfma_f32_16x16x32_bf16 v[26:29], v[160:163], v[200:203], v[26:29]
	s_waitcnt lgkmcnt(0)
	v_mfma_f32_16x16x32_bf16 v[14:17], v[152:155], v[208:211], v[14:17]
	v_mfma_f32_16x16x32_bf16 v[10:13], v[160:163], v[208:211], v[10:13]
	s_setprio 0
	s_setprio 1
	v_mfma_f32_16x16x32_bf16 v[54:57], v[164:167], v[180:183], v[54:57]
	v_mfma_f32_16x16x32_bf16 v[50:53], v[172:175], v[180:183], v[50:53]
	v_mfma_f32_16x16x32_bf16 v[38:41], v[164:167], v[188:191], v[38:41]
	v_mfma_f32_16x16x32_bf16 v[34:37], v[172:175], v[188:191], v[34:37]
	v_mfma_f32_16x16x32_bf16 v[22:25], v[164:167], v[196:199], v[22:25]
	v_mfma_f32_16x16x32_bf16 v[18:21], v[172:175], v[196:199], v[18:21]
	v_mfma_f32_16x16x32_bf16 v[6:9], v[164:167], v[204:207], v[6:9]
	v_mfma_f32_16x16x32_bf16 v[2:5], v[172:175], v[204:207], v[2:5]
	v_mfma_f32_16x16x32_bf16 v[54:57], v[168:171], v[184:187], v[54:57]
	v_mfma_f32_16x16x32_bf16 v[50:53], v[176:179], v[184:187], v[50:53]
	v_mfma_f32_16x16x32_bf16 v[38:41], v[168:171], v[192:195], v[38:41]
	v_mfma_f32_16x16x32_bf16 v[34:37], v[176:179], v[192:195], v[34:37]
	v_mfma_f32_16x16x32_bf16 v[22:25], v[168:171], v[200:203], v[22:25]
	v_mfma_f32_16x16x32_bf16 v[18:21], v[176:179], v[200:203], v[18:21]
	v_mfma_f32_16x16x32_bf16 v[6:9], v[168:171], v[208:211], v[6:9]
	s_setprio 2
	s_barrier
; __device__ __forceinline__ unsigned cvt_pk_bf16(float lo, float hi) { unsigned r; asm volatile("v_cvt_pk_bf16_f32 %0, %1, %2" : "=v"(r) : "v"(lo), "v"(hi)); return r; }
; __device__ __forceinline__ float silu_f(float x) { return x * sigmoid_f(x); }
;     __device__ __forceinline__ void operator()(const f32x4 (&acc)[2][2][4][2], const Unit& u, int wr, int wc, int fr, int fq) const {
;         const int row0 = u.pm * BM + wr * 64 + fr, col0 = u.pn * HALF + wc * 32 + 8 * fq;
; #pragma unroll
;         for (int ai = 0; ai < 2; ++ai)
; #pragma unroll
;             for (int m = 0; m < 4; ++m) { bf16_t* rowp = O + (size_t)(row0 + ai * HALF + m * 16) * ldc + col0;
;                 const f32x4 g0 = acc[ai][0][m][0], g1 = acc[ai][0][m][1], u0 = acc[ai][1][m][0], u1 = acc[ai][1][m][1];
;                 f32x4 v0, v1;
; #pragma unroll
;                 for (int j = 0; j < 4; ++j) { v0[j] = silu_f(g0[j]) * u0[j]; v1[j] = silu_f(g1[j]) * u1[j]; }
;                 u32x4 w; w.x = cvt_pk_bf16(v0[0], v0[1]); w.y = cvt_pk_bf16(v0[2], v0[3]); w.z = cvt_pk_bf16(v1[0], v1[1]); w.w = cvt_pk_bf16(v1[2], v1[3]);
;                 *(u32x4*)rowp = w; }
; template <class Epi, class Sched, bool ALIGN_EPI = false, bool SP2 = false>
; __device__ __forceinline__ void gemm_phase(PG8_LAS unsigned char* lds, const Gemm g, const Sched& S, const Epi& E) {
;     ...
;             PG8_LDB(B0, 0, 0); PG8_LDB(B1, 0, 1); PG8_SCHED; PG8_LDA(At, 0, 0); PG8_STAGE(PG8_SA(1, 1), a1 + hstep, voffA);
;             PG8_WAIT_V(8); PG8_WAIT_L(0); PG8_BAR; PG8_MMA(0, 0, At, B0); PG8_MMA(0, 1, At, B1); PG8_BAR; PG8_SCHED;
;             PG8_LDA(At, 0, 1); PG8_STAGE(PG8_SB(0, 0), b2, voffB); PG8_STAGE(PG8_SB(0, 1), b2 + hstep, voffB); PG8_STAGE(PG8_SA(0, 0), a2, voffA);
;             PG8_WAIT_V(8); PG8_WAIT_L(0); PG8_BAR; PG8_MMA(1, 0, At, B0); PG8_MMA(1, 1, At, B1); PG8_BAR; PG8_SCHED;
;             PG8_LDB(B0, 1, 0); PG8_LDB(B1, 1, 1); PG8_SCHED; PG8_LDA(At, 1, 0); PG8_STAGE(PG8_SA(0, 1), a2 + hstep, voffA);
;             PG8_WAIT_V(8); PG8_WAIT_L(0); PG8_BAR; PG8_MMA(0, 0, At, B0); PG8_MMA(0, 1, At, B1); PG8_BAR; PG8_SCHED;
;             PG8_LDA(At, 1, 1); PG8_STAGE(PG8_SB(1, 0), b3, voffB); PG8_STAGE(PG8_SB(1, 1), b3 + hstep, voffB); PG8_STAGE(PG8_SA(1, 0), a3, voffA);
;             PG8_WAIT_V(8); PG8_WAIT_L(0); PG8_BAR; PG8_MMA(1, 0, At, B0); PG8_MMA(1, 1, At, B1); PG8_BAR; PG8_SCHED;
	v_mfma_f32_16x16x32_bf16 v[2:5], v[176:179], v[208:211], v[2:5]
	s_setprio 0
	s_add_i32 s96, s96, 2
	s_add_u32 s94, s94, 0x100
	s_addc_u32 s95, s95, 0
	s_cmp_gt_u32 s96, 61
	s_mov_b64 s[66:67], s[62:63]
	s_cbranch_scc0 .LBB0_138
	v_mul_f32_e32 v134, 0xbfb8aa3b, v126
	v_exp_f32_e32 v150, v134
	v_mul_f32_e32 v134, 0xbfb8aa3b, v122
	v_exp_f32_e32 v151, v134
	v_lshl_or_b32 v148, s91, 7, v141
	v_add_f32_e32 v150, 1.0, v150
	v_rcp_f32_e32 v152, v150
	v_add_f32_e32 v150, 1.0, v151
	v_rcp_f32_e32 v153, v150
	v_lshl_add_u32 v147, s82, 8, v140
	v_mul_f32_e32 v126, v126, v152
	v_mul_f32_e32 v118, v126, v118
	v_mul_f32_e32 v126, 0xbfb8aa3b, v127
	v_exp_f32_e32 v126, v126
	v_mul_f32_e32 v152, 0xbfb8aa3b, v123
	v_exp_f32_e32 v152, v152
	v_mul_f32_e32 v122, v122, v153
	v_mul_f32_e32 v122, v122, v114
	v_add_f32_e32 v114, 1.0, v126
	v_rcp_f32_e32 v114, v114
	v_add_f32_e32 v126, 1.0, v152
	v_mul_f32_e32 v152, 0xbfb8aa3b, v128
	v_rcp_f32_e32 v126, v126
	v_exp_f32_e32 v152, v152
	v_mul_f32_e32 v114, v127, v114
	v_mul_f32_e32 v119, v114, v119
	v_mul_f32_e32 v114, v123, v126
	v_add_f32_e32 v123, 1.0, v152
	v_rcp_f32_e32 v123, v123
	v_mul_f32_e32 v126, 0xbfb8aa3b, v124
	v_exp_f32_e32 v126, v126
	v_mul_f32_e32 v127, v114, v115
	v_mul_f32_e32 v114, v128, v123
	v_mul_f32_e32 v115, 0xbfb8aa3b, v129
	v_mul_f32_e32 v123, v114, v120
	v_exp_f32_e32 v115, v115
	v_mul_f32_e32 v120, 0xbfb8aa3b, v125
	v_exp_f32_e32 v120, v120
	v_add_f32_e32 v114, 1.0, v126
	v_rcp_f32_e32 v114, v114
	v_add_f32_e32 v115, 1.0, v115
	v_rcp_f32_e32 v115, v115
	v_add_f32_e32 v120, 1.0, v120
	v_rcp_f32_e32 v120, v120
	v_mul_f32_e32 v114, v124, v114
	v_mul_f32_e32 v124, v114, v116
	v_mul_f32_e32 v114, v129, v115
	v_ashrrev_i32_e32 v149, 31, v148
	v_mov_b64_e32 v[134:135], s[72:73]
	v_mul_f32_e32 v126, v114, v121
	v_mul_f32_e32 v114, v125, v120
	v_mad_i64_i32 v[150:151], s[62:63], v147, s90, v[134:135]
	v_mul_f32_e32 v125, v114, v117
	v_lshlrev_b64 v[114:115], 1, v[148:149]
	v_lshl_add_u64 v[120:121], v[150:151], 0, v[114:115]
	v_cvt_pk_bf16_f32 v116, v118, v119
	v_cvt_pk_bf16_f32 v117, v123, v126
	v_cvt_pk_bf16_f32 v118, v122, v127
	v_cvt_pk_bf16_f32 v119, v124, v125
	global_store_dwordx4 v[120:121], v[116:119], off
	s_and_b64 vcc, exec, s[0:1]
	s_mov_b32 s91, s10
	v_mul_f32_e32 v116, 0xbfb8aa3b, v110
	v_exp_f32_e32 v116, v116
	v_mul_f32_e32 v117, 0xbfb8aa3b, v106
	v_exp_f32_e32 v117, v117
	v_or_b32_e32 v118, 16, v147
	v_add_f32_e32 v116, 1.0, v116
	v_rcp_f32_e32 v119, v116
	v_add_f32_e32 v116, 1.0, v117
	v_rcp_f32_e32 v120, v116
	v_mad_i64_i32 v[116:117], s[62:63], v118, s90, v[134:135]
	v_mul_f32_e32 v110, v110, v119
	v_mul_f32_e32 v110, v110, v102
	v_mul_f32_e32 v102, v106, v120
	v_mul_f32_e32 v106, 0xbfb8aa3b, v111
	v_exp_f32_e32 v106, v106
	v_mul_f32_e32 v118, 0xbfb8aa3b, v107
	v_mul_f32_e32 v119, v102, v98
	v_exp_f32_e32 v118, v118
	v_add_f32_e32 v98, 1.0, v106
	v_rcp_f32_e32 v98, v98
	v_mul_f32_e32 v106, 0xbfb8aa3b, v112
	v_exp_f32_e32 v106, v106
	v_add_f32_e32 v102, 1.0, v118
	v_mul_f32_e32 v98, v111, v98
	v_rcp_f32_e32 v102, v102
	v_mul_f32_e32 v98, v98, v103
	v_add_f32_e32 v103, 1.0, v106
	v_rcp_f32_e32 v103, v103
	v_mul_f32_e32 v102, v107, v102
	v_mul_f32_e32 v106, 0xbfb8aa3b, v108
	v_mul_f32_e32 v107, v102, v99
	v_mul_f32_e32 v99, v112, v103
	v_exp_f32_e32 v106, v106
	v_mul_f32_e32 v99, v99, v104
	v_mul_f32_e32 v103, 0xbfb8aa3b, v113
	v_mul_f32_e32 v104, 0xbfb8aa3b, v109
	v_exp_f32_e32 v103, v103
	v_exp_f32_e32 v104, v104
	v_add_f32_e32 v102, 1.0, v106
	v_rcp_f32_e32 v102, v102
	v_add_f32_e32 v103, 1.0, v103
	v_add_f32_e32 v104, 1.0, v104
	v_rcp_f32_e32 v103, v103
	v_rcp_f32_e32 v104, v104
	v_mul_f32_e32 v102, v108, v102
	v_mul_f32_e32 v106, v102, v100
	v_mul_f32_e32 v100, v113, v103
	v_mul_f32_e32 v102, v109, v104
	v_mul_f32_e32 v100, v100, v105
	v_mul_f32_e32 v101, v102, v101
	v_lshl_add_u64 v[102:103], v[116:117], 0, v[114:115]
	v_cvt_pk_bf16_f32 v98, v110, v98
	v_cvt_pk_bf16_f32 v99, v99, v100
	v_cvt_pk_bf16_f32 v100, v119, v107
	v_cvt_pk_bf16_f32 v101, v106, v101
	global_store_dwordx4 v[102:103], v[98:101], off
	s_mov_b32 s82, s12
	s_mov_b64 s[66:67], s[14:15]
	v_mul_f32_e32 v98, 0xbfb8aa3b, v94
	v_exp_f32_e32 v98, v98
	v_mul_f32_e32 v99, 0xbfb8aa3b, v90
	v_exp_f32_e32 v99, v99
	v_or_b32_e32 v100, 32, v147
	v_add_f32_e32 v98, 1.0, v98
	v_rcp_f32_e32 v101, v98
	v_add_f32_e32 v98, 1.0, v99
	v_rcp_f32_e32 v102, v98
	v_mad_i64_i32 v[98:99], s[62:63], v100, s90, v[134:135]
	v_mul_f32_e32 v94, v94, v101
	v_mul_f32_e32 v94, v94, v86
	v_mul_f32_e32 v86, v90, v102
	v_mul_f32_e32 v90, 0xbfb8aa3b, v95
	v_exp_f32_e32 v90, v90
	v_mul_f32_e32 v100, 0xbfb8aa3b, v91
	v_mul_f32_e32 v101, v86, v82
	v_exp_f32_e32 v100, v100
	v_add_f32_e32 v82, 1.0, v90
	v_rcp_f32_e32 v82, v82
	v_mul_f32_e32 v90, 0xbfb8aa3b, v96
	v_exp_f32_e32 v90, v90
	v_add_f32_e32 v86, 1.0, v100
	v_mul_f32_e32 v82, v95, v82
	v_rcp_f32_e32 v86, v86
	v_mul_f32_e32 v82, v82, v87
	v_add_f32_e32 v87, 1.0, v90
	v_rcp_f32_e32 v87, v87
	v_mul_f32_e32 v86, v91, v86
	v_mul_f32_e32 v90, 0xbfb8aa3b, v92
	v_mul_f32_e32 v91, v86, v83
	v_mul_f32_e32 v83, v96, v87
	v_exp_f32_e32 v90, v90
	v_mul_f32_e32 v83, v83, v88
	v_mul_f32_e32 v87, 0xbfb8aa3b, v97
	v_mul_f32_e32 v88, 0xbfb8aa3b, v93
	v_exp_f32_e32 v87, v87
	v_exp_f32_e32 v88, v88
	v_add_f32_e32 v86, 1.0, v90
	v_rcp_f32_e32 v86, v86
	v_add_f32_e32 v87, 1.0, v87
	v_add_f32_e32 v88, 1.0, v88
	v_rcp_f32_e32 v87, v87
	v_rcp_f32_e32 v88, v88
	v_mul_f32_e32 v86, v92, v86
	v_mul_f32_e32 v90, v86, v84
	v_mul_f32_e32 v84, v97, v87
	v_mul_f32_e32 v86, v93, v88
	v_mul_f32_e32 v84, v84, v89
	v_mul_f32_e32 v85, v86, v85
	v_lshl_add_u64 v[86:87], v[98:99], 0, v[114:115]
	v_cvt_pk_bf16_f32 v82, v94, v82
; __device__ __forceinline__ unsigned cvt_pk_bf16(float lo, float hi) { unsigned r; asm volatile("v_cvt_pk_bf16_f32 %0, %1, %2" : "=v"(r) : "v"(lo), "v"(hi)); return r; }
; __device__ __forceinline__ float silu_f(float x) { return x * sigmoid_f(x); }
;     __device__ __forceinline__ void operator()(const f32x4 (&acc)[2][2][4][2], const Unit& u, int wr, int wc, int fr, int fq) const {
;         const int row0 = u.pm * BM + wr * 64 + fr, col0 = u.pn * HALF + wc * 32 + 8 * fq;
; #pragma unroll
;         for (int ai = 0; ai < 2; ++ai)
; #pragma unroll
;             for (int m = 0; m < 4; ++m) { bf16_t* rowp = O + (size_t)(row0 + ai * HALF + m * 16) * ldc + col0;
;                 const f32x4 g0 = acc[ai][0][m][0], g1 = acc[ai][0][m][1], u0 = acc[ai][1][m][0], u1 = acc[ai][1][m][1];
;                 f32x4 v0, v1;
; #pragma unroll
;                 for (int j = 0; j < 4; ++j) { v0[j] = silu_f(g0[j]) * u0[j]; v1[j] = silu_f(g1[j]) * u1[j]; }
;                 u32x4 w; w.x = cvt_pk_bf16(v0[0], v0[1]); w.y = cvt_pk_bf16(v0[2], v0[3]); w.z = cvt_pk_bf16(v1[0], v1[1]); w.w = cvt_pk_bf16(v1[2], v1[3]);
;                 *(u32x4*)rowp = w; }
	v_cvt_pk_bf16_f32 v83, v83, v84
	v_cvt_pk_bf16_f32 v84, v101, v91
	v_cvt_pk_bf16_f32 v85, v90, v85
	global_store_dwordx4 v[86:87], v[82:85], off
	s_nop 1
	v_mul_f32_e32 v82, 0xbfb8aa3b, v78
	v_exp_f32_e32 v82, v82
	v_mul_f32_e32 v83, 0xbfb8aa3b, v74
	v_exp_f32_e32 v83, v83
	v_or_b32_e32 v84, 48, v147
	v_add_f32_e32 v82, 1.0, v82
	v_rcp_f32_e32 v85, v82
	v_add_f32_e32 v82, 1.0, v83
	v_rcp_f32_e32 v86, v82
	v_mad_i64_i32 v[82:83], s[62:63], v84, s90, v[134:135]
	v_mul_f32_e32 v78, v78, v85
	v_mul_f32_e32 v78, v78, v70
	v_mul_f32_e32 v70, v74, v86
	v_mul_f32_e32 v74, 0xbfb8aa3b, v79
	v_exp_f32_e32 v74, v74
	v_mul_f32_e32 v84, 0xbfb8aa3b, v75
	v_mul_f32_e32 v85, v70, v66
	v_exp_f32_e32 v84, v84
	v_add_f32_e32 v66, 1.0, v74
	v_rcp_f32_e32 v66, v66
	v_mul_f32_e32 v74, 0xbfb8aa3b, v80
	v_exp_f32_e32 v74, v74
	v_add_f32_e32 v70, 1.0, v84
	v_mul_f32_e32 v66, v79, v66
	v_rcp_f32_e32 v70, v70
	v_mul_f32_e32 v66, v66, v71
	v_add_f32_e32 v71, 1.0, v74
	v_rcp_f32_e32 v71, v71
	v_mul_f32_e32 v70, v75, v70
	v_mul_f32_e32 v74, 0xbfb8aa3b, v76
	v_mul_f32_e32 v75, v70, v67
	v_mul_f32_e32 v67, v80, v71
	v_exp_f32_e32 v74, v74
	v_mul_f32_e32 v67, v67, v72
	v_mul_f32_e32 v71, 0xbfb8aa3b, v81
	v_mul_f32_e32 v72, 0xbfb8aa3b, v77
	v_exp_f32_e32 v71, v71
	v_exp_f32_e32 v72, v72
	v_add_f32_e32 v70, 1.0, v74
	v_rcp_f32_e32 v70, v70
	v_add_f32_e32 v71, 1.0, v71
	v_add_f32_e32 v72, 1.0, v72
	v_rcp_f32_e32 v71, v71
	v_rcp_f32_e32 v72, v72
	v_mul_f32_e32 v70, v76, v70
	v_mul_f32_e32 v74, v70, v68
	v_mul_f32_e32 v68, v81, v71
	v_mul_f32_e32 v70, v77, v72
	v_mul_f32_e32 v68, v68, v73
	v_mul_f32_e32 v69, v70, v69
	v_lshl_add_u64 v[70:71], v[82:83], 0, v[114:115]
	v_cvt_pk_bf16_f32 v66, v78, v66
	v_cvt_pk_bf16_f32 v67, v67, v68
	v_cvt_pk_bf16_f32 v68, v85, v75
	v_cvt_pk_bf16_f32 v69, v74, v69
	global_store_dwordx4 v[70:71], v[66:69], off
	s_nop 1
	v_mul_f32_e32 v66, 0xbfb8aa3b, v62
	v_exp_f32_e32 v66, v66
	v_mul_f32_e32 v67, 0xbfb8aa3b, v58
	v_exp_f32_e32 v67, v67
	v_add_u32_e32 v68, 0x80, v147
	v_add_f32_e32 v66, 1.0, v66
	v_rcp_f32_e32 v69, v66
	v_add_f32_e32 v66, 1.0, v67
	v_rcp_f32_e32 v70, v66
	v_mad_i64_i32 v[66:67], s[62:63], v68, s90, v[134:135]
	v_mul_f32_e32 v62, v62, v69
	v_mul_f32_e32 v62, v62, v54
	v_mul_f32_e32 v54, v58, v70
	v_mul_f32_e32 v58, 0xbfb8aa3b, v63
	v_exp_f32_e32 v58, v58
	v_mul_f32_e32 v68, 0xbfb8aa3b, v59
	v_mul_f32_e32 v69, v54, v50
	v_exp_f32_e32 v68, v68
	v_add_f32_e32 v50, 1.0, v58
	v_rcp_f32_e32 v50, v50
	v_mul_f32_e32 v58, 0xbfb8aa3b, v64
	v_exp_f32_e32 v58, v58
	v_add_f32_e32 v54, 1.0, v68
	v_mul_f32_e32 v50, v63, v50
	v_rcp_f32_e32 v54, v54
	v_mul_f32_e32 v50, v50, v55
	v_add_f32_e32 v55, 1.0, v58
	v_rcp_f32_e32 v55, v55
	v_mul_f32_e32 v54, v59, v54
	v_mul_f32_e32 v58, 0xbfb8aa3b, v60
	v_mul_f32_e32 v59, v54, v51
	v_mul_f32_e32 v51, v64, v55
	v_exp_f32_e32 v58, v58
	v_mul_f32_e32 v51, v51, v56
	v_mul_f32_e32 v55, 0xbfb8aa3b, v65
	v_mul_f32_e32 v56, 0xbfb8aa3b, v61
	v_exp_f32_e32 v55, v55
	v_exp_f32_e32 v56, v56
	v_add_f32_e32 v54, 1.0, v58
	v_rcp_f32_e32 v54, v54
	v_add_f32_e32 v55, 1.0, v55
	v_add_f32_e32 v56, 1.0, v56
	v_rcp_f32_e32 v55, v55
	v_rcp_f32_e32 v56, v56
	v_mul_f32_e32 v54, v60, v54
	v_mul_f32_e32 v58, v54, v52
	v_mul_f32_e32 v52, v65, v55
	v_mul_f32_e32 v54, v61, v56
	v_mul_f32_e32 v52, v52, v57
	v_mul_f32_e32 v53, v54, v53
	v_lshl_add_u64 v[54:55], v[66:67], 0, v[114:115]
	v_cvt_pk_bf16_f32 v50, v62, v50
	v_cvt_pk_bf16_f32 v51, v51, v52
	v_cvt_pk_bf16_f32 v52, v69, v59
	v_cvt_pk_bf16_f32 v53, v58, v53
	global_store_dwordx4 v[54:55], v[50:53], off
	s_nop 1
	v_mul_f32_e32 v50, 0xbfb8aa3b, v46
	v_exp_f32_e32 v50, v50
	v_mul_f32_e32 v51, 0xbfb8aa3b, v42
	v_exp_f32_e32 v51, v51
	v_add_u32_e32 v52, 0x90, v147
	v_add_f32_e32 v50, 1.0, v50
	v_rcp_f32_e32 v53, v50
	v_add_f32_e32 v50, 1.0, v51
	v_rcp_f32_e32 v54, v50
	v_mad_i64_i32 v[50:51], s[62:63], v52, s90, v[134:135]
	v_mul_f32_e32 v46, v46, v53
	v_mul_f32_e32 v46, v46, v38
	v_mul_f32_e32 v38, v42, v54
	v_mul_f32_e32 v42, 0xbfb8aa3b, v47
	v_exp_f32_e32 v42, v42
	v_mul_f32_e32 v52, 0xbfb8aa3b, v43
	v_mul_f32_e32 v53, v38, v34
	v_exp_f32_e32 v52, v52
	v_add_f32_e32 v34, 1.0, v42
	v_rcp_f32_e32 v34, v34
	v_mul_f32_e32 v42, 0xbfb8aa3b, v48
	v_exp_f32_e32 v42, v42
	v_add_f32_e32 v38, 1.0, v52
	v_mul_f32_e32 v34, v47, v34
	v_rcp_f32_e32 v38, v38
	v_mul_f32_e32 v34, v34, v39
	v_add_f32_e32 v39, 1.0, v42
; __device__ __forceinline__ unsigned cvt_pk_bf16(float lo, float hi) { unsigned r; asm volatile("v_cvt_pk_bf16_f32 %0, %1, %2" : "=v"(r) : "v"(lo), "v"(hi)); return r; }
; __device__ __forceinline__ float silu_f(float x) { return x * sigmoid_f(x); }
; #define PG8_WAIT_V(n) asm volatile("s_waitcnt vmcnt(" #n ")" ::: "memory")
; #define PG8_BAR __builtin_amdgcn_s_barrier()
;     __device__ __forceinline__ void operator()(const f32x4 (&acc)[2][2][4][2], const Unit& u, int wr, int wc, int fr, int fq) const {
;         const int row0 = u.pm * BM + wr * 64 + fr, col0 = u.pn * HALF + wc * 32 + 8 * fq;
; #pragma unroll
;         for (int ai = 0; ai < 2; ++ai)
; #pragma unroll
;             for (int m = 0; m < 4; ++m) { bf16_t* rowp = O + (size_t)(row0 + ai * HALF + m * 16) * ldc + col0;
;                 const f32x4 g0 = acc[ai][0][m][0], g1 = acc[ai][0][m][1], u0 = acc[ai][1][m][0], u1 = acc[ai][1][m][1];
;                 f32x4 v0, v1;
; #pragma unroll
;                 for (int j = 0; j < 4; ++j) { v0[j] = silu_f(g0[j]) * u0[j]; v1[j] = silu_f(g1[j]) * u1[j]; }
;                 u32x4 w; w.x = cvt_pk_bf16(v0[0], v0[1]); w.y = cvt_pk_bf16(v0[2], v0[3]); w.z = cvt_pk_bf16(v1[0], v1[1]); w.w = cvt_pk_bf16(v1[2], v1[3]);
;                 *(u32x4*)rowp = w; }
; template <class Epi, class Sched, bool ALIGN_EPI = false, bool SP2 = false>
; __device__ __forceinline__ void gemm_phase(PG8_LAS unsigned char* lds, const Gemm g, const Sched& S, const Epi& E) {
;     ...
;     PG8_WAIT_V(0);
;     if constexpr (!ALIGN_EPI) { if (wr == 0) PG8_BAR; }
;     PG8_BAR;
	v_rcp_f32_e32 v39, v39
	v_mul_f32_e32 v38, v43, v38
	v_mul_f32_e32 v42, 0xbfb8aa3b, v44
	v_mul_f32_e32 v43, v38, v35
	v_mul_f32_e32 v35, v48, v39
	v_exp_f32_e32 v42, v42
	v_mul_f32_e32 v35, v35, v40
	v_mul_f32_e32 v39, 0xbfb8aa3b, v49
	v_mul_f32_e32 v40, 0xbfb8aa3b, v45
	v_exp_f32_e32 v39, v39
	v_exp_f32_e32 v40, v40
	v_add_f32_e32 v38, 1.0, v42
	v_rcp_f32_e32 v38, v38
	v_add_f32_e32 v39, 1.0, v39
	v_add_f32_e32 v40, 1.0, v40
	v_rcp_f32_e32 v39, v39
	v_rcp_f32_e32 v40, v40
	v_mul_f32_e32 v38, v44, v38
	v_mul_f32_e32 v42, v38, v36
	v_mul_f32_e32 v36, v49, v39
	v_mul_f32_e32 v38, v45, v40
	v_mul_f32_e32 v36, v36, v41
	v_mul_f32_e32 v37, v38, v37
	v_lshl_add_u64 v[38:39], v[50:51], 0, v[114:115]
	v_cvt_pk_bf16_f32 v34, v46, v34
	v_cvt_pk_bf16_f32 v35, v35, v36
	v_cvt_pk_bf16_f32 v36, v53, v43
	v_cvt_pk_bf16_f32 v37, v42, v37
	global_store_dwordx4 v[38:39], v[34:37], off
	s_nop 1
	v_mul_f32_e32 v34, 0xbfb8aa3b, v30
	v_exp_f32_e32 v34, v34
	v_mul_f32_e32 v35, 0xbfb8aa3b, v26
	v_exp_f32_e32 v35, v35
	v_add_u32_e32 v36, 0xa0, v147
	v_add_f32_e32 v34, 1.0, v34
	v_rcp_f32_e32 v37, v34
	v_add_f32_e32 v34, 1.0, v35
	v_rcp_f32_e32 v38, v34
	v_mad_i64_i32 v[34:35], s[62:63], v36, s90, v[134:135]
	v_mul_f32_e32 v30, v30, v37
	v_mul_f32_e32 v30, v30, v22
	v_mul_f32_e32 v22, v26, v38
	v_mul_f32_e32 v26, 0xbfb8aa3b, v31
	v_exp_f32_e32 v26, v26
	v_mul_f32_e32 v36, 0xbfb8aa3b, v27
	v_mul_f32_e32 v37, v22, v18
	v_exp_f32_e32 v36, v36
	v_add_f32_e32 v18, 1.0, v26
	v_rcp_f32_e32 v18, v18
	v_mul_f32_e32 v26, 0xbfb8aa3b, v32
	v_exp_f32_e32 v26, v26
	v_add_f32_e32 v22, 1.0, v36
	v_mul_f32_e32 v18, v31, v18
	v_rcp_f32_e32 v22, v22
	v_mul_f32_e32 v18, v18, v23
	v_add_f32_e32 v23, 1.0, v26
	v_rcp_f32_e32 v23, v23
	v_mul_f32_e32 v22, v27, v22
	v_mul_f32_e32 v26, 0xbfb8aa3b, v28
	v_mul_f32_e32 v27, v22, v19
	v_mul_f32_e32 v19, v32, v23
	v_exp_f32_e32 v26, v26
	v_mul_f32_e32 v19, v19, v24
	v_mul_f32_e32 v23, 0xbfb8aa3b, v33
	v_mul_f32_e32 v24, 0xbfb8aa3b, v29
	v_exp_f32_e32 v23, v23
	v_exp_f32_e32 v24, v24
	v_add_f32_e32 v22, 1.0, v26
	v_rcp_f32_e32 v22, v22
	v_add_f32_e32 v23, 1.0, v23
	v_add_f32_e32 v24, 1.0, v24
	v_rcp_f32_e32 v23, v23
	v_rcp_f32_e32 v24, v24
	v_mul_f32_e32 v22, v28, v22
	v_mul_f32_e32 v26, v22, v20
	v_mul_f32_e32 v20, v33, v23
	v_mul_f32_e32 v22, v29, v24
	v_mul_f32_e32 v20, v20, v25
	v_mul_f32_e32 v21, v22, v21
	v_lshl_add_u64 v[22:23], v[34:35], 0, v[114:115]
	v_cvt_pk_bf16_f32 v18, v30, v18
	v_cvt_pk_bf16_f32 v19, v19, v20
	v_cvt_pk_bf16_f32 v20, v37, v27
	v_cvt_pk_bf16_f32 v21, v26, v21
	global_store_dwordx4 v[22:23], v[18:21], off
	s_nop 1
	v_mul_f32_e32 v18, 0xbfb8aa3b, v14
	v_exp_f32_e32 v18, v18
	v_mul_f32_e32 v19, 0xbfb8aa3b, v10
	v_exp_f32_e32 v19, v19
	v_add_u32_e32 v20, 0xb0, v147
	v_add_f32_e32 v18, 1.0, v18
	v_rcp_f32_e32 v21, v18
	v_add_f32_e32 v18, 1.0, v19
	v_rcp_f32_e32 v22, v18
	v_mad_i64_i32 v[18:19], s[62:63], v20, s90, v[134:135]
	v_mul_f32_e32 v14, v14, v21
	v_mul_f32_e32 v14, v14, v6
	v_mul_f32_e32 v6, v10, v22
	v_mul_f32_e32 v10, 0xbfb8aa3b, v15
	v_exp_f32_e32 v10, v10
	v_mul_f32_e32 v20, 0xbfb8aa3b, v11
	v_mul_f32_e32 v21, v6, v2
	v_exp_f32_e32 v20, v20
	v_add_f32_e32 v2, 1.0, v10
	v_rcp_f32_e32 v2, v2
	v_mul_f32_e32 v10, 0xbfb8aa3b, v16
	v_exp_f32_e32 v10, v10
	v_add_f32_e32 v6, 1.0, v20
	v_mul_f32_e32 v2, v15, v2
	v_rcp_f32_e32 v6, v6
	v_mul_f32_e32 v2, v2, v7
	v_add_f32_e32 v7, 1.0, v10
	v_rcp_f32_e32 v7, v7
	v_mul_f32_e32 v6, v11, v6
	v_mul_f32_e32 v10, 0xbfb8aa3b, v12
	v_mul_f32_e32 v11, v6, v3
	v_mul_f32_e32 v3, v16, v7
	v_exp_f32_e32 v10, v10
	v_mul_f32_e32 v3, v3, v8
	v_mul_f32_e32 v7, 0xbfb8aa3b, v17
	v_mul_f32_e32 v8, 0xbfb8aa3b, v13
	v_exp_f32_e32 v7, v7
	v_exp_f32_e32 v8, v8
	v_add_f32_e32 v6, 1.0, v10
	v_rcp_f32_e32 v6, v6
	v_add_f32_e32 v7, 1.0, v7
	v_add_f32_e32 v8, 1.0, v8
	v_rcp_f32_e32 v7, v7
	v_rcp_f32_e32 v8, v8
	v_mul_f32_e32 v6, v12, v6
	v_mul_f32_e32 v10, v6, v4
	v_mul_f32_e32 v4, v17, v7
	v_mul_f32_e32 v6, v13, v8
	v_mul_f32_e32 v4, v4, v9
	v_mul_f32_e32 v5, v6, v5
	v_lshl_add_u64 v[6:7], v[18:19], 0, v[114:115]
	s_mov_b64 s[62:63], s[16:17]
	v_cvt_pk_bf16_f32 v2, v14, v2
	v_cvt_pk_bf16_f32 v3, v3, v4
	v_cvt_pk_bf16_f32 v4, v21, v11
	v_cvt_pk_bf16_f32 v5, v10, v5
	global_store_dwordx4 v[6:7], v[2:5], off
	s_cbranch_vccz .LBB0_135
	s_waitcnt vmcnt(0)
	s_cmpk_gt_u32 s3, 0xff
	s_cbranch_scc1 .LBB0_142
	s_barrier

; #define PG8_STAGE(bufoff, gbase, voff) do { _Pragma("unroll") for (int _i = 0; _i < 2; ++_i) \
;         asm volatile("s_mov_b32 m0, %2\n\ts_nop 0\n\tglobal_load_lds_dwordx4 %0, %1" :: "v"((voff)[_i]), "s"((const char*)(gbase)), "s"(ldsbase + (unsigned)(bufoff) + ldsw + (unsigned)_i * 8192u) : "memory", "m0"); } while (0)
; #define PG8_LDA(dst, b, h) do { _Pragma("unroll") for (int m = 0; m < 4; ++m) _Pragma("unroll") for (int k = 0; k < 2; ++k) dst[m][k] = *(const PG8_LAS bf16x8*)(lds + PG8_SA(b, h) + aoff + m * 2048 + k * 1024); } while (0)
; #define PG8_WAIT_V(n) asm volatile("s_waitcnt vmcnt(" #n ")" ::: "memory")
; template <class Epi, class Sched, bool ALIGN_EPI = false, bool SP2 = false>
; __device__ __forceinline__ void gemm_phase(PG8_LAS unsigned char* lds, const Gemm g, const Sched& S, const Epi& E) {
;     ...
;             const bool last = (t == nt - 2);
;             const char* a1 = cA + (size_t)(t + 1) * kstep;
;             const char* a2 = last ? nA : cA + (size_t)(t + 2) * kstep; const char* b2 = last ? nB : cB + (size_t)(t + 2) * kstep;
;             const char* a3 = a2 + kstep; const char* b3 = b2 + kstep;
;             if (last && has_next) S.a_ready(nxt);
;             if constexpr (epi_has_mid<Epi>::value) { if (t == Epi::MID_T) E.mid(acc, cur, wr, wc, fr, fq); }
;             if constexpr (SP2) {
;             PG8_LDB(B0, 0, 0); PG8_LDB(B1, 0, 1); PG8_SCHED; PG8_LDA(At, 0, 0); PG8_STAGE(PG8_SA(1, 1), a1 + hstep, voffA);
;             PG8_WAIT_V(8); PG8_WAIT_L(0); PG8_BAR; PG8_MMA(0, 0, At, B0); PG8_MMA(0, 1, At, B1); PG8_BAR; PG8_SCHED;
;             PG8_LDA(At, 0, 1); PG8_STAGE(PG8_SB(0, 0), b2, voffB); PG8_STAGE(PG8_SB(0, 1), b2 + hstep, voffB); PG8_STAGE(PG8_SA(0, 0), a2, voffA);
;             PG8_WAIT_V(8); PG8_WAIT_L(0); PG8_BAR; PG8_MMA(1, 0, At, B0); PG8_MMA(1, 1, At, B1); PG8_BAR; PG8_SCHED;
;             PG8_LDB(B0, 1, 0); PG8_LDB(B1, 1, 1); PG8_SCHED; PG8_LDA(At, 1, 0); PG8_STAGE(PG8_SA(0, 1), a2 + hstep, voffA);
;             PG8_WAIT_V(8); PG8_WAIT_L(0); PG8_BAR; PG8_MMA(0, 0, At, B0); PG8_MMA(0, 1, At, B1); PG8_BAR; PG8_SCHED;
;             PG8_LDA(At, 1, 1); PG8_STAGE(PG8_SB(1, 0), b3, voffB); PG8_STAGE(PG8_SB(1, 1), b3 + hstep, voffB); PG8_STAGE(PG8_SA(1, 0), a3, voffA);
;             PG8_WAIT_V(8); PG8_WAIT_L(0); PG8_BAR; PG8_MMA(1, 0, At, B0); PG8_MMA(1, 1, At, B1); PG8_BAR; PG8_SCHED;
.LBB0_234:
	ds_read_b128 v[134:137], v145
	ds_read_b128 v[152:155], v145 offset:1024
	ds_read_b128 v[156:159], v145 offset:2048
	ds_read_b128 v[160:163], v145 offset:3072
	ds_read_b128 v[164:167], v146
	ds_read_b128 v[168:171], v146 offset:1024
	ds_read_b128 v[172:175], v146 offset:2048
	ds_read_b128 v[176:179], v146 offset:3072
	s_cmpk_eq_i32 s57, 0xa8
	s_cselect_b32 s76, s4, s53
	s_cselect_b32 s77, s5, s54
	s_cselect_b32 s66, s46, s55
	s_cselect_b32 s67, s47, s56
	s_add_u32 s62, s76, 0x80
	s_addc_u32 s63, s77, 0
	ds_read_b128 v[180:183], v147
	ds_read_b128 v[184:187], v147 offset:1024
	ds_read_b128 v[188:191], v147 offset:2048
	ds_read_b128 v[192:195], v147 offset:3072
	ds_read_b128 v[196:199], v147 offset:4096
	ds_read_b128 v[200:203], v147 offset:5120
	ds_read_b128 v[204:207], v147 offset:6144
	ds_read_b128 v[208:211], v147 offset:7168
	s_mov_b32 m0, s94
	s_nop 0
	global_load_lds_dwordx4 v1, s[50:51]
	s_nop 0
	s_mov_b32 m0, s95
	s_nop 0
	global_load_lds_dwordx4 v141, s[50:51]
	s_waitcnt vmcnt(8)
	s_waitcnt lgkmcnt(0)
	s_setprio 1
	s_barrier
	v_mfma_f32_16x16x32_bf16 v[126:129], v[134:137], v[180:183], v[126:129]
	v_mfma_f32_16x16x32_bf16 v[122:125], v[156:159], v[180:183], v[122:125]
	s_waitcnt lgkmcnt(5)
	v_mfma_f32_16x16x32_bf16 v[110:113], v[134:137], v[188:191], v[110:113]
	v_mfma_f32_16x16x32_bf16 v[106:109], v[156:159], v[188:191], v[106:109]
	s_waitcnt lgkmcnt(3)
	v_mfma_f32_16x16x32_bf16 v[94:97], v[134:137], v[196:199], v[94:97]
	v_mfma_f32_16x16x32_bf16 v[90:93], v[156:159], v[196:199], v[90:93]
	s_waitcnt lgkmcnt(1)
	v_mfma_f32_16x16x32_bf16 v[78:81], v[134:137], v[204:207], v[78:81]
	v_mfma_f32_16x16x32_bf16 v[74:77], v[156:159], v[204:207], v[74:77]
	v_mfma_f32_16x16x32_bf16 v[126:129], v[152:155], v[184:187], v[126:129]
	v_mfma_f32_16x16x32_bf16 v[122:125], v[160:163], v[184:187], v[122:125]
	v_mfma_f32_16x16x32_bf16 v[110:113], v[152:155], v[192:195], v[110:113]
	v_mfma_f32_16x16x32_bf16 v[106:109], v[160:163], v[192:195], v[106:109]
	v_mfma_f32_16x16x32_bf16 v[94:97], v[152:155], v[200:203], v[94:97]
	v_mfma_f32_16x16x32_bf16 v[90:93], v[160:163], v[200:203], v[90:93]
	s_waitcnt lgkmcnt(0)
	v_mfma_f32_16x16x32_bf16 v[78:81], v[152:155], v[208:211], v[78:81]
	v_mfma_f32_16x16x32_bf16 v[74:77], v[160:163], v[208:211], v[74:77]
	s_setprio 0
	s_setprio 1
	v_mfma_f32_16x16x32_bf16 v[118:121], v[164:167], v[180:183], v[118:121]
	v_mfma_f32_16x16x32_bf16 v[114:117], v[172:175], v[180:183], v[114:117]
	v_mfma_f32_16x16x32_bf16 v[102:105], v[164:167], v[188:191], v[102:105]
	v_mfma_f32_16x16x32_bf16 v[98:101], v[172:175], v[188:191], v[98:101]
	v_mfma_f32_16x16x32_bf16 v[86:89], v[164:167], v[196:199], v[86:89]
	v_mfma_f32_16x16x32_bf16 v[82:85], v[172:175], v[196:199], v[82:85]
	v_mfma_f32_16x16x32_bf16 v[70:73], v[164:167], v[204:207], v[70:73]
	v_mfma_f32_16x16x32_bf16 v[66:69], v[172:175], v[204:207], v[66:69]
	v_mfma_f32_16x16x32_bf16 v[118:121], v[168:171], v[184:187], v[118:121]
	v_mfma_f32_16x16x32_bf16 v[114:117], v[176:179], v[184:187], v[114:117]
	v_mfma_f32_16x16x32_bf16 v[102:105], v[168:171], v[192:195], v[102:105]
	v_mfma_f32_16x16x32_bf16 v[98:101], v[176:179], v[192:195], v[98:101]
	v_mfma_f32_16x16x32_bf16 v[86:89], v[168:171], v[200:203], v[86:89]
	v_mfma_f32_16x16x32_bf16 v[82:85], v[176:179], v[200:203], v[82:85]
	v_mfma_f32_16x16x32_bf16 v[70:73], v[168:171], v[208:211], v[70:73]
	s_setprio 2
	s_barrier
	v_mfma_f32_16x16x32_bf16 v[66:69], v[176:179], v[208:211], v[66:69]
	s_setprio 0
	ds_read_b128 v[180:183], v147 offset:16384
	ds_read_b128 v[184:187], v147 offset:17408
	ds_read_b128 v[188:191], v147 offset:18432
	ds_read_b128 v[192:195], v147 offset:19456
	ds_read_b128 v[196:199], v147 offset:20480
	ds_read_b128 v[200:203], v147 offset:21504
	ds_read_b128 v[204:207], v147 offset:22528
	ds_read_b128 v[208:211], v147 offset:23552
	s_mov_b32 m0, s64
	s_nop 0
	global_load_lds_dwordx4 v140, s[66:67]
	s_add_u32 s58, s66, 0x2b0000
	s_mov_b32 m0, s65
	s_nop 0
	global_load_lds_dwordx4 v142, s[66:67]
	s_addc_u32 s59, s67, 0
	s_mov_b32 m0, s82
	s_nop 0
	global_load_lds_dwordx4 v140, s[58:59]
	s_nop 0
	s_mov_b32 m0, s83
	s_nop 0
	global_load_lds_dwordx4 v142, s[58:59]
	s_nop 0
	s_mov_b32 m0, s35
	s_nop 0
	global_load_lds_dwordx4 v1, s[76:77]
	s_nop 0
	s_mov_b32 m0, s84
	s_nop 0
	global_load_lds_dwordx4 v141, s[76:77]
	s_waitcnt vmcnt(8)
	s_waitcnt lgkmcnt(0)
	s_setprio 1
	s_barrier
	v_mfma_f32_16x16x32_bf16 v[62:65], v[134:137], v[180:183], v[62:65]
	v_mfma_f32_16x16x32_bf16 v[58:61], v[156:159], v[180:183], v[58:61]
	s_waitcnt lgkmcnt(5)
	v_mfma_f32_16x16x32_bf16 v[46:49], v[134:137], v[188:191], v[46:49]
	v_mfma_f32_16x16x32_bf16 v[42:45], v[156:159], v[188:191], v[42:45]
	s_waitcnt lgkmcnt(3)
	v_mfma_f32_16x16x32_bf16 v[30:33], v[134:137], v[196:199], v[30:33]
	v_mfma_f32_16x16x32_bf16 v[26:29], v[156:159], v[196:199], v[26:29]
	s_waitcnt lgkmcnt(1)
	v_mfma_f32_16x16x32_bf16 v[14:17], v[134:137], v[204:207], v[14:17]
	v_mfma_f32_16x16x32_bf16 v[10:13], v[156:159], v[204:207], v[10:13]
	v_mfma_f32_16x16x32_bf16 v[62:65], v[152:155], v[184:187], v[62:65]
	v_mfma_f32_16x16x32_bf16 v[58:61], v[160:163], v[184:187], v[58:61]
	v_mfma_f32_16x16x32_bf16 v[46:49], v[152:155], v[192:195], v[46:49]
	v_mfma_f32_16x16x32_bf16 v[42:45], v[160:163], v[192:195], v[42:45]
	v_mfma_f32_16x16x32_bf16 v[30:33], v[152:155], v[200:203], v[30:33]
	v_mfma_f32_16x16x32_bf16 v[26:29], v[160:163], v[200:203], v[26:29]
	s_waitcnt lgkmcnt(0)
	v_mfma_f32_16x16x32_bf16 v[14:17], v[152:155], v[208:211], v[14:17]
	v_mfma_f32_16x16x32_bf16 v[10:13], v[160:163], v[208:211], v[10:13]
	s_setprio 0
	s_setprio 1
	v_mfma_f32_16x16x32_bf16 v[54:57], v[164:167], v[180:183], v[54:57]
	v_mfma_f32_16x16x32_bf16 v[50:53], v[172:175], v[180:183], v[50:53]
	v_mfma_f32_16x16x32_bf16 v[38:41], v[164:167], v[188:191], v[38:41]
	v_mfma_f32_16x16x32_bf16 v[34:37], v[172:175], v[188:191], v[34:37]
	v_mfma_f32_16x16x32_bf16 v[22:25], v[164:167], v[196:199], v[22:25]
	v_mfma_f32_16x16x32_bf16 v[18:21], v[172:175], v[196:199], v[18:21]
	v_mfma_f32_16x16x32_bf16 v[6:9], v[164:167], v[204:207], v[6:9]
	v_mfma_f32_16x16x32_bf16 v[2:5], v[172:175], v[204:207], v[2:5]
	v_mfma_f32_16x16x32_bf16 v[54:57], v[168:171], v[184:187], v[54:57]
	v_mfma_f32_16x16x32_bf16 v[50:53], v[176:179], v[184:187], v[50:53]
	v_mfma_f32_16x16x32_bf16 v[38:41], v[168:171], v[192:195], v[38:41]
	v_mfma_f32_16x16x32_bf16 v[34:37], v[176:179], v[192:195], v[34:37]
	v_mfma_f32_16x16x32_bf16 v[22:25], v[168:171], v[200:203], v[22:25]
	v_mfma_f32_16x16x32_bf16 v[18:21], v[176:179], v[200:203], v[18:21]
	v_mfma_f32_16x16x32_bf16 v[6:9], v[168:171], v[208:211], v[6:9]
	s_setprio 2
	s_barrier
; #define PG8_STAGE(bufoff, gbase, voff) do { _Pragma("unroll") for (int _i = 0; _i < 2; ++_i) \
;         asm volatile("s_mov_b32 m0, %2\n\ts_nop 0\n\tglobal_load_lds_dwordx4 %0, %1" :: "v"((voff)[_i]), "s"((const char*)(gbase)), "s"(ldsbase + (unsigned)(bufoff) + ldsw + (unsigned)_i * 8192u) : "memory", "m0"); } while (0)
; #define PG8_LDA(dst, b, h) do { _Pragma("unroll") for (int m = 0; m < 4; ++m) _Pragma("unroll") for (int k = 0; k < 2; ++k) dst[m][k] = *(const PG8_LAS bf16x8*)(lds + PG8_SA(b, h) + aoff + m * 2048 + k * 1024); } while (0)
; #define PG8_LDB(dst, b, h) do { _Pragma("unroll") for (int n = 0; n < 2; ++n) _Pragma("unroll") for (int k = 0; k < 2; ++k) dst[n][k] = *(const PG8_LAS bf16x8*)(lds + PG8_SB(b, h) + boff + n * 2048 + k * 1024); } while (0)
; #define PG8_MMA(ai, bj, At, Bt) do { __builtin_amdgcn_s_setprio(1); _Pragma("unroll") for (int m = 0; m < 4; ++m) _Pragma("unroll") for (int n = 0; n < 2; ++n) _Pragma("unroll") for (int k = 0; k < 2; ++k) \
;         acc[ai][bj][m][n] = __builtin_amdgcn_mfma_f32_16x16x32_bf16(Bt[n][k], At[m][k], acc[ai][bj][m][n], 0, 0, 0); __builtin_amdgcn_s_setprio(0); } while (0)
; template <class Epi, class Sched, bool ALIGN_EPI = false, bool SP2 = false>
; __device__ __forceinline__ void gemm_phase(PG8_LAS unsigned char* lds, const Gemm g, const Sched& S, const Epi& E) {
;     ...
;             PG8_LDB(B0, 0, 0); PG8_LDB(B1, 0, 1); PG8_SCHED; PG8_LDA(At, 0, 0); PG8_STAGE(PG8_SA(1, 1), a1 + hstep, voffA);
;             PG8_WAIT_V(8); PG8_WAIT_L(0); PG8_BAR; PG8_MMA(0, 0, At, B0); PG8_MMA(0, 1, At, B1); PG8_BAR; PG8_SCHED;
;             PG8_LDA(At, 0, 1); PG8_STAGE(PG8_SB(0, 0), b2, voffB); PG8_STAGE(PG8_SB(0, 1), b2 + hstep, voffB); PG8_STAGE(PG8_SA(0, 0), a2, voffA);
;             PG8_WAIT_V(8); PG8_WAIT_L(0); PG8_BAR; PG8_MMA(1, 0, At, B0); PG8_MMA(1, 1, At, B1); PG8_BAR; PG8_SCHED;
;             PG8_LDB(B0, 1, 0); PG8_LDB(B1, 1, 1); PG8_SCHED; PG8_LDA(At, 1, 0); PG8_STAGE(PG8_SA(0, 1), a2 + hstep, voffA);
;             PG8_WAIT_V(8); PG8_WAIT_L(0); PG8_BAR; PG8_MMA(0, 0, At, B0); PG8_MMA(0, 1, At, B1); PG8_BAR; PG8_SCHED;
;             PG8_LDA(At, 1, 1); PG8_STAGE(PG8_SB(1, 0), b3, voffB); PG8_STAGE(PG8_SB(1, 1), b3 + hstep, voffB); PG8_STAGE(PG8_SA(1, 0), a3, voffA);
;             PG8_WAIT_V(8); PG8_WAIT_L(0); PG8_BAR; PG8_MMA(1, 0, At, B0); PG8_MMA(1, 1, At, B1); PG8_BAR; PG8_SCHED;
	v_mfma_f32_16x16x32_bf16 v[2:5], v[176:179], v[208:211], v[2:5]
	s_setprio 0
	ds_read_b128 v[134:137], v148
	ds_read_b128 v[152:155], v148 offset:1024
	ds_read_b128 v[156:159], v148 offset:2048
	ds_read_b128 v[160:163], v148 offset:3072
	ds_read_b128 v[164:167], v149
	ds_read_b128 v[168:171], v149 offset:1024
	ds_read_b128 v[172:175], v149 offset:2048
	ds_read_b128 v[176:179], v149 offset:3072
	ds_read_b128 v[180:183], v147 offset:32768
	ds_read_b128 v[184:187], v147 offset:33792
	ds_read_b128 v[188:191], v147 offset:34816
	ds_read_b128 v[192:195], v147 offset:35840
	ds_read_b128 v[196:199], v147 offset:36864
	ds_read_b128 v[200:203], v147 offset:37888
	ds_read_b128 v[204:207], v147 offset:38912
	ds_read_b128 v[208:211], v147 offset:39936
	s_add_u32 s58, s76, 0x2b0000
	s_addc_u32 s59, s77, 0
	s_mov_b32 m0, s85
	s_nop 0
	global_load_lds_dwordx4 v1, s[58:59]
	s_nop 0
	s_mov_b32 m0, s86
	s_nop 0
	global_load_lds_dwordx4 v141, s[58:59]
	s_waitcnt vmcnt(8)
	s_waitcnt lgkmcnt(0)
	s_setprio 1
	s_barrier
	v_mfma_f32_16x16x32_bf16 v[126:129], v[134:137], v[180:183], v[126:129]
	v_mfma_f32_16x16x32_bf16 v[122:125], v[156:159], v[180:183], v[122:125]
	s_waitcnt lgkmcnt(5)
	v_mfma_f32_16x16x32_bf16 v[110:113], v[134:137], v[188:191], v[110:113]
	v_mfma_f32_16x16x32_bf16 v[106:109], v[156:159], v[188:191], v[106:109]
	s_waitcnt lgkmcnt(3)
	v_mfma_f32_16x16x32_bf16 v[94:97], v[134:137], v[196:199], v[94:97]
	v_mfma_f32_16x16x32_bf16 v[90:93], v[156:159], v[196:199], v[90:93]
	s_waitcnt lgkmcnt(1)
	v_mfma_f32_16x16x32_bf16 v[78:81], v[134:137], v[204:207], v[78:81]
	v_mfma_f32_16x16x32_bf16 v[74:77], v[156:159], v[204:207], v[74:77]
	v_mfma_f32_16x16x32_bf16 v[126:129], v[152:155], v[184:187], v[126:129]
	v_mfma_f32_16x16x32_bf16 v[122:125], v[160:163], v[184:187], v[122:125]
	v_mfma_f32_16x16x32_bf16 v[110:113], v[152:155], v[192:195], v[110:113]
	v_mfma_f32_16x16x32_bf16 v[106:109], v[160:163], v[192:195], v[106:109]
	v_mfma_f32_16x16x32_bf16 v[94:97], v[152:155], v[200:203], v[94:97]
	v_mfma_f32_16x16x32_bf16 v[90:93], v[160:163], v[200:203], v[90:93]
	s_waitcnt lgkmcnt(0)
	v_mfma_f32_16x16x32_bf16 v[78:81], v[152:155], v[208:211], v[78:81]
	v_mfma_f32_16x16x32_bf16 v[74:77], v[160:163], v[208:211], v[74:77]
	s_setprio 0
	s_setprio 1
	v_mfma_f32_16x16x32_bf16 v[118:121], v[164:167], v[180:183], v[118:121]
	v_mfma_f32_16x16x32_bf16 v[114:117], v[172:175], v[180:183], v[114:117]
	v_mfma_f32_16x16x32_bf16 v[102:105], v[164:167], v[188:191], v[102:105]
	v_mfma_f32_16x16x32_bf16 v[98:101], v[172:175], v[188:191], v[98:101]
	v_mfma_f32_16x16x32_bf16 v[86:89], v[164:167], v[196:199], v[86:89]
	v_mfma_f32_16x16x32_bf16 v[82:85], v[172:175], v[196:199], v[82:85]
	v_mfma_f32_16x16x32_bf16 v[70:73], v[164:167], v[204:207], v[70:73]
	v_mfma_f32_16x16x32_bf16 v[66:69], v[172:175], v[204:207], v[66:69]
	v_mfma_f32_16x16x32_bf16 v[118:121], v[168:171], v[184:187], v[118:121]
	v_mfma_f32_16x16x32_bf16 v[114:117], v[176:179], v[184:187], v[114:117]
	v_mfma_f32_16x16x32_bf16 v[102:105], v[168:171], v[192:195], v[102:105]
	v_mfma_f32_16x16x32_bf16 v[98:101], v[176:179], v[192:195], v[98:101]
	v_mfma_f32_16x16x32_bf16 v[86:89], v[168:171], v[200:203], v[86:89]
	v_mfma_f32_16x16x32_bf16 v[82:85], v[176:179], v[200:203], v[82:85]
	v_mfma_f32_16x16x32_bf16 v[70:73], v[168:171], v[208:211], v[70:73]
	s_setprio 2
	s_barrier
	v_mfma_f32_16x16x32_bf16 v[66:69], v[176:179], v[208:211], v[66:69]
	s_setprio 0
	ds_read_b128 v[180:183], v147 offset:49152
	ds_read_b128 v[184:187], v147 offset:50176
	ds_read_b128 v[188:191], v147 offset:51200
	ds_read_b128 v[192:195], v147 offset:52224
	ds_read_b128 v[196:199], v147 offset:53248
	ds_read_b128 v[200:203], v147 offset:54272
	ds_read_b128 v[204:207], v147 offset:55296
	ds_read_b128 v[208:211], v147 offset:56320
	s_add_u32 s58, s66, 0x80
	s_addc_u32 s59, s67, 0
	s_mov_b32 m0, s88
	s_nop 0
	global_load_lds_dwordx4 v140, s[58:59]
	s_nop 0
	s_mov_b32 m0, s89
	s_nop 0
	global_load_lds_dwordx4 v142, s[58:59]
	s_add_u32 s58, s66, 0x2b0080
	s_addc_u32 s59, s67, 0
	s_mov_b32 m0, s92
	s_nop 0
	global_load_lds_dwordx4 v140, s[58:59]
	s_nop 0
	s_mov_b32 m0, s93
	s_nop 0
	global_load_lds_dwordx4 v142, s[58:59]
	s_nop 0
	s_mov_b32 m0, s90
	s_nop 0
	global_load_lds_dwordx4 v1, s[62:63]
	s_nop 0
	s_mov_b32 m0, s91
	s_nop 0
	global_load_lds_dwordx4 v141, s[62:63]
	s_waitcnt vmcnt(8)
	s_waitcnt lgkmcnt(0)
	s_setprio 1
	s_barrier
	v_mfma_f32_16x16x32_bf16 v[62:65], v[134:137], v[180:183], v[62:65]
	v_mfma_f32_16x16x32_bf16 v[58:61], v[156:159], v[180:183], v[58:61]
	s_waitcnt lgkmcnt(5)
	v_mfma_f32_16x16x32_bf16 v[46:49], v[134:137], v[188:191], v[46:49]
	v_mfma_f32_16x16x32_bf16 v[42:45], v[156:159], v[188:191], v[42:45]
	s_waitcnt lgkmcnt(3)
	v_mfma_f32_16x16x32_bf16 v[30:33], v[134:137], v[196:199], v[30:33]
	v_mfma_f32_16x16x32_bf16 v[26:29], v[156:159], v[196:199], v[26:29]
	s_waitcnt lgkmcnt(1)
	v_mfma_f32_16x16x32_bf16 v[14:17], v[134:137], v[204:207], v[14:17]
	v_mfma_f32_16x16x32_bf16 v[10:13], v[156:159], v[204:207], v[10:13]
	v_mfma_f32_16x16x32_bf16 v[62:65], v[152:155], v[184:187], v[62:65]
	v_mfma_f32_16x16x32_bf16 v[58:61], v[160:163], v[184:187], v[58:61]
	v_mfma_f32_16x16x32_bf16 v[46:49], v[152:155], v[192:195], v[46:49]
	v_mfma_f32_16x16x32_bf16 v[42:45], v[160:163], v[192:195], v[42:45]
	v_mfma_f32_16x16x32_bf16 v[30:33], v[152:155], v[200:203], v[30:33]
	v_mfma_f32_16x16x32_bf16 v[26:29], v[160:163], v[200:203], v[26:29]
	s_waitcnt lgkmcnt(0)
	v_mfma_f32_16x16x32_bf16 v[14:17], v[152:155], v[208:211], v[14:17]
	v_mfma_f32_16x16x32_bf16 v[10:13], v[160:163], v[208:211], v[10:13]
	s_setprio 0
	s_setprio 1
	v_mfma_f32_16x16x32_bf16 v[54:57], v[164:167], v[180:183], v[54:57]
	v_mfma_f32_16x16x32_bf16 v[50:53], v[172:175], v[180:183], v[50:53]
	v_mfma_f32_16x16x32_bf16 v[38:41], v[164:167], v[188:191], v[38:41]
	v_mfma_f32_16x16x32_bf16 v[34:37], v[172:175], v[188:191], v[34:37]
	v_mfma_f32_16x16x32_bf16 v[22:25], v[164:167], v[196:199], v[22:25]
	v_mfma_f32_16x16x32_bf16 v[18:21], v[172:175], v[196:199], v[18:21]
	v_mfma_f32_16x16x32_bf16 v[6:9], v[164:167], v[204:207], v[6:9]
	v_mfma_f32_16x16x32_bf16 v[2:5], v[172:175], v[204:207], v[2:5]
	v_mfma_f32_16x16x32_bf16 v[54:57], v[168:171], v[184:187], v[54:57]
	v_mfma_f32_16x16x32_bf16 v[50:53], v[176:179], v[184:187], v[50:53]
	v_mfma_f32_16x16x32_bf16 v[38:41], v[168:171], v[192:195], v[38:41]
	v_mfma_f32_16x16x32_bf16 v[34:37], v[176:179], v[192:195], v[34:37]
	v_mfma_f32_16x16x32_bf16 v[22:25], v[168:171], v[200:203], v[22:25]
	v_mfma_f32_16x16x32_bf16 v[18:21], v[176:179], v[200:203], v[18:21]
	v_mfma_f32_16x16x32_bf16 v[6:9], v[168:171], v[208:211], v[6:9]
	s_setprio 2
	s_barrier
	v_mfma_f32_16x16x32_bf16 v[2:5], v[176:179], v[208:211], v[2:5]
	s_setprio 0
	s_add_i32 s57, s57, 2
	s_add_u32 s53, s53, 0x100
	s_addc_u32 s54, s54, 0
	s_add_u32 s55, s55, 0x100
	s_addc_u32 s56, s56, 0
	s_add_u32 s50, s50, 0x100
	s_addc_u32 s51, s51, 0
	s_cmpk_gt_u32 s57, 0xa9
	s_cbranch_scc0 .LBB0_234
	s_and_b64 vcc, exec, s[16:17]
	s_cbranch_vccz .LBB0_237
	s_barrier

; #define PG8_STAGE(bufoff, gbase, voff) do { _Pragma("unroll") for (int _i = 0; _i < 2; ++_i) \
;         asm volatile("s_mov_b32 m0, %2\n\ts_nop 0\n\tglobal_load_lds_dwordx4 %0, %1" :: "v"((voff)[_i]), "s"((const char*)(gbase)), "s"(ldsbase + (unsigned)(bufoff) + ldsw + (unsigned)_i * 8192u) : "memory", "m0"); } while (0)
; #define PG8_LDA(dst, b, h) do { _Pragma("unroll") for (int m = 0; m < 4; ++m) _Pragma("unroll") for (int k = 0; k < 2; ++k) dst[m][k] = *(const PG8_LAS bf16x8*)(lds + PG8_SA(b, h) + aoff + m * 2048 + k * 1024); } while (0)
; #define PG8_LDB(dst, b, h) do { _Pragma("unroll") for (int n = 0; n < 2; ++n) _Pragma("unroll") for (int k = 0; k < 2; ++k) dst[n][k] = *(const PG8_LAS bf16x8*)(lds + PG8_SB(b, h) + boff + n * 2048 + k * 1024); } while (0)
; #define PG8_MMA(ai, bj, At, Bt) do { __builtin_amdgcn_s_setprio(1); _Pragma("unroll") for (int m = 0; m < 4; ++m) _Pragma("unroll") for (int n = 0; n < 2; ++n) _Pragma("unroll") for (int k = 0; k < 2; ++k) \
;         acc[ai][bj][m][n] = __builtin_amdgcn_mfma_f32_16x16x32_bf16(Bt[n][k], At[m][k], acc[ai][bj][m][n], 0, 0, 0); __builtin_amdgcn_s_setprio(0); } while (0)
; template <class Epi, class Sched, bool ALIGN_EPI = false, bool SP2 = false>
; __device__ __forceinline__ void gemm_phase(PG8_LAS unsigned char* lds, const Gemm g, const Sched& S, const Epi& E) {
;     ...
;             PG8_LDB(B0, 0, 0); PG8_LDB(B1, 0, 1); PG8_SCHED; PG8_LDA(At, 0, 0); PG8_STAGE(PG8_SA(1, 1), a1 + hstep, voffA);
;             PG8_WAIT_V(8); PG8_WAIT_L(0); PG8_BAR; PG8_MMA(0, 0, At, B0); PG8_MMA(0, 1, At, B1); PG8_BAR; PG8_SCHED;
;             PG8_LDA(At, 0, 1); PG8_STAGE(PG8_SB(0, 0), b2, voffB); PG8_STAGE(PG8_SB(0, 1), b2 + hstep, voffB); PG8_STAGE(PG8_SA(0, 0), a2, voffA);
;             PG8_WAIT_V(8); PG8_WAIT_L(0); PG8_BAR; PG8_MMA(1, 0, At, B0); PG8_MMA(1, 1, At, B1); PG8_BAR; PG8_SCHED;
;             PG8_LDB(B0, 1, 0); PG8_LDB(B1, 1, 1); PG8_SCHED; PG8_LDA(At, 1, 0); PG8_STAGE(PG8_SA(0, 1), a2 + hstep, voffA);
;             PG8_WAIT_V(8); PG8_WAIT_L(0); PG8_BAR; PG8_MMA(0, 0, At, B0); PG8_MMA(0, 1, At, B1); PG8_BAR; PG8_SCHED;
;             PG8_LDA(At, 1, 1); PG8_STAGE(PG8_SB(1, 0), b3, voffB); PG8_STAGE(PG8_SB(1, 1), b3 + hstep, voffB); PG8_STAGE(PG8_SA(1, 0), a3, voffA);
;             PG8_WAIT_V(8); PG8_WAIT_L(0); PG8_BAR; PG8_MMA(1, 0, At, B0); PG8_MMA(1, 1, At, B1); PG8_BAR; PG8_SCHED;
.LBB0_325:
	v_add_u32_e32 v138, 0x10000, v151
	ds_read_b128 v[154:157], v138
	ds_read_b128 v[158:161], v138 offset:1024
	ds_read_b128 v[162:165], v138 offset:2048
	ds_read_b128 v[166:169], v138 offset:3072
	v_add_u32_e32 v138, 0x14000, v151
	s_add_u32 s8, s82, 0x100
	ds_read_b128 v[170:173], v138
	ds_read_b128 v[174:177], v138 offset:1024
	ds_read_b128 v[178:181], v138 offset:2048
	ds_read_b128 v[182:185], v138 offset:3072
	s_addc_u32 s9, s83, 0
	s_and_b64 s[60:61], s[62:63], exec
	s_cselect_b32 s84, s54, s8
	s_cselect_b32 s85, s19, s9
	s_cselect_b32 s63, s17, s57
	s_cselect_b32 s62, s55, s56
	s_add_u32 s66, s84, 0x80
	s_addc_u32 s67, s85, 0
	s_add_u32 s76, s62, 0x80
	s_addc_u32 s77, s63, 0
	ds_read_b128 v[186:189], v152
	ds_read_b128 v[190:193], v152 offset:1024
	ds_read_b128 v[194:197], v152 offset:2048
	ds_read_b128 v[198:201], v152 offset:3072
	ds_read_b128 v[202:205], v152 offset:4096
	ds_read_b128 v[206:209], v152 offset:5120
	ds_read_b128 v[210:213], v152 offset:6144
	ds_read_b128 v[214:217], v152 offset:7168
	s_add_u32 s60, s82, 0x100080
	s_addc_u32 s61, s83, 0
	s_mov_b32 m0, s97
	s_nop 0
	global_load_lds_dwordx4 v141, s[60:61]
	s_nop 0
	s_mov_b32 m0, s70
	s_nop 0
	global_load_lds_dwordx4 v143, s[60:61]
	s_waitcnt vmcnt(8)
	s_waitcnt lgkmcnt(0)
	s_setprio 1
	s_barrier
	v_mfma_f32_16x16x32_bf16 v[126:129], v[154:157], v[186:189], v[126:129]
	v_mfma_f32_16x16x32_bf16 v[122:125], v[162:165], v[186:189], v[122:125]
	s_waitcnt lgkmcnt(5)
	v_mfma_f32_16x16x32_bf16 v[110:113], v[154:157], v[194:197], v[110:113]
	v_mfma_f32_16x16x32_bf16 v[106:109], v[162:165], v[194:197], v[106:109]
	s_waitcnt lgkmcnt(3)
	v_mfma_f32_16x16x32_bf16 v[94:97], v[154:157], v[202:205], v[94:97]
	v_mfma_f32_16x16x32_bf16 v[90:93], v[162:165], v[202:205], v[90:93]
	s_waitcnt lgkmcnt(1)
	v_mfma_f32_16x16x32_bf16 v[78:81], v[154:157], v[210:213], v[78:81]
	v_mfma_f32_16x16x32_bf16 v[74:77], v[162:165], v[210:213], v[74:77]
	v_mfma_f32_16x16x32_bf16 v[126:129], v[158:161], v[190:193], v[126:129]
	v_mfma_f32_16x16x32_bf16 v[122:125], v[166:169], v[190:193], v[122:125]
	v_mfma_f32_16x16x32_bf16 v[110:113], v[158:161], v[198:201], v[110:113]
	v_mfma_f32_16x16x32_bf16 v[106:109], v[166:169], v[198:201], v[106:109]
	v_mfma_f32_16x16x32_bf16 v[94:97], v[158:161], v[206:209], v[94:97]
	v_mfma_f32_16x16x32_bf16 v[90:93], v[166:169], v[206:209], v[90:93]
	s_waitcnt lgkmcnt(0)
	v_mfma_f32_16x16x32_bf16 v[78:81], v[158:161], v[214:217], v[78:81]
	v_mfma_f32_16x16x32_bf16 v[74:77], v[166:169], v[214:217], v[74:77]
	s_setprio 0
	s_setprio 1
	v_mfma_f32_16x16x32_bf16 v[118:121], v[170:173], v[186:189], v[118:121]
	v_mfma_f32_16x16x32_bf16 v[114:117], v[178:181], v[186:189], v[114:117]
	v_mfma_f32_16x16x32_bf16 v[102:105], v[170:173], v[194:197], v[102:105]
	v_mfma_f32_16x16x32_bf16 v[98:101], v[178:181], v[194:197], v[98:101]
	v_mfma_f32_16x16x32_bf16 v[86:89], v[170:173], v[202:205], v[86:89]
	v_mfma_f32_16x16x32_bf16 v[82:85], v[178:181], v[202:205], v[82:85]
	v_mfma_f32_16x16x32_bf16 v[70:73], v[170:173], v[210:213], v[70:73]
	v_mfma_f32_16x16x32_bf16 v[66:69], v[178:181], v[210:213], v[66:69]
	v_mfma_f32_16x16x32_bf16 v[118:121], v[174:177], v[190:193], v[118:121]
	v_mfma_f32_16x16x32_bf16 v[114:117], v[182:185], v[190:193], v[114:117]
	v_mfma_f32_16x16x32_bf16 v[102:105], v[174:177], v[198:201], v[102:105]
	v_mfma_f32_16x16x32_bf16 v[98:101], v[182:185], v[198:201], v[98:101]
	v_mfma_f32_16x16x32_bf16 v[86:89], v[174:177], v[206:209], v[86:89]
	v_mfma_f32_16x16x32_bf16 v[82:85], v[182:185], v[206:209], v[82:85]
	v_mfma_f32_16x16x32_bf16 v[70:73], v[174:177], v[214:217], v[70:73]
	s_setprio 2
	s_barrier
	v_mfma_f32_16x16x32_bf16 v[66:69], v[182:185], v[214:217], v[66:69]
	s_setprio 0
	ds_read_b128 v[186:189], v152 offset:16384
	ds_read_b128 v[190:193], v152 offset:17408
	ds_read_b128 v[194:197], v152 offset:18432
	ds_read_b128 v[198:201], v152 offset:19456
	ds_read_b128 v[202:205], v152 offset:20480
	ds_read_b128 v[206:209], v152 offset:21504
	ds_read_b128 v[210:213], v152 offset:22528
	ds_read_b128 v[214:217], v152 offset:23552
	s_mov_b32 m0, s68
	s_nop 0
	global_load_lds_dwordx4 v142, s[62:63]
	s_add_u32 s60, s62, 0x100000
	s_mov_b32 m0, s69
	s_nop 0
	global_load_lds_dwordx4 v144, s[62:63]
	s_addc_u32 s61, s63, 0
	s_mov_b32 m0, s81
	s_nop 0
	global_load_lds_dwordx4 v142, s[60:61]
	s_nop 0
	s_mov_b32 m0, s86
	s_nop 0
	global_load_lds_dwordx4 v144, s[60:61]
	s_nop 0
	s_mov_b32 m0, s65
	s_nop 0
	global_load_lds_dwordx4 v141, s[84:85]
	s_nop 0
	s_mov_b32 m0, s87
	s_nop 0
	global_load_lds_dwordx4 v143, s[84:85]
	s_waitcnt vmcnt(8)
	s_waitcnt lgkmcnt(0)
	s_setprio 1
	s_barrier
; #define PG8_STAGE(bufoff, gbase, voff) do { _Pragma("unroll") for (int _i = 0; _i < 2; ++_i) \
;         asm volatile("s_mov_b32 m0, %2\n\ts_nop 0\n\tglobal_load_lds_dwordx4 %0, %1" :: "v"((voff)[_i]), "s"((const char*)(gbase)), "s"(ldsbase + (unsigned)(bufoff) + ldsw + (unsigned)_i * 8192u) : "memory", "m0"); } while (0)
; #define PG8_LDA(dst, b, h) do { _Pragma("unroll") for (int m = 0; m < 4; ++m) _Pragma("unroll") for (int k = 0; k < 2; ++k) dst[m][k] = *(const PG8_LAS bf16x8*)(lds + PG8_SA(b, h) + aoff + m * 2048 + k * 1024); } while (0)
; #define PG8_LDB(dst, b, h) do { _Pragma("unroll") for (int n = 0; n < 2; ++n) _Pragma("unroll") for (int k = 0; k < 2; ++k) dst[n][k] = *(const PG8_LAS bf16x8*)(lds + PG8_SB(b, h) + boff + n * 2048 + k * 1024); } while (0)
; #define PG8_MMA(ai, bj, At, Bt) do { __builtin_amdgcn_s_setprio(1); _Pragma("unroll") for (int m = 0; m < 4; ++m) _Pragma("unroll") for (int n = 0; n < 2; ++n) _Pragma("unroll") for (int k = 0; k < 2; ++k) \
;         acc[ai][bj][m][n] = __builtin_amdgcn_mfma_f32_16x16x32_bf16(Bt[n][k], At[m][k], acc[ai][bj][m][n], 0, 0, 0); __builtin_amdgcn_s_setprio(0); } while (0)
; template <class Epi, class Sched, bool ALIGN_EPI = false, bool SP2 = false>
; __device__ __forceinline__ void gemm_phase(PG8_LAS unsigned char* lds, const Gemm g, const Sched& S, const Epi& E) {
;     ...
;             PG8_LDB(B0, 0, 0); PG8_LDB(B1, 0, 1); PG8_SCHED; PG8_LDA(At, 0, 0); PG8_STAGE(PG8_SA(1, 1), a1 + hstep, voffA);
;             PG8_WAIT_V(8); PG8_WAIT_L(0); PG8_BAR; PG8_MMA(0, 0, At, B0); PG8_MMA(0, 1, At, B1); PG8_BAR; PG8_SCHED;
;             PG8_LDA(At, 0, 1); PG8_STAGE(PG8_SB(0, 0), b2, voffB); PG8_STAGE(PG8_SB(0, 1), b2 + hstep, voffB); PG8_STAGE(PG8_SA(0, 0), a2, voffA);
;             PG8_WAIT_V(8); PG8_WAIT_L(0); PG8_BAR; PG8_MMA(1, 0, At, B0); PG8_MMA(1, 1, At, B1); PG8_BAR; PG8_SCHED;
;             PG8_LDB(B0, 1, 0); PG8_LDB(B1, 1, 1); PG8_SCHED; PG8_LDA(At, 1, 0); PG8_STAGE(PG8_SA(0, 1), a2 + hstep, voffA);
;             PG8_WAIT_V(8); PG8_WAIT_L(0); PG8_BAR; PG8_MMA(0, 0, At, B0); PG8_MMA(0, 1, At, B1); PG8_BAR; PG8_SCHED;
;             PG8_LDA(At, 1, 1); PG8_STAGE(PG8_SB(1, 0), b3, voffB); PG8_STAGE(PG8_SB(1, 1), b3 + hstep, voffB); PG8_STAGE(PG8_SA(1, 0), a3, voffA);
;             PG8_WAIT_V(8); PG8_WAIT_L(0); PG8_BAR; PG8_MMA(1, 0, At, B0); PG8_MMA(1, 1, At, B1); PG8_BAR; PG8_SCHED;
	v_mfma_f32_16x16x32_bf16 v[62:65], v[154:157], v[186:189], v[62:65]
	v_mfma_f32_16x16x32_bf16 v[58:61], v[162:165], v[186:189], v[58:61]
	s_waitcnt lgkmcnt(5)
	v_mfma_f32_16x16x32_bf16 v[46:49], v[154:157], v[194:197], v[46:49]
	v_mfma_f32_16x16x32_bf16 v[42:45], v[162:165], v[194:197], v[42:45]
	s_waitcnt lgkmcnt(3)
	v_mfma_f32_16x16x32_bf16 v[30:33], v[154:157], v[202:205], v[30:33]
	v_mfma_f32_16x16x32_bf16 v[26:29], v[162:165], v[202:205], v[26:29]
	s_waitcnt lgkmcnt(1)
	v_mfma_f32_16x16x32_bf16 v[14:17], v[154:157], v[210:213], v[14:17]
	v_mfma_f32_16x16x32_bf16 v[10:13], v[162:165], v[210:213], v[10:13]
	v_mfma_f32_16x16x32_bf16 v[62:65], v[158:161], v[190:193], v[62:65]
	v_mfma_f32_16x16x32_bf16 v[58:61], v[166:169], v[190:193], v[58:61]
	v_mfma_f32_16x16x32_bf16 v[46:49], v[158:161], v[198:201], v[46:49]
	v_mfma_f32_16x16x32_bf16 v[42:45], v[166:169], v[198:201], v[42:45]
	v_mfma_f32_16x16x32_bf16 v[30:33], v[158:161], v[206:209], v[30:33]
	v_mfma_f32_16x16x32_bf16 v[26:29], v[166:169], v[206:209], v[26:29]
	s_waitcnt lgkmcnt(0)
	v_mfma_f32_16x16x32_bf16 v[14:17], v[158:161], v[214:217], v[14:17]
	v_mfma_f32_16x16x32_bf16 v[10:13], v[166:169], v[214:217], v[10:13]
	s_setprio 0
	s_setprio 1
	v_mfma_f32_16x16x32_bf16 v[54:57], v[170:173], v[186:189], v[54:57]
	v_mfma_f32_16x16x32_bf16 v[50:53], v[178:181], v[186:189], v[50:53]
	v_mfma_f32_16x16x32_bf16 v[38:41], v[170:173], v[194:197], v[38:41]
	v_mfma_f32_16x16x32_bf16 v[34:37], v[178:181], v[194:197], v[34:37]
	v_mfma_f32_16x16x32_bf16 v[22:25], v[170:173], v[202:205], v[22:25]
	v_mfma_f32_16x16x32_bf16 v[18:21], v[178:181], v[202:205], v[18:21]
	v_mfma_f32_16x16x32_bf16 v[6:9], v[170:173], v[210:213], v[6:9]
	v_mfma_f32_16x16x32_bf16 v[2:5], v[178:181], v[210:213], v[2:5]
	v_mfma_f32_16x16x32_bf16 v[54:57], v[174:177], v[190:193], v[54:57]
	v_mfma_f32_16x16x32_bf16 v[50:53], v[182:185], v[190:193], v[50:53]
	v_mfma_f32_16x16x32_bf16 v[38:41], v[174:177], v[198:201], v[38:41]
	v_mfma_f32_16x16x32_bf16 v[34:37], v[182:185], v[198:201], v[34:37]
	v_mfma_f32_16x16x32_bf16 v[22:25], v[174:177], v[206:209], v[22:25]
	v_mfma_f32_16x16x32_bf16 v[18:21], v[182:185], v[206:209], v[18:21]
	v_mfma_f32_16x16x32_bf16 v[6:9], v[174:177], v[214:217], v[6:9]
	s_setprio 2
	s_barrier
	v_mfma_f32_16x16x32_bf16 v[2:5], v[182:185], v[214:217], v[2:5]
	s_setprio 0
	v_add_u32_e32 v138, 0x18000, v151
	ds_read_b128 v[154:157], v138
	ds_read_b128 v[158:161], v138 offset:1024
	ds_read_b128 v[162:165], v138 offset:2048
	ds_read_b128 v[166:169], v138 offset:3072
	v_add_u32_e32 v138, 0x1c000, v151
	ds_read_b128 v[170:173], v138
	ds_read_b128 v[174:177], v138 offset:1024
	ds_read_b128 v[178:181], v138 offset:2048
	ds_read_b128 v[182:185], v138 offset:3072
	ds_read_b128 v[186:189], v152 offset:32768
	ds_read_b128 v[190:193], v152 offset:33792
	ds_read_b128 v[194:197], v152 offset:34816
	ds_read_b128 v[198:201], v152 offset:35840
	ds_read_b128 v[202:205], v152 offset:36864
	ds_read_b128 v[206:209], v152 offset:37888
	ds_read_b128 v[210:213], v152 offset:38912
	ds_read_b128 v[214:217], v152 offset:39936
	s_add_u32 s60, s84, 0x100000
	s_addc_u32 s61, s85, 0
	s_mov_b32 m0, s88
	s_nop 0
	global_load_lds_dwordx4 v141, s[60:61]
	s_nop 0
	s_mov_b32 m0, s89
	s_nop 0
	global_load_lds_dwordx4 v143, s[60:61]
	s_waitcnt vmcnt(8)
	s_waitcnt lgkmcnt(0)
	s_setprio 1
	s_barrier
	v_mfma_f32_16x16x32_bf16 v[126:129], v[154:157], v[186:189], v[126:129]
	v_mfma_f32_16x16x32_bf16 v[122:125], v[162:165], v[186:189], v[122:125]
	s_waitcnt lgkmcnt(5)
	v_mfma_f32_16x16x32_bf16 v[110:113], v[154:157], v[194:197], v[110:113]
	v_mfma_f32_16x16x32_bf16 v[106:109], v[162:165], v[194:197], v[106:109]
	s_waitcnt lgkmcnt(3)
	v_mfma_f32_16x16x32_bf16 v[94:97], v[154:157], v[202:205], v[94:97]
	v_mfma_f32_16x16x32_bf16 v[90:93], v[162:165], v[202:205], v[90:93]
	s_waitcnt lgkmcnt(1)
	v_mfma_f32_16x16x32_bf16 v[78:81], v[154:157], v[210:213], v[78:81]
	v_mfma_f32_16x16x32_bf16 v[74:77], v[162:165], v[210:213], v[74:77]
	v_mfma_f32_16x16x32_bf16 v[126:129], v[158:161], v[190:193], v[126:129]
	v_mfma_f32_16x16x32_bf16 v[122:125], v[166:169], v[190:193], v[122:125]
	v_mfma_f32_16x16x32_bf16 v[110:113], v[158:161], v[198:201], v[110:113]
	v_mfma_f32_16x16x32_bf16 v[106:109], v[166:169], v[198:201], v[106:109]
	v_mfma_f32_16x16x32_bf16 v[94:97], v[158:161], v[206:209], v[94:97]
	v_mfma_f32_16x16x32_bf16 v[90:93], v[166:169], v[206:209], v[90:93]
	s_waitcnt lgkmcnt(0)
	v_mfma_f32_16x16x32_bf16 v[78:81], v[158:161], v[214:217], v[78:81]
	v_mfma_f32_16x16x32_bf16 v[74:77], v[166:169], v[214:217], v[74:77]
	s_setprio 0
	s_setprio 1
	v_mfma_f32_16x16x32_bf16 v[118:121], v[170:173], v[186:189], v[118:121]
	v_mfma_f32_16x16x32_bf16 v[114:117], v[178:181], v[186:189], v[114:117]
	v_mfma_f32_16x16x32_bf16 v[102:105], v[170:173], v[194:197], v[102:105]
	v_mfma_f32_16x16x32_bf16 v[98:101], v[178:181], v[194:197], v[98:101]
	v_mfma_f32_16x16x32_bf16 v[86:89], v[170:173], v[202:205], v[86:89]
	v_mfma_f32_16x16x32_bf16 v[82:85], v[178:181], v[202:205], v[82:85]
	v_mfma_f32_16x16x32_bf16 v[70:73], v[170:173], v[210:213], v[70:73]
	v_mfma_f32_16x16x32_bf16 v[66:69], v[178:181], v[210:213], v[66:69]
	v_mfma_f32_16x16x32_bf16 v[118:121], v[174:177], v[190:193], v[118:121]
	v_mfma_f32_16x16x32_bf16 v[114:117], v[182:185], v[190:193], v[114:117]
	v_mfma_f32_16x16x32_bf16 v[102:105], v[174:177], v[198:201], v[102:105]
	v_mfma_f32_16x16x32_bf16 v[98:101], v[182:185], v[198:201], v[98:101]
	v_mfma_f32_16x16x32_bf16 v[86:89], v[174:177], v[206:209], v[86:89]
	v_mfma_f32_16x16x32_bf16 v[82:85], v[182:185], v[206:209], v[82:85]
	v_mfma_f32_16x16x32_bf16 v[70:73], v[174:177], v[214:217], v[70:73]
	s_setprio 2
	s_barrier
; #define PG8_STAGE(bufoff, gbase, voff) do { _Pragma("unroll") for (int _i = 0; _i < 2; ++_i) \
;         asm volatile("s_mov_b32 m0, %2\n\ts_nop 0\n\tglobal_load_lds_dwordx4 %0, %1" :: "v"((voff)[_i]), "s"((const char*)(gbase)), "s"(ldsbase + (unsigned)(bufoff) + ldsw + (unsigned)_i * 8192u) : "memory", "m0"); } while (0)
; #define PG8_LDA(dst, b, h) do { _Pragma("unroll") for (int m = 0; m < 4; ++m) _Pragma("unroll") for (int k = 0; k < 2; ++k) dst[m][k] = *(const PG8_LAS bf16x8*)(lds + PG8_SA(b, h) + aoff + m * 2048 + k * 1024); } while (0)
; #define PG8_LDB(dst, b, h) do { _Pragma("unroll") for (int n = 0; n < 2; ++n) _Pragma("unroll") for (int k = 0; k < 2; ++k) dst[n][k] = *(const PG8_LAS bf16x8*)(lds + PG8_SB(b, h) + boff + n * 2048 + k * 1024); } while (0)
; #define PG8_MMA(ai, bj, At, Bt) do { __builtin_amdgcn_s_setprio(1); _Pragma("unroll") for (int m = 0; m < 4; ++m) _Pragma("unroll") for (int n = 0; n < 2; ++n) _Pragma("unroll") for (int k = 0; k < 2; ++k) \
;         acc[ai][bj][m][n] = __builtin_amdgcn_mfma_f32_16x16x32_bf16(Bt[n][k], At[m][k], acc[ai][bj][m][n], 0, 0, 0); __builtin_amdgcn_s_setprio(0); } while (0)
; template <class Epi, class Sched, bool ALIGN_EPI = false, bool SP2 = false>
; __device__ __forceinline__ void gemm_phase(PG8_LAS unsigned char* lds, const Gemm g, const Sched& S, const Epi& E) {
;     ...
;             PG8_LDB(B0, 0, 0); PG8_LDB(B1, 0, 1); PG8_SCHED; PG8_LDA(At, 0, 0); PG8_STAGE(PG8_SA(1, 1), a1 + hstep, voffA);
;             PG8_WAIT_V(8); PG8_WAIT_L(0); PG8_BAR; PG8_MMA(0, 0, At, B0); PG8_MMA(0, 1, At, B1); PG8_BAR; PG8_SCHED;
;             PG8_LDA(At, 0, 1); PG8_STAGE(PG8_SB(0, 0), b2, voffB); PG8_STAGE(PG8_SB(0, 1), b2 + hstep, voffB); PG8_STAGE(PG8_SA(0, 0), a2, voffA);
;             PG8_WAIT_V(8); PG8_WAIT_L(0); PG8_BAR; PG8_MMA(1, 0, At, B0); PG8_MMA(1, 1, At, B1); PG8_BAR; PG8_SCHED;
;             PG8_LDB(B0, 1, 0); PG8_LDB(B1, 1, 1); PG8_SCHED; PG8_LDA(At, 1, 0); PG8_STAGE(PG8_SA(0, 1), a2 + hstep, voffA);
;             PG8_WAIT_V(8); PG8_WAIT_L(0); PG8_BAR; PG8_MMA(0, 0, At, B0); PG8_MMA(0, 1, At, B1); PG8_BAR; PG8_SCHED;
;             PG8_LDA(At, 1, 1); PG8_STAGE(PG8_SB(1, 0), b3, voffB); PG8_STAGE(PG8_SB(1, 1), b3 + hstep, voffB); PG8_STAGE(PG8_SA(1, 0), a3, voffA);
;             PG8_WAIT_V(8); PG8_WAIT_L(0); PG8_BAR; PG8_MMA(1, 0, At, B0); PG8_MMA(1, 1, At, B1); PG8_BAR; PG8_SCHED;
	v_mfma_f32_16x16x32_bf16 v[66:69], v[182:185], v[214:217], v[66:69]
	s_setprio 0
	ds_read_b128 v[186:189], v152 offset:49152
	ds_read_b128 v[190:193], v152 offset:50176
	ds_read_b128 v[194:197], v152 offset:51200
	ds_read_b128 v[198:201], v152 offset:52224
	ds_read_b128 v[202:205], v152 offset:53248
	ds_read_b128 v[206:209], v152 offset:54272
	ds_read_b128 v[210:213], v152 offset:55296
	ds_read_b128 v[214:217], v152 offset:56320
	s_mov_b32 m0, s90
	s_nop 0
	global_load_lds_dwordx4 v142, s[76:77]
	s_add_u32 s60, s62, 0x100080
	s_mov_b32 m0, s91
	s_nop 0
	global_load_lds_dwordx4 v144, s[76:77]
	s_addc_u32 s61, s63, 0
	s_mov_b32 m0, s95
	s_nop 0
	global_load_lds_dwordx4 v142, s[60:61]
	s_nop 0
	s_mov_b32 m0, s96
	s_nop 0
	global_load_lds_dwordx4 v144, s[60:61]
	s_nop 0
	s_mov_b32 m0, s92
	s_nop 0
	global_load_lds_dwordx4 v141, s[66:67]
	s_nop 0
	s_mov_b32 m0, s94
	s_nop 0
	global_load_lds_dwordx4 v143, s[66:67]
	s_waitcnt vmcnt(8)
	s_waitcnt lgkmcnt(0)
	s_setprio 1
	s_barrier
	v_mfma_f32_16x16x32_bf16 v[62:65], v[154:157], v[186:189], v[62:65]
	v_mfma_f32_16x16x32_bf16 v[58:61], v[162:165], v[186:189], v[58:61]
	s_waitcnt lgkmcnt(5)
	v_mfma_f32_16x16x32_bf16 v[46:49], v[154:157], v[194:197], v[46:49]
	v_mfma_f32_16x16x32_bf16 v[42:45], v[162:165], v[194:197], v[42:45]
	s_waitcnt lgkmcnt(3)
	v_mfma_f32_16x16x32_bf16 v[30:33], v[154:157], v[202:205], v[30:33]
	v_mfma_f32_16x16x32_bf16 v[26:29], v[162:165], v[202:205], v[26:29]
	s_waitcnt lgkmcnt(1)
	v_mfma_f32_16x16x32_bf16 v[14:17], v[154:157], v[210:213], v[14:17]
	v_mfma_f32_16x16x32_bf16 v[10:13], v[162:165], v[210:213], v[10:13]
	v_mfma_f32_16x16x32_bf16 v[62:65], v[158:161], v[190:193], v[62:65]
	v_mfma_f32_16x16x32_bf16 v[58:61], v[166:169], v[190:193], v[58:61]
	v_mfma_f32_16x16x32_bf16 v[46:49], v[158:161], v[198:201], v[46:49]
	v_mfma_f32_16x16x32_bf16 v[42:45], v[166:169], v[198:201], v[42:45]
	v_mfma_f32_16x16x32_bf16 v[30:33], v[158:161], v[206:209], v[30:33]
	v_mfma_f32_16x16x32_bf16 v[26:29], v[166:169], v[206:209], v[26:29]
	s_waitcnt lgkmcnt(0)
	v_mfma_f32_16x16x32_bf16 v[14:17], v[158:161], v[214:217], v[14:17]
	v_mfma_f32_16x16x32_bf16 v[10:13], v[166:169], v[214:217], v[10:13]
	s_setprio 0
	s_setprio 1
	v_mfma_f32_16x16x32_bf16 v[54:57], v[170:173], v[186:189], v[54:57]
	v_mfma_f32_16x16x32_bf16 v[50:53], v[178:181], v[186:189], v[50:53]
	v_mfma_f32_16x16x32_bf16 v[38:41], v[170:173], v[194:197], v[38:41]
	v_mfma_f32_16x16x32_bf16 v[34:37], v[178:181], v[194:197], v[34:37]
	v_mfma_f32_16x16x32_bf16 v[22:25], v[170:173], v[202:205], v[22:25]
	v_mfma_f32_16x16x32_bf16 v[18:21], v[178:181], v[202:205], v[18:21]
	v_mfma_f32_16x16x32_bf16 v[6:9], v[170:173], v[210:213], v[6:9]
	v_mfma_f32_16x16x32_bf16 v[2:5], v[178:181], v[210:213], v[2:5]
	v_mfma_f32_16x16x32_bf16 v[54:57], v[174:177], v[190:193], v[54:57]
	v_mfma_f32_16x16x32_bf16 v[50:53], v[182:185], v[190:193], v[50:53]
	v_mfma_f32_16x16x32_bf16 v[38:41], v[174:177], v[198:201], v[38:41]
	v_mfma_f32_16x16x32_bf16 v[34:37], v[182:185], v[198:201], v[34:37]
	v_mfma_f32_16x16x32_bf16 v[22:25], v[174:177], v[206:209], v[22:25]
	v_mfma_f32_16x16x32_bf16 v[18:21], v[182:185], v[206:209], v[18:21]
	v_mfma_f32_16x16x32_bf16 v[6:9], v[174:177], v[214:217], v[6:9]
	s_setprio 2
	s_barrier
	v_mfma_f32_16x16x32_bf16 v[2:5], v[182:185], v[214:217], v[2:5]
	s_setprio 0
	s_add_i32 s58, s58, 2
	s_add_u32 s56, s56, 0x100
	s_addc_u32 s57, s57, 0
	s_cmp_gt_u32 s58, 61
	s_cbranch_scc1 .LBB0_316
	s_mov_b64 s[82:83], s[8:9]
	s_branch .LBB0_320

; #define PG8_STAGE(bufoff, gbase, voff) do { _Pragma("unroll") for (int _i = 0; _i < 2; ++_i) \
;         asm volatile("s_mov_b32 m0, %2\n\ts_nop 0\n\tglobal_load_lds_dwordx4 %0, %1" :: "v"((voff)[_i]), "s"((const char*)(gbase)), "s"(ldsbase + (unsigned)(bufoff) + ldsw + (unsigned)_i * 8192u) : "memory", "m0"); } while (0)
; #define PG8_LDA(dst, b, h) do { _Pragma("unroll") for (int m = 0; m < 4; ++m) _Pragma("unroll") for (int k = 0; k < 2; ++k) dst[m][k] = *(const PG8_LAS bf16x8*)(lds + PG8_SA(b, h) + aoff + m * 2048 + k * 1024); } while (0)
; #define PG8_LDB(dst, b, h) do { _Pragma("unroll") for (int n = 0; n < 2; ++n) _Pragma("unroll") for (int k = 0; k < 2; ++k) dst[n][k] = *(const PG8_LAS bf16x8*)(lds + PG8_SB(b, h) + boff + n * 2048 + k * 1024); } while (0)
; #define PG8_MMA(ai, bj, At, Bt) do { __builtin_amdgcn_s_setprio(1); _Pragma("unroll") for (int m = 0; m < 4; ++m) _Pragma("unroll") for (int n = 0; n < 2; ++n) _Pragma("unroll") for (int k = 0; k < 2; ++k) \
;         acc[ai][bj][m][n] = __builtin_amdgcn_mfma_f32_16x16x32_bf16(Bt[n][k], At[m][k], acc[ai][bj][m][n], 0, 0, 0); __builtin_amdgcn_s_setprio(0); } while (0)
; template <class Epi, class Sched, bool ALIGN_EPI = false, bool SP2 = false>
; __device__ __forceinline__ void gemm_phase(PG8_LAS unsigned char* lds, const Gemm g, const Sched& S, const Epi& E) {
;     ...
;             PG8_LDB(B0, 0, 0); PG8_LDB(B1, 0, 1); PG8_SCHED; PG8_LDA(At, 0, 0); PG8_STAGE(PG8_SA(1, 1), a1 + hstep, voffA);
;             PG8_WAIT_V(8); PG8_WAIT_L(0); PG8_BAR; PG8_MMA(0, 0, At, B0); PG8_MMA(0, 1, At, B1); PG8_BAR; PG8_SCHED;
;             PG8_LDA(At, 0, 1); PG8_STAGE(PG8_SB(0, 0), b2, voffB); PG8_STAGE(PG8_SB(0, 1), b2 + hstep, voffB); PG8_STAGE(PG8_SA(0, 0), a2, voffA);
;             PG8_WAIT_V(8); PG8_WAIT_L(0); PG8_BAR; PG8_MMA(1, 0, At, B0); PG8_MMA(1, 1, At, B1); PG8_BAR; PG8_SCHED;
;             PG8_LDB(B0, 1, 0); PG8_LDB(B1, 1, 1); PG8_SCHED; PG8_LDA(At, 1, 0); PG8_STAGE(PG8_SA(0, 1), a2 + hstep, voffA);
;             PG8_WAIT_V(8); PG8_WAIT_L(0); PG8_BAR; PG8_MMA(0, 0, At, B0); PG8_MMA(0, 1, At, B1); PG8_BAR; PG8_SCHED;
;             PG8_LDA(At, 1, 1); PG8_STAGE(PG8_SB(1, 0), b3, voffB); PG8_STAGE(PG8_SB(1, 1), b3 + hstep, voffB); PG8_STAGE(PG8_SA(1, 0), a3, voffA);
;             PG8_WAIT_V(8); PG8_WAIT_L(0); PG8_BAR; PG8_MMA(1, 0, At, B0); PG8_MMA(1, 1, At, B1); PG8_BAR; PG8_SCHED;
.LBB0_620:
	v_add_u32_e32 v3, 0x10000, v199
	ds_read_b128 v[134:137], v3
	ds_read_b128 v[138:141], v3 offset:1024
	ds_read_b128 v[142:145], v3 offset:2048
	ds_read_b128 v[146:149], v3 offset:3072
	v_add_u32_e32 v3, 0x14000, v199
	s_add_u32 s44, s42, 0x100
	ds_read_b128 v[158:161], v3
	ds_read_b128 v[162:165], v3 offset:1024
	ds_read_b128 v[166:169], v3 offset:2048
	ds_read_b128 v[170:173], v3 offset:3072
	s_addc_u32 s45, s43, 0
	s_cmp_eq_u32 s92, 60
	s_cselect_b32 s56, s88, s44
	s_cselect_b32 s57, s23, s45
	s_cselect_b32 s47, s19, s91
	s_cselect_b32 s46, s89, s90
	s_add_u32 s50, s56, 0x80
	s_addc_u32 s51, s57, 0
	s_add_u32 s54, s46, 0x80
	s_addc_u32 s55, s47, 0
	ds_read_b128 v[174:177], v200
	ds_read_b128 v[178:181], v200 offset:1024
	ds_read_b128 v[182:185], v200 offset:2048
	ds_read_b128 v[186:189], v200 offset:3072
	ds_read_b128 v[190:193], v200 offset:4096
	ds_read_b128 v[202:205], v200 offset:5120
	ds_read_b128 v[206:209], v200 offset:6144
	ds_read_b128 v[210:213], v200 offset:7168
	s_add_u32 s42, s42, 0x100080
	s_addc_u32 s43, s43, 0
	s_mov_b32 m0, s85
	s_nop 0
	global_load_lds_dwordx4 v1, s[42:43]
	s_nop 0
	s_mov_b32 m0, s86
	s_nop 0
	global_load_lds_dwordx4 v195, s[42:43]
	s_waitcnt vmcnt(8)
	s_waitcnt lgkmcnt(0)
	s_setprio 1
	s_barrier
	v_mfma_f32_16x16x32_bf16 v[130:133], v[134:137], v[174:177], v[130:133]
	v_mfma_f32_16x16x32_bf16 v[126:129], v[142:145], v[174:177], v[126:129]
	s_waitcnt lgkmcnt(5)
	v_mfma_f32_16x16x32_bf16 v[122:125], v[134:137], v[182:185], v[122:125]
	v_mfma_f32_16x16x32_bf16 v[118:121], v[142:145], v[182:185], v[118:121]
	s_waitcnt lgkmcnt(3)
	v_mfma_f32_16x16x32_bf16 v[114:117], v[134:137], v[190:193], v[114:117]
	v_mfma_f32_16x16x32_bf16 v[110:113], v[142:145], v[190:193], v[110:113]
	s_waitcnt lgkmcnt(1)
	v_mfma_f32_16x16x32_bf16 v[106:109], v[134:137], v[206:209], v[106:109]
	v_mfma_f32_16x16x32_bf16 v[102:105], v[142:145], v[206:209], v[102:105]
	v_mfma_f32_16x16x32_bf16 v[130:133], v[138:141], v[178:181], v[130:133]
	v_mfma_f32_16x16x32_bf16 v[126:129], v[146:149], v[178:181], v[126:129]
	v_mfma_f32_16x16x32_bf16 v[122:125], v[138:141], v[186:189], v[122:125]
	v_mfma_f32_16x16x32_bf16 v[118:121], v[146:149], v[186:189], v[118:121]
	v_mfma_f32_16x16x32_bf16 v[114:117], v[138:141], v[202:205], v[114:117]
	v_mfma_f32_16x16x32_bf16 v[110:113], v[146:149], v[202:205], v[110:113]
	s_waitcnt lgkmcnt(0)
	v_mfma_f32_16x16x32_bf16 v[106:109], v[138:141], v[210:213], v[106:109]
	v_mfma_f32_16x16x32_bf16 v[102:105], v[146:149], v[210:213], v[102:105]
	s_setprio 0
	s_setprio 1
	v_mfma_f32_16x16x32_bf16 v[66:69], v[158:161], v[174:177], v[66:69]
	v_mfma_f32_16x16x32_bf16 v[62:65], v[166:169], v[174:177], v[62:65]
	v_mfma_f32_16x16x32_bf16 v[58:61], v[158:161], v[182:185], v[58:61]
	v_mfma_f32_16x16x32_bf16 v[54:57], v[166:169], v[182:185], v[54:57]
	v_mfma_f32_16x16x32_bf16 v[50:53], v[158:161], v[190:193], v[50:53]
	v_mfma_f32_16x16x32_bf16 v[46:49], v[166:169], v[190:193], v[46:49]
	v_mfma_f32_16x16x32_bf16 v[42:45], v[158:161], v[206:209], v[42:45]
	v_mfma_f32_16x16x32_bf16 v[38:41], v[166:169], v[206:209], v[38:41]
	v_mfma_f32_16x16x32_bf16 v[66:69], v[162:165], v[178:181], v[66:69]
	v_mfma_f32_16x16x32_bf16 v[62:65], v[170:173], v[178:181], v[62:65]
	v_mfma_f32_16x16x32_bf16 v[58:61], v[162:165], v[186:189], v[58:61]
	v_mfma_f32_16x16x32_bf16 v[54:57], v[170:173], v[186:189], v[54:57]
	v_mfma_f32_16x16x32_bf16 v[50:53], v[162:165], v[202:205], v[50:53]
	v_mfma_f32_16x16x32_bf16 v[46:49], v[170:173], v[202:205], v[46:49]
	v_mfma_f32_16x16x32_bf16 v[42:45], v[162:165], v[210:213], v[42:45]
	s_setprio 2
	s_barrier
	v_mfma_f32_16x16x32_bf16 v[38:41], v[170:173], v[210:213], v[38:41]
	s_setprio 0
	ds_read_b128 v[174:177], v200 offset:16384
	ds_read_b128 v[178:181], v200 offset:17408
	ds_read_b128 v[182:185], v200 offset:18432
	ds_read_b128 v[186:189], v200 offset:19456
	ds_read_b128 v[190:193], v200 offset:20480
	ds_read_b128 v[202:205], v200 offset:21504
	ds_read_b128 v[206:209], v200 offset:22528
	ds_read_b128 v[210:213], v200 offset:23552
	s_mov_b32 m0, s63
	s_nop 0
	global_load_lds_dwordx4 v194, s[46:47]
	s_add_u32 s42, s46, 0x100000
	s_mov_b32 m0, s64
	s_nop 0
	global_load_lds_dwordx4 v196, s[46:47]
	s_addc_u32 s43, s47, 0
	s_mov_b32 m0, s65
	s_nop 0
	global_load_lds_dwordx4 v194, s[42:43]
	s_nop 0
	s_mov_b32 m0, s66
	s_nop 0
	global_load_lds_dwordx4 v196, s[42:43]
	s_nop 0
	s_mov_b32 m0, s62
	s_nop 0
	global_load_lds_dwordx4 v1, s[56:57]
	s_nop 0
	s_mov_b32 m0, s67
	s_nop 0
	global_load_lds_dwordx4 v195, s[56:57]
	s_waitcnt vmcnt(8)
	s_waitcnt lgkmcnt(0)
	s_setprio 1
	s_barrier
; #define PG8_STAGE(bufoff, gbase, voff) do { _Pragma("unroll") for (int _i = 0; _i < 2; ++_i) \
;         asm volatile("s_mov_b32 m0, %2\n\ts_nop 0\n\tglobal_load_lds_dwordx4 %0, %1" :: "v"((voff)[_i]), "s"((const char*)(gbase)), "s"(ldsbase + (unsigned)(bufoff) + ldsw + (unsigned)_i * 8192u) : "memory", "m0"); } while (0)
; #define PG8_LDA(dst, b, h) do { _Pragma("unroll") for (int m = 0; m < 4; ++m) _Pragma("unroll") for (int k = 0; k < 2; ++k) dst[m][k] = *(const PG8_LAS bf16x8*)(lds + PG8_SA(b, h) + aoff + m * 2048 + k * 1024); } while (0)
; #define PG8_LDB(dst, b, h) do { _Pragma("unroll") for (int n = 0; n < 2; ++n) _Pragma("unroll") for (int k = 0; k < 2; ++k) dst[n][k] = *(const PG8_LAS bf16x8*)(lds + PG8_SB(b, h) + boff + n * 2048 + k * 1024); } while (0)
; #define PG8_MMA(ai, bj, At, Bt) do { __builtin_amdgcn_s_setprio(1); _Pragma("unroll") for (int m = 0; m < 4; ++m) _Pragma("unroll") for (int n = 0; n < 2; ++n) _Pragma("unroll") for (int k = 0; k < 2; ++k) \
;         acc[ai][bj][m][n] = __builtin_amdgcn_mfma_f32_16x16x32_bf16(Bt[n][k], At[m][k], acc[ai][bj][m][n], 0, 0, 0); __builtin_amdgcn_s_setprio(0); } while (0)
; template <class Epi, class Sched, bool ALIGN_EPI = false, bool SP2 = false>
; __device__ __forceinline__ void gemm_phase(PG8_LAS unsigned char* lds, const Gemm g, const Sched& S, const Epi& E) {
;     ...
;             PG8_LDB(B0, 0, 0); PG8_LDB(B1, 0, 1); PG8_SCHED; PG8_LDA(At, 0, 0); PG8_STAGE(PG8_SA(1, 1), a1 + hstep, voffA);
;             PG8_WAIT_V(8); PG8_WAIT_L(0); PG8_BAR; PG8_MMA(0, 0, At, B0); PG8_MMA(0, 1, At, B1); PG8_BAR; PG8_SCHED;
;             PG8_LDA(At, 0, 1); PG8_STAGE(PG8_SB(0, 0), b2, voffB); PG8_STAGE(PG8_SB(0, 1), b2 + hstep, voffB); PG8_STAGE(PG8_SA(0, 0), a2, voffA);
;             PG8_WAIT_V(8); PG8_WAIT_L(0); PG8_BAR; PG8_MMA(1, 0, At, B0); PG8_MMA(1, 1, At, B1); PG8_BAR; PG8_SCHED;
;             PG8_LDB(B0, 1, 0); PG8_LDB(B1, 1, 1); PG8_SCHED; PG8_LDA(At, 1, 0); PG8_STAGE(PG8_SA(0, 1), a2 + hstep, voffA);
;             PG8_WAIT_V(8); PG8_WAIT_L(0); PG8_BAR; PG8_MMA(0, 0, At, B0); PG8_MMA(0, 1, At, B1); PG8_BAR; PG8_SCHED;
;             PG8_LDA(At, 1, 1); PG8_STAGE(PG8_SB(1, 0), b3, voffB); PG8_STAGE(PG8_SB(1, 1), b3 + hstep, voffB); PG8_STAGE(PG8_SA(1, 0), a3, voffA);
;             PG8_WAIT_V(8); PG8_WAIT_L(0); PG8_BAR; PG8_MMA(1, 0, At, B0); PG8_MMA(1, 1, At, B1); PG8_BAR; PG8_SCHED;
	v_mfma_f32_16x16x32_bf16 v[98:101], v[134:137], v[174:177], v[98:101]
	v_mfma_f32_16x16x32_bf16 v[94:97], v[142:145], v[174:177], v[94:97]
	s_waitcnt lgkmcnt(5)
	v_mfma_f32_16x16x32_bf16 v[90:93], v[134:137], v[182:185], v[90:93]
	v_mfma_f32_16x16x32_bf16 v[86:89], v[142:145], v[182:185], v[86:89]
	s_waitcnt lgkmcnt(3)
	v_mfma_f32_16x16x32_bf16 v[82:85], v[134:137], v[190:193], v[82:85]
	v_mfma_f32_16x16x32_bf16 v[78:81], v[142:145], v[190:193], v[78:81]
	s_waitcnt lgkmcnt(1)
	v_mfma_f32_16x16x32_bf16 v[74:77], v[134:137], v[206:209], v[74:77]
	v_mfma_f32_16x16x32_bf16 v[70:73], v[142:145], v[206:209], v[70:73]
	v_mfma_f32_16x16x32_bf16 v[98:101], v[138:141], v[178:181], v[98:101]
	v_mfma_f32_16x16x32_bf16 v[94:97], v[146:149], v[178:181], v[94:97]
	v_mfma_f32_16x16x32_bf16 v[90:93], v[138:141], v[186:189], v[90:93]
	v_mfma_f32_16x16x32_bf16 v[86:89], v[146:149], v[186:189], v[86:89]
	v_mfma_f32_16x16x32_bf16 v[82:85], v[138:141], v[202:205], v[82:85]
	v_mfma_f32_16x16x32_bf16 v[78:81], v[146:149], v[202:205], v[78:81]
	s_waitcnt lgkmcnt(0)
	v_mfma_f32_16x16x32_bf16 v[74:77], v[138:141], v[210:213], v[74:77]
	v_mfma_f32_16x16x32_bf16 v[70:73], v[146:149], v[210:213], v[70:73]
	s_setprio 0
	s_setprio 1
	v_mfma_f32_16x16x32_bf16 v[34:37], v[158:161], v[174:177], v[34:37]
	v_mfma_f32_16x16x32_bf16 v[30:33], v[166:169], v[174:177], v[30:33]
	v_mfma_f32_16x16x32_bf16 v[26:29], v[158:161], v[182:185], v[26:29]
	v_mfma_f32_16x16x32_bf16 v[22:25], v[166:169], v[182:185], v[22:25]
	v_mfma_f32_16x16x32_bf16 v[18:21], v[158:161], v[190:193], v[18:21]
	v_mfma_f32_16x16x32_bf16 v[14:17], v[166:169], v[190:193], v[14:17]
	v_mfma_f32_16x16x32_bf16 v[10:13], v[158:161], v[206:209], v[10:13]
	v_mfma_f32_16x16x32_bf16 v[4:7], v[166:169], v[206:209], v[6:9]
	v_mfma_f32_16x16x32_bf16 v[34:37], v[162:165], v[178:181], v[34:37]
	v_mfma_f32_16x16x32_bf16 v[30:33], v[170:173], v[178:181], v[30:33]
	v_mfma_f32_16x16x32_bf16 v[26:29], v[162:165], v[186:189], v[26:29]
	v_mfma_f32_16x16x32_bf16 v[22:25], v[170:173], v[186:189], v[22:25]
	v_mfma_f32_16x16x32_bf16 v[18:21], v[162:165], v[202:205], v[18:21]
	v_mfma_f32_16x16x32_bf16 v[14:17], v[170:173], v[202:205], v[14:17]
	v_mfma_f32_16x16x32_bf16 v[10:13], v[162:165], v[210:213], v[10:13]
	s_setprio 2
	s_barrier
	v_mfma_f32_16x16x32_bf16 v[4:7], v[170:173], v[210:213], v[4:7]
	s_setprio 0
	v_add_u32_e32 v3, 0x18000, v199
	ds_read_b128 v[134:137], v3
	ds_read_b128 v[138:141], v3 offset:1024
	ds_read_b128 v[142:145], v3 offset:2048
	ds_read_b128 v[146:149], v3 offset:3072
	v_add_u32_e32 v3, 0x1c000, v199
	ds_read_b128 v[158:161], v3
	ds_read_b128 v[162:165], v3 offset:1024
	ds_read_b128 v[166:169], v3 offset:2048
	ds_read_b128 v[170:173], v3 offset:3072
	ds_read_b128 v[174:177], v200 offset:32768
	ds_read_b128 v[178:181], v200 offset:33792
	ds_read_b128 v[182:185], v200 offset:34816
	ds_read_b128 v[186:189], v200 offset:35840
	ds_read_b128 v[190:193], v200 offset:36864
	ds_read_b128 v[202:205], v200 offset:37888
	ds_read_b128 v[206:209], v200 offset:38912
	ds_read_b128 v[210:213], v200 offset:39936
	s_add_u32 s42, s56, 0x100000
	s_addc_u32 s43, s57, 0
	s_mov_b32 m0, s76
	s_nop 0
	global_load_lds_dwordx4 v1, s[42:43]
	s_nop 0
	s_mov_b32 m0, s77
	s_nop 0
	global_load_lds_dwordx4 v195, s[42:43]
	s_waitcnt vmcnt(8)
	s_waitcnt lgkmcnt(0)
	s_setprio 1
	s_barrier
	v_mfma_f32_16x16x32_bf16 v[130:133], v[134:137], v[174:177], v[130:133]
	v_mfma_f32_16x16x32_bf16 v[126:129], v[142:145], v[174:177], v[126:129]
	s_waitcnt lgkmcnt(5)
	v_mfma_f32_16x16x32_bf16 v[122:125], v[134:137], v[182:185], v[122:125]
	v_mfma_f32_16x16x32_bf16 v[118:121], v[142:145], v[182:185], v[118:121]
	s_waitcnt lgkmcnt(3)
	v_mfma_f32_16x16x32_bf16 v[114:117], v[134:137], v[190:193], v[114:117]
	v_mfma_f32_16x16x32_bf16 v[110:113], v[142:145], v[190:193], v[110:113]
	s_waitcnt lgkmcnt(1)
	v_mfma_f32_16x16x32_bf16 v[106:109], v[134:137], v[206:209], v[106:109]
	v_mfma_f32_16x16x32_bf16 v[102:105], v[142:145], v[206:209], v[102:105]
	v_mfma_f32_16x16x32_bf16 v[130:133], v[138:141], v[178:181], v[130:133]
	v_mfma_f32_16x16x32_bf16 v[126:129], v[146:149], v[178:181], v[126:129]
	v_mfma_f32_16x16x32_bf16 v[122:125], v[138:141], v[186:189], v[122:125]
	v_mfma_f32_16x16x32_bf16 v[118:121], v[146:149], v[186:189], v[118:121]
	v_mfma_f32_16x16x32_bf16 v[114:117], v[138:141], v[202:205], v[114:117]
	v_mfma_f32_16x16x32_bf16 v[110:113], v[146:149], v[202:205], v[110:113]
	s_waitcnt lgkmcnt(0)
	v_mfma_f32_16x16x32_bf16 v[106:109], v[138:141], v[210:213], v[106:109]
	v_mfma_f32_16x16x32_bf16 v[102:105], v[146:149], v[210:213], v[102:105]
	s_setprio 0
	s_setprio 1
	v_mfma_f32_16x16x32_bf16 v[66:69], v[158:161], v[174:177], v[66:69]
	v_mfma_f32_16x16x32_bf16 v[62:65], v[166:169], v[174:177], v[62:65]
	v_mfma_f32_16x16x32_bf16 v[58:61], v[158:161], v[182:185], v[58:61]
	v_mfma_f32_16x16x32_bf16 v[54:57], v[166:169], v[182:185], v[54:57]
	v_mfma_f32_16x16x32_bf16 v[50:53], v[158:161], v[190:193], v[50:53]
	v_mfma_f32_16x16x32_bf16 v[46:49], v[166:169], v[190:193], v[46:49]
	v_mfma_f32_16x16x32_bf16 v[42:45], v[158:161], v[206:209], v[42:45]
	v_mfma_f32_16x16x32_bf16 v[38:41], v[166:169], v[206:209], v[38:41]
	v_mfma_f32_16x16x32_bf16 v[66:69], v[162:165], v[178:181], v[66:69]
	v_mfma_f32_16x16x32_bf16 v[62:65], v[170:173], v[178:181], v[62:65]
	v_mfma_f32_16x16x32_bf16 v[58:61], v[162:165], v[186:189], v[58:61]
	v_mfma_f32_16x16x32_bf16 v[54:57], v[170:173], v[186:189], v[54:57]
	v_mfma_f32_16x16x32_bf16 v[50:53], v[162:165], v[202:205], v[50:53]
	v_mfma_f32_16x16x32_bf16 v[46:49], v[170:173], v[202:205], v[46:49]
	v_mfma_f32_16x16x32_bf16 v[42:45], v[162:165], v[210:213], v[42:45]
	s_setprio 2
	s_barrier
; #define PG8_STAGE(bufoff, gbase, voff) do { _Pragma("unroll") for (int _i = 0; _i < 2; ++_i) \
;         asm volatile("s_mov_b32 m0, %2\n\ts_nop 0\n\tglobal_load_lds_dwordx4 %0, %1" :: "v"((voff)[_i]), "s"((const char*)(gbase)), "s"(ldsbase + (unsigned)(bufoff) + ldsw + (unsigned)_i * 8192u) : "memory", "m0"); } while (0)
; #define PG8_LDA(dst, b, h) do { _Pragma("unroll") for (int m = 0; m < 4; ++m) _Pragma("unroll") for (int k = 0; k < 2; ++k) dst[m][k] = *(const PG8_LAS bf16x8*)(lds + PG8_SA(b, h) + aoff + m * 2048 + k * 1024); } while (0)
; #define PG8_LDB(dst, b, h) do { _Pragma("unroll") for (int n = 0; n < 2; ++n) _Pragma("unroll") for (int k = 0; k < 2; ++k) dst[n][k] = *(const PG8_LAS bf16x8*)(lds + PG8_SB(b, h) + boff + n * 2048 + k * 1024); } while (0)
; #define PG8_MMA(ai, bj, At, Bt) do { __builtin_amdgcn_s_setprio(1); _Pragma("unroll") for (int m = 0; m < 4; ++m) _Pragma("unroll") for (int n = 0; n < 2; ++n) _Pragma("unroll") for (int k = 0; k < 2; ++k) \
;         acc[ai][bj][m][n] = __builtin_amdgcn_mfma_f32_16x16x32_bf16(Bt[n][k], At[m][k], acc[ai][bj][m][n], 0, 0, 0); __builtin_amdgcn_s_setprio(0); } while (0)
; template <class Epi, class Sched, bool ALIGN_EPI = false, bool SP2 = false>
; __device__ __forceinline__ void gemm_phase(PG8_LAS unsigned char* lds, const Gemm g, const Sched& S, const Epi& E) {
;     ...
;             PG8_LDB(B0, 0, 0); PG8_LDB(B1, 0, 1); PG8_SCHED; PG8_LDA(At, 0, 0); PG8_STAGE(PG8_SA(1, 1), a1 + hstep, voffA);
;             PG8_WAIT_V(8); PG8_WAIT_L(0); PG8_BAR; PG8_MMA(0, 0, At, B0); PG8_MMA(0, 1, At, B1); PG8_BAR; PG8_SCHED;
;             PG8_LDA(At, 0, 1); PG8_STAGE(PG8_SB(0, 0), b2, voffB); PG8_STAGE(PG8_SB(0, 1), b2 + hstep, voffB); PG8_STAGE(PG8_SA(0, 0), a2, voffA);
;             PG8_WAIT_V(8); PG8_WAIT_L(0); PG8_BAR; PG8_MMA(1, 0, At, B0); PG8_MMA(1, 1, At, B1); PG8_BAR; PG8_SCHED;
;             PG8_LDB(B0, 1, 0); PG8_LDB(B1, 1, 1); PG8_SCHED; PG8_LDA(At, 1, 0); PG8_STAGE(PG8_SA(0, 1), a2 + hstep, voffA);
;             PG8_WAIT_V(8); PG8_WAIT_L(0); PG8_BAR; PG8_MMA(0, 0, At, B0); PG8_MMA(0, 1, At, B1); PG8_BAR; PG8_SCHED;
;             PG8_LDA(At, 1, 1); PG8_STAGE(PG8_SB(1, 0), b3, voffB); PG8_STAGE(PG8_SB(1, 1), b3 + hstep, voffB); PG8_STAGE(PG8_SA(1, 0), a3, voffA);
;             PG8_WAIT_V(8); PG8_WAIT_L(0); PG8_BAR; PG8_MMA(1, 0, At, B0); PG8_MMA(1, 1, At, B1); PG8_BAR; PG8_SCHED;
	v_mfma_f32_16x16x32_bf16 v[38:41], v[170:173], v[210:213], v[38:41]
	s_setprio 0
	ds_read_b128 v[174:177], v200 offset:49152
	ds_read_b128 v[178:181], v200 offset:50176
	ds_read_b128 v[182:185], v200 offset:51200
	ds_read_b128 v[186:189], v200 offset:52224
	ds_read_b128 v[190:193], v200 offset:53248
	ds_read_b128 v[202:205], v200 offset:54272
	ds_read_b128 v[206:209], v200 offset:55296
	ds_read_b128 v[210:213], v200 offset:56320
	s_mov_b32 m0, s78
	s_nop 0
	global_load_lds_dwordx4 v194, s[54:55]
	s_add_u32 s42, s46, 0x100080
	s_mov_b32 m0, s79
	s_nop 0
	global_load_lds_dwordx4 v196, s[54:55]
	s_addc_u32 s43, s47, 0
	s_mov_b32 m0, s83
	s_nop 0
	global_load_lds_dwordx4 v194, s[42:43]
	s_nop 0
	s_mov_b32 m0, s84
	s_nop 0
	global_load_lds_dwordx4 v196, s[42:43]
	s_nop 0
	s_mov_b32 m0, s80
	s_nop 0
	global_load_lds_dwordx4 v1, s[50:51]
	s_nop 0
	s_mov_b32 m0, s82
	s_nop 0
	global_load_lds_dwordx4 v195, s[50:51]
	s_waitcnt vmcnt(8)
	s_waitcnt lgkmcnt(0)
	s_setprio 1
	s_barrier
	v_mfma_f32_16x16x32_bf16 v[98:101], v[134:137], v[174:177], v[98:101]
	v_mfma_f32_16x16x32_bf16 v[94:97], v[142:145], v[174:177], v[94:97]
	s_waitcnt lgkmcnt(5)
	v_mfma_f32_16x16x32_bf16 v[90:93], v[134:137], v[182:185], v[90:93]
	v_mfma_f32_16x16x32_bf16 v[86:89], v[142:145], v[182:185], v[86:89]
	s_waitcnt lgkmcnt(3)
	v_mfma_f32_16x16x32_bf16 v[82:85], v[134:137], v[190:193], v[82:85]
	v_mfma_f32_16x16x32_bf16 v[78:81], v[142:145], v[190:193], v[78:81]
	s_waitcnt lgkmcnt(1)
	v_mfma_f32_16x16x32_bf16 v[74:77], v[134:137], v[206:209], v[74:77]
	v_mfma_f32_16x16x32_bf16 v[70:73], v[142:145], v[206:209], v[70:73]
	v_mfma_f32_16x16x32_bf16 v[98:101], v[138:141], v[178:181], v[98:101]
	v_mfma_f32_16x16x32_bf16 v[94:97], v[146:149], v[178:181], v[94:97]
	v_mfma_f32_16x16x32_bf16 v[90:93], v[138:141], v[186:189], v[90:93]
	v_mfma_f32_16x16x32_bf16 v[86:89], v[146:149], v[186:189], v[86:89]
	v_mfma_f32_16x16x32_bf16 v[82:85], v[138:141], v[202:205], v[82:85]
	v_mfma_f32_16x16x32_bf16 v[78:81], v[146:149], v[202:205], v[78:81]
	s_waitcnt lgkmcnt(0)
	v_mfma_f32_16x16x32_bf16 v[74:77], v[138:141], v[210:213], v[74:77]
	v_mfma_f32_16x16x32_bf16 v[70:73], v[146:149], v[210:213], v[70:73]
	s_setprio 0
	s_setprio 1
	v_mfma_f32_16x16x32_bf16 v[34:37], v[158:161], v[174:177], v[34:37]
	v_mfma_f32_16x16x32_bf16 v[30:33], v[166:169], v[174:177], v[30:33]
	v_mfma_f32_16x16x32_bf16 v[26:29], v[158:161], v[182:185], v[26:29]
	v_mfma_f32_16x16x32_bf16 v[22:25], v[166:169], v[182:185], v[22:25]
	v_mfma_f32_16x16x32_bf16 v[18:21], v[158:161], v[190:193], v[18:21]
	v_mfma_f32_16x16x32_bf16 v[14:17], v[166:169], v[190:193], v[14:17]
	v_mfma_f32_16x16x32_bf16 v[8:11], v[158:161], v[206:209], v[10:13]
	v_mfma_f32_16x16x32_bf16 v[4:7], v[166:169], v[206:209], v[4:7]
	v_mfma_f32_16x16x32_bf16 v[34:37], v[162:165], v[178:181], v[34:37]
	v_mfma_f32_16x16x32_bf16 v[30:33], v[170:173], v[178:181], v[30:33]
	v_mfma_f32_16x16x32_bf16 v[26:29], v[162:165], v[186:189], v[26:29]
	v_mfma_f32_16x16x32_bf16 v[22:25], v[170:173], v[186:189], v[22:25]
	v_mfma_f32_16x16x32_bf16 v[18:21], v[162:165], v[202:205], v[18:21]
	v_mfma_f32_16x16x32_bf16 v[14:17], v[170:173], v[202:205], v[14:17]
	v_mfma_f32_16x16x32_bf16 v[10:13], v[162:165], v[210:213], v[8:11]
	s_setprio 2
	s_barrier
	v_mfma_f32_16x16x32_bf16 v[6:9], v[170:173], v[210:213], v[4:7]
	s_setprio 0
	s_add_i32 s92, s92, 2
	s_add_u32 s90, s90, 0x100
	s_addc_u32 s91, s91, 0
	s_cmp_gt_u32 s92, 61
	s_cbranch_scc1 .LBB0_622
	s_mov_b64 s[42:43], s[44:45]
	s_cmp_lg_u32 s92, 30
	s_cbranch_scc0 .LBB0_619
	s_branch .LBB0_620

; #define PG8_STAGE(bufoff, gbase, voff) do { _Pragma("unroll") for (int _i = 0; _i < 2; ++_i) \
;         asm volatile("s_mov_b32 m0, %2\n\ts_nop 0\n\tglobal_load_lds_dwordx4 %0, %1" :: "v"((voff)[_i]), "s"((const char*)(gbase)), "s"(ldsbase + (unsigned)(bufoff) + ldsw + (unsigned)_i * 8192u) : "memory", "m0"); } while (0)
; #define PG8_LDA(dst, b, h) do { _Pragma("unroll") for (int m = 0; m < 4; ++m) _Pragma("unroll") for (int k = 0; k < 2; ++k) dst[m][k] = *(const PG8_LAS bf16x8*)(lds + PG8_SA(b, h) + aoff + m * 2048 + k * 1024); } while (0)
; #define PG8_LDB(dst, b, h) do { _Pragma("unroll") for (int n = 0; n < 2; ++n) _Pragma("unroll") for (int k = 0; k < 2; ++k) dst[n][k] = *(const PG8_LAS bf16x8*)(lds + PG8_SB(b, h) + boff + n * 2048 + k * 1024); } while (0)
; #define PG8_MMA(ai, bj, At, Bt) do { __builtin_amdgcn_s_setprio(1); _Pragma("unroll") for (int m = 0; m < 4; ++m) _Pragma("unroll") for (int n = 0; n < 2; ++n) _Pragma("unroll") for (int k = 0; k < 2; ++k) \
;         acc[ai][bj][m][n] = __builtin_amdgcn_mfma_f32_16x16x32_bf16(Bt[n][k], At[m][k], acc[ai][bj][m][n], 0, 0, 0); __builtin_amdgcn_s_setprio(0); } while (0)
; template <class Epi, class Sched, bool ALIGN_EPI = false, bool SP2 = false>
; __device__ __forceinline__ void gemm_phase(PG8_LAS unsigned char* lds, const Gemm g, const Sched& S, const Epi& E) {
;     ...
;             PG8_LDB(B0, 0, 0); PG8_LDB(B1, 0, 1); PG8_SCHED; PG8_LDA(At, 0, 0); PG8_STAGE(PG8_SA(1, 1), a1 + hstep, voffA);
;             PG8_WAIT_V(8); PG8_WAIT_L(0); PG8_BAR; PG8_MMA(0, 0, At, B0); PG8_MMA(0, 1, At, B1); PG8_BAR; PG8_SCHED;
;             PG8_LDA(At, 0, 1); PG8_STAGE(PG8_SB(0, 0), b2, voffB); PG8_STAGE(PG8_SB(0, 1), b2 + hstep, voffB); PG8_STAGE(PG8_SA(0, 0), a2, voffA);
;             PG8_WAIT_V(8); PG8_WAIT_L(0); PG8_BAR; PG8_MMA(1, 0, At, B0); PG8_MMA(1, 1, At, B1); PG8_BAR; PG8_SCHED;
;             PG8_LDB(B0, 1, 0); PG8_LDB(B1, 1, 1); PG8_SCHED; PG8_LDA(At, 1, 0); PG8_STAGE(PG8_SA(0, 1), a2 + hstep, voffA);
;             PG8_WAIT_V(8); PG8_WAIT_L(0); PG8_BAR; PG8_MMA(0, 0, At, B0); PG8_MMA(0, 1, At, B1); PG8_BAR; PG8_SCHED;
;             PG8_LDA(At, 1, 1); PG8_STAGE(PG8_SB(1, 0), b3, voffB); PG8_STAGE(PG8_SB(1, 1), b3 + hstep, voffB); PG8_STAGE(PG8_SA(1, 0), a3, voffA);
;             PG8_WAIT_V(8); PG8_WAIT_L(0); PG8_BAR; PG8_MMA(1, 0, At, B0); PG8_MMA(1, 1, At, B1); PG8_BAR; PG8_SCHED;
.LBB0_698:
	ds_read_b128 v[134:137], v145
	ds_read_b128 v[152:155], v145 offset:1024
	ds_read_b128 v[156:159], v145 offset:2048
	ds_read_b128 v[160:163], v145 offset:3072
	ds_read_b128 v[164:167], v146
	ds_read_b128 v[168:171], v146 offset:1024
	ds_read_b128 v[172:175], v146 offset:2048
	ds_read_b128 v[176:179], v146 offset:3072
	s_cmp_eq_u32 s69, 60
	s_cselect_b32 s48, s41, s53
	s_cselect_b32 s49, s19, s58
	s_cselect_b32 s46, s52, s59
	s_cselect_b32 s47, s17, s68
	s_add_u32 s44, s48, 0x80
	s_addc_u32 s45, s49, 0
	ds_read_b128 v[180:183], v147
	ds_read_b128 v[184:187], v147 offset:1024
	ds_read_b128 v[188:191], v147 offset:2048
	ds_read_b128 v[192:195], v147 offset:3072
	ds_read_b128 v[196:199], v147 offset:4096
	ds_read_b128 v[200:203], v147 offset:5120
	ds_read_b128 v[204:207], v147 offset:6144
	ds_read_b128 v[208:211], v147 offset:7168
	s_mov_b32 m0, s67
	s_nop 0
	global_load_lds_dwordx4 v1, s[42:43]
	s_nop 0
	s_mov_b32 m0, s74
	s_nop 0
	global_load_lds_dwordx4 v141, s[42:43]
	s_waitcnt vmcnt(8)
	s_waitcnt lgkmcnt(0)
	s_setprio 1
	s_barrier
	v_mfma_f32_16x16x32_bf16 v[126:129], v[134:137], v[180:183], v[126:129]
	v_mfma_f32_16x16x32_bf16 v[122:125], v[156:159], v[180:183], v[122:125]
	s_waitcnt lgkmcnt(5)
	v_mfma_f32_16x16x32_bf16 v[110:113], v[134:137], v[188:191], v[110:113]
	v_mfma_f32_16x16x32_bf16 v[106:109], v[156:159], v[188:191], v[106:109]
	s_waitcnt lgkmcnt(3)
	v_mfma_f32_16x16x32_bf16 v[94:97], v[134:137], v[196:199], v[94:97]
	v_mfma_f32_16x16x32_bf16 v[90:93], v[156:159], v[196:199], v[90:93]
	s_waitcnt lgkmcnt(1)
	v_mfma_f32_16x16x32_bf16 v[78:81], v[134:137], v[204:207], v[78:81]
	v_mfma_f32_16x16x32_bf16 v[74:77], v[156:159], v[204:207], v[74:77]
	v_mfma_f32_16x16x32_bf16 v[126:129], v[152:155], v[184:187], v[126:129]
	v_mfma_f32_16x16x32_bf16 v[122:125], v[160:163], v[184:187], v[122:125]
	v_mfma_f32_16x16x32_bf16 v[110:113], v[152:155], v[192:195], v[110:113]
	v_mfma_f32_16x16x32_bf16 v[106:109], v[160:163], v[192:195], v[106:109]
	v_mfma_f32_16x16x32_bf16 v[94:97], v[152:155], v[200:203], v[94:97]
	v_mfma_f32_16x16x32_bf16 v[90:93], v[160:163], v[200:203], v[90:93]
	s_waitcnt lgkmcnt(0)
	v_mfma_f32_16x16x32_bf16 v[78:81], v[152:155], v[208:211], v[78:81]
	v_mfma_f32_16x16x32_bf16 v[74:77], v[160:163], v[208:211], v[74:77]
	s_setprio 0
	s_setprio 1
	v_mfma_f32_16x16x32_bf16 v[118:121], v[164:167], v[180:183], v[118:121]
	v_mfma_f32_16x16x32_bf16 v[114:117], v[172:175], v[180:183], v[114:117]
	v_mfma_f32_16x16x32_bf16 v[102:105], v[164:167], v[188:191], v[102:105]
	v_mfma_f32_16x16x32_bf16 v[98:101], v[172:175], v[188:191], v[98:101]
	v_mfma_f32_16x16x32_bf16 v[86:89], v[164:167], v[196:199], v[86:89]
	v_mfma_f32_16x16x32_bf16 v[82:85], v[172:175], v[196:199], v[82:85]
	v_mfma_f32_16x16x32_bf16 v[70:73], v[164:167], v[204:207], v[70:73]
	v_mfma_f32_16x16x32_bf16 v[66:69], v[172:175], v[204:207], v[66:69]
	v_mfma_f32_16x16x32_bf16 v[118:121], v[168:171], v[184:187], v[118:121]
	v_mfma_f32_16x16x32_bf16 v[114:117], v[176:179], v[184:187], v[114:117]
	v_mfma_f32_16x16x32_bf16 v[102:105], v[168:171], v[192:195], v[102:105]
	v_mfma_f32_16x16x32_bf16 v[98:101], v[176:179], v[192:195], v[98:101]
	v_mfma_f32_16x16x32_bf16 v[86:89], v[168:171], v[200:203], v[86:89]
	v_mfma_f32_16x16x32_bf16 v[82:85], v[176:179], v[200:203], v[82:85]
	v_mfma_f32_16x16x32_bf16 v[70:73], v[168:171], v[208:211], v[70:73]
	s_setprio 2
	s_barrier
	v_mfma_f32_16x16x32_bf16 v[66:69], v[176:179], v[208:211], v[66:69]
	s_setprio 0
	ds_read_b128 v[180:183], v147 offset:16384
	ds_read_b128 v[184:187], v147 offset:17408
	ds_read_b128 v[188:191], v147 offset:18432
	ds_read_b128 v[192:195], v147 offset:19456
	ds_read_b128 v[196:199], v147 offset:20480
	ds_read_b128 v[200:203], v147 offset:21504
	ds_read_b128 v[204:207], v147 offset:22528
	ds_read_b128 v[208:211], v147 offset:23552
	s_mov_b32 m0, s35
	s_nop 0
	global_load_lds_dwordx4 v140, s[46:47]
	s_add_u32 s70, s46, 0x100000
	s_mov_b32 m0, s50
	s_nop 0
	global_load_lds_dwordx4 v142, s[46:47]
	s_addc_u32 s71, s47, 0
	s_mov_b32 m0, s51
	s_nop 0
	global_load_lds_dwordx4 v140, s[70:71]
	s_nop 0
	s_mov_b32 m0, s54
	s_nop 0
	global_load_lds_dwordx4 v142, s[70:71]
	s_nop 0
	s_mov_b32 m0, s3
	s_nop 0
	global_load_lds_dwordx4 v1, s[48:49]
	s_nop 0
	s_mov_b32 m0, s55
	s_nop 0
	global_load_lds_dwordx4 v141, s[48:49]
	s_waitcnt vmcnt(8)
	s_waitcnt lgkmcnt(0)
	s_setprio 1
	s_barrier
	v_mfma_f32_16x16x32_bf16 v[62:65], v[134:137], v[180:183], v[62:65]
	v_mfma_f32_16x16x32_bf16 v[58:61], v[156:159], v[180:183], v[58:61]
	s_waitcnt lgkmcnt(5)
	v_mfma_f32_16x16x32_bf16 v[46:49], v[134:137], v[188:191], v[46:49]
	v_mfma_f32_16x16x32_bf16 v[42:45], v[156:159], v[188:191], v[42:45]
	s_waitcnt lgkmcnt(3)
	v_mfma_f32_16x16x32_bf16 v[30:33], v[134:137], v[196:199], v[30:33]
	v_mfma_f32_16x16x32_bf16 v[26:29], v[156:159], v[196:199], v[26:29]
	s_waitcnt lgkmcnt(1)
	v_mfma_f32_16x16x32_bf16 v[14:17], v[134:137], v[204:207], v[14:17]
	v_mfma_f32_16x16x32_bf16 v[10:13], v[156:159], v[204:207], v[10:13]
	v_mfma_f32_16x16x32_bf16 v[62:65], v[152:155], v[184:187], v[62:65]
	v_mfma_f32_16x16x32_bf16 v[58:61], v[160:163], v[184:187], v[58:61]
	v_mfma_f32_16x16x32_bf16 v[46:49], v[152:155], v[192:195], v[46:49]
	v_mfma_f32_16x16x32_bf16 v[42:45], v[160:163], v[192:195], v[42:45]
	v_mfma_f32_16x16x32_bf16 v[30:33], v[152:155], v[200:203], v[30:33]
	v_mfma_f32_16x16x32_bf16 v[26:29], v[160:163], v[200:203], v[26:29]
	s_waitcnt lgkmcnt(0)
	v_mfma_f32_16x16x32_bf16 v[14:17], v[152:155], v[208:211], v[14:17]
	v_mfma_f32_16x16x32_bf16 v[10:13], v[160:163], v[208:211], v[10:13]
	s_setprio 0
	s_setprio 1
	v_mfma_f32_16x16x32_bf16 v[54:57], v[164:167], v[180:183], v[54:57]
	v_mfma_f32_16x16x32_bf16 v[50:53], v[172:175], v[180:183], v[50:53]
	v_mfma_f32_16x16x32_bf16 v[38:41], v[164:167], v[188:191], v[38:41]
	v_mfma_f32_16x16x32_bf16 v[34:37], v[172:175], v[188:191], v[34:37]
	v_mfma_f32_16x16x32_bf16 v[22:25], v[164:167], v[196:199], v[22:25]
	v_mfma_f32_16x16x32_bf16 v[18:21], v[172:175], v[196:199], v[18:21]
	v_mfma_f32_16x16x32_bf16 v[6:9], v[164:167], v[204:207], v[6:9]
	v_mfma_f32_16x16x32_bf16 v[2:5], v[172:175], v[204:207], v[2:5]
	v_mfma_f32_16x16x32_bf16 v[54:57], v[168:171], v[184:187], v[54:57]
	v_mfma_f32_16x16x32_bf16 v[50:53], v[176:179], v[184:187], v[50:53]
	v_mfma_f32_16x16x32_bf16 v[38:41], v[168:171], v[192:195], v[38:41]
	v_mfma_f32_16x16x32_bf16 v[34:37], v[176:179], v[192:195], v[34:37]
	v_mfma_f32_16x16x32_bf16 v[22:25], v[168:171], v[200:203], v[22:25]
	v_mfma_f32_16x16x32_bf16 v[18:21], v[176:179], v[200:203], v[18:21]
	v_mfma_f32_16x16x32_bf16 v[6:9], v[168:171], v[208:211], v[6:9]
	s_setprio 2
	s_barrier
; #define PG8_STAGE(bufoff, gbase, voff) do { _Pragma("unroll") for (int _i = 0; _i < 2; ++_i) \
;         asm volatile("s_mov_b32 m0, %2\n\ts_nop 0\n\tglobal_load_lds_dwordx4 %0, %1" :: "v"((voff)[_i]), "s"((const char*)(gbase)), "s"(ldsbase + (unsigned)(bufoff) + ldsw + (unsigned)_i * 8192u) : "memory", "m0"); } while (0)
; #define PG8_LDA(dst, b, h) do { _Pragma("unroll") for (int m = 0; m < 4; ++m) _Pragma("unroll") for (int k = 0; k < 2; ++k) dst[m][k] = *(const PG8_LAS bf16x8*)(lds + PG8_SA(b, h) + aoff + m * 2048 + k * 1024); } while (0)
; #define PG8_LDB(dst, b, h) do { _Pragma("unroll") for (int n = 0; n < 2; ++n) _Pragma("unroll") for (int k = 0; k < 2; ++k) dst[n][k] = *(const PG8_LAS bf16x8*)(lds + PG8_SB(b, h) + boff + n * 2048 + k * 1024); } while (0)
; #define PG8_MMA(ai, bj, At, Bt) do { __builtin_amdgcn_s_setprio(1); _Pragma("unroll") for (int m = 0; m < 4; ++m) _Pragma("unroll") for (int n = 0; n < 2; ++n) _Pragma("unroll") for (int k = 0; k < 2; ++k) \
;         acc[ai][bj][m][n] = __builtin_amdgcn_mfma_f32_16x16x32_bf16(Bt[n][k], At[m][k], acc[ai][bj][m][n], 0, 0, 0); __builtin_amdgcn_s_setprio(0); } while (0)
; template <class Epi, class Sched, bool ALIGN_EPI = false, bool SP2 = false>
; __device__ __forceinline__ void gemm_phase(PG8_LAS unsigned char* lds, const Gemm g, const Sched& S, const Epi& E) {
;     ...
;             PG8_LDB(B0, 0, 0); PG8_LDB(B1, 0, 1); PG8_SCHED; PG8_LDA(At, 0, 0); PG8_STAGE(PG8_SA(1, 1), a1 + hstep, voffA);
;             PG8_WAIT_V(8); PG8_WAIT_L(0); PG8_BAR; PG8_MMA(0, 0, At, B0); PG8_MMA(0, 1, At, B1); PG8_BAR; PG8_SCHED;
;             PG8_LDA(At, 0, 1); PG8_STAGE(PG8_SB(0, 0), b2, voffB); PG8_STAGE(PG8_SB(0, 1), b2 + hstep, voffB); PG8_STAGE(PG8_SA(0, 0), a2, voffA);
;             PG8_WAIT_V(8); PG8_WAIT_L(0); PG8_BAR; PG8_MMA(1, 0, At, B0); PG8_MMA(1, 1, At, B1); PG8_BAR; PG8_SCHED;
;             PG8_LDB(B0, 1, 0); PG8_LDB(B1, 1, 1); PG8_SCHED; PG8_LDA(At, 1, 0); PG8_STAGE(PG8_SA(0, 1), a2 + hstep, voffA);
;             PG8_WAIT_V(8); PG8_WAIT_L(0); PG8_BAR; PG8_MMA(0, 0, At, B0); PG8_MMA(0, 1, At, B1); PG8_BAR; PG8_SCHED;
;             PG8_LDA(At, 1, 1); PG8_STAGE(PG8_SB(1, 0), b3, voffB); PG8_STAGE(PG8_SB(1, 1), b3 + hstep, voffB); PG8_STAGE(PG8_SA(1, 0), a3, voffA);
;             PG8_WAIT_V(8); PG8_WAIT_L(0); PG8_BAR; PG8_MMA(1, 0, At, B0); PG8_MMA(1, 1, At, B1); PG8_BAR; PG8_SCHED;
	v_mfma_f32_16x16x32_bf16 v[2:5], v[176:179], v[208:211], v[2:5]
	s_setprio 0
	ds_read_b128 v[134:137], v148
	ds_read_b128 v[152:155], v148 offset:1024
	ds_read_b128 v[156:159], v148 offset:2048
	ds_read_b128 v[160:163], v148 offset:3072
	ds_read_b128 v[164:167], v149
	ds_read_b128 v[168:171], v149 offset:1024
	ds_read_b128 v[172:175], v149 offset:2048
	ds_read_b128 v[176:179], v149 offset:3072
	ds_read_b128 v[180:183], v147 offset:32768
	ds_read_b128 v[184:187], v147 offset:33792
	ds_read_b128 v[188:191], v147 offset:34816
	ds_read_b128 v[192:195], v147 offset:35840
	ds_read_b128 v[196:199], v147 offset:36864
	ds_read_b128 v[200:203], v147 offset:37888
	ds_read_b128 v[204:207], v147 offset:38912
	ds_read_b128 v[208:211], v147 offset:39936
	s_add_u32 s48, s48, 0x100000
	s_addc_u32 s49, s49, 0
	s_mov_b32 m0, s56
	s_nop 0
	global_load_lds_dwordx4 v1, s[48:49]
	s_nop 0
	s_mov_b32 m0, s57
	s_nop 0
	global_load_lds_dwordx4 v141, s[48:49]
	s_waitcnt vmcnt(8)
	s_waitcnt lgkmcnt(0)
	s_setprio 1
	s_barrier
	v_mfma_f32_16x16x32_bf16 v[126:129], v[134:137], v[180:183], v[126:129]
	v_mfma_f32_16x16x32_bf16 v[122:125], v[156:159], v[180:183], v[122:125]
	s_waitcnt lgkmcnt(5)
	v_mfma_f32_16x16x32_bf16 v[110:113], v[134:137], v[188:191], v[110:113]
	v_mfma_f32_16x16x32_bf16 v[106:109], v[156:159], v[188:191], v[106:109]
	s_waitcnt lgkmcnt(3)
	v_mfma_f32_16x16x32_bf16 v[94:97], v[134:137], v[196:199], v[94:97]
	v_mfma_f32_16x16x32_bf16 v[90:93], v[156:159], v[196:199], v[90:93]
	s_waitcnt lgkmcnt(1)
	v_mfma_f32_16x16x32_bf16 v[78:81], v[134:137], v[204:207], v[78:81]
	v_mfma_f32_16x16x32_bf16 v[74:77], v[156:159], v[204:207], v[74:77]
	v_mfma_f32_16x16x32_bf16 v[126:129], v[152:155], v[184:187], v[126:129]
	v_mfma_f32_16x16x32_bf16 v[122:125], v[160:163], v[184:187], v[122:125]
	v_mfma_f32_16x16x32_bf16 v[110:113], v[152:155], v[192:195], v[110:113]
	v_mfma_f32_16x16x32_bf16 v[106:109], v[160:163], v[192:195], v[106:109]
	v_mfma_f32_16x16x32_bf16 v[94:97], v[152:155], v[200:203], v[94:97]
	v_mfma_f32_16x16x32_bf16 v[90:93], v[160:163], v[200:203], v[90:93]
	s_waitcnt lgkmcnt(0)
	v_mfma_f32_16x16x32_bf16 v[78:81], v[152:155], v[208:211], v[78:81]
	v_mfma_f32_16x16x32_bf16 v[74:77], v[160:163], v[208:211], v[74:77]
	s_setprio 0
	s_setprio 1
	v_mfma_f32_16x16x32_bf16 v[118:121], v[164:167], v[180:183], v[118:121]
	v_mfma_f32_16x16x32_bf16 v[114:117], v[172:175], v[180:183], v[114:117]
	v_mfma_f32_16x16x32_bf16 v[102:105], v[164:167], v[188:191], v[102:105]
	v_mfma_f32_16x16x32_bf16 v[98:101], v[172:175], v[188:191], v[98:101]
	v_mfma_f32_16x16x32_bf16 v[86:89], v[164:167], v[196:199], v[86:89]
	v_mfma_f32_16x16x32_bf16 v[82:85], v[172:175], v[196:199], v[82:85]
	v_mfma_f32_16x16x32_bf16 v[70:73], v[164:167], v[204:207], v[70:73]
	v_mfma_f32_16x16x32_bf16 v[66:69], v[172:175], v[204:207], v[66:69]
	v_mfma_f32_16x16x32_bf16 v[118:121], v[168:171], v[184:187], v[118:121]
	v_mfma_f32_16x16x32_bf16 v[114:117], v[176:179], v[184:187], v[114:117]
	v_mfma_f32_16x16x32_bf16 v[102:105], v[168:171], v[192:195], v[102:105]
	v_mfma_f32_16x16x32_bf16 v[98:101], v[176:179], v[192:195], v[98:101]
	v_mfma_f32_16x16x32_bf16 v[86:89], v[168:171], v[200:203], v[86:89]
	v_mfma_f32_16x16x32_bf16 v[82:85], v[176:179], v[200:203], v[82:85]
	v_mfma_f32_16x16x32_bf16 v[70:73], v[168:171], v[208:211], v[70:73]
	s_setprio 2
	s_barrier
	v_mfma_f32_16x16x32_bf16 v[66:69], v[176:179], v[208:211], v[66:69]
	s_setprio 0
	ds_read_b128 v[180:183], v147 offset:49152
	ds_read_b128 v[184:187], v147 offset:50176
	ds_read_b128 v[188:191], v147 offset:51200
	ds_read_b128 v[192:195], v147 offset:52224
	ds_read_b128 v[196:199], v147 offset:53248
	ds_read_b128 v[200:203], v147 offset:54272
	ds_read_b128 v[204:207], v147 offset:55296
	ds_read_b128 v[208:211], v147 offset:56320
	s_add_u32 s48, s46, 0x80
	s_addc_u32 s49, s47, 0
	s_mov_b32 m0, s61
	s_nop 0
	global_load_lds_dwordx4 v140, s[48:49]
	s_add_u32 s46, s46, 0x100080
	s_mov_b32 m0, s62
	s_nop 0
	global_load_lds_dwordx4 v142, s[48:49]
	s_addc_u32 s47, s47, 0
	s_mov_b32 m0, s65
	s_nop 0
	global_load_lds_dwordx4 v140, s[46:47]
	s_nop 0
	s_mov_b32 m0, s66
	s_nop 0
	global_load_lds_dwordx4 v142, s[46:47]
	s_nop 0
	s_mov_b32 m0, s63
	s_nop 0
	global_load_lds_dwordx4 v1, s[44:45]
	s_nop 0
	s_mov_b32 m0, s64
	s_nop 0
	global_load_lds_dwordx4 v141, s[44:45]
	s_waitcnt vmcnt(8)
	s_waitcnt lgkmcnt(0)
	s_setprio 1
	s_barrier
	v_mfma_f32_16x16x32_bf16 v[62:65], v[134:137], v[180:183], v[62:65]
	v_mfma_f32_16x16x32_bf16 v[58:61], v[156:159], v[180:183], v[58:61]
	s_waitcnt lgkmcnt(5)
	v_mfma_f32_16x16x32_bf16 v[46:49], v[134:137], v[188:191], v[46:49]
	v_mfma_f32_16x16x32_bf16 v[42:45], v[156:159], v[188:191], v[42:45]
	s_waitcnt lgkmcnt(3)
	v_mfma_f32_16x16x32_bf16 v[30:33], v[134:137], v[196:199], v[30:33]
	v_mfma_f32_16x16x32_bf16 v[26:29], v[156:159], v[196:199], v[26:29]
	s_waitcnt lgkmcnt(1)
	v_mfma_f32_16x16x32_bf16 v[14:17], v[134:137], v[204:207], v[14:17]
	v_mfma_f32_16x16x32_bf16 v[10:13], v[156:159], v[204:207], v[10:13]
	v_mfma_f32_16x16x32_bf16 v[62:65], v[152:155], v[184:187], v[62:65]
	v_mfma_f32_16x16x32_bf16 v[58:61], v[160:163], v[184:187], v[58:61]
	v_mfma_f32_16x16x32_bf16 v[46:49], v[152:155], v[192:195], v[46:49]
	v_mfma_f32_16x16x32_bf16 v[42:45], v[160:163], v[192:195], v[42:45]
	v_mfma_f32_16x16x32_bf16 v[30:33], v[152:155], v[200:203], v[30:33]
	v_mfma_f32_16x16x32_bf16 v[26:29], v[160:163], v[200:203], v[26:29]
	s_waitcnt lgkmcnt(0)
	v_mfma_f32_16x16x32_bf16 v[14:17], v[152:155], v[208:211], v[14:17]
	v_mfma_f32_16x16x32_bf16 v[10:13], v[160:163], v[208:211], v[10:13]
	s_setprio 0
	s_setprio 1
	v_mfma_f32_16x16x32_bf16 v[54:57], v[164:167], v[180:183], v[54:57]
	v_mfma_f32_16x16x32_bf16 v[50:53], v[172:175], v[180:183], v[50:53]
	v_mfma_f32_16x16x32_bf16 v[38:41], v[164:167], v[188:191], v[38:41]
	v_mfma_f32_16x16x32_bf16 v[34:37], v[172:175], v[188:191], v[34:37]
	v_mfma_f32_16x16x32_bf16 v[22:25], v[164:167], v[196:199], v[22:25]
	v_mfma_f32_16x16x32_bf16 v[18:21], v[172:175], v[196:199], v[18:21]
	v_mfma_f32_16x16x32_bf16 v[6:9], v[164:167], v[204:207], v[6:9]
	v_mfma_f32_16x16x32_bf16 v[2:5], v[172:175], v[204:207], v[2:5]
	v_mfma_f32_16x16x32_bf16 v[54:57], v[168:171], v[184:187], v[54:57]
	v_mfma_f32_16x16x32_bf16 v[50:53], v[176:179], v[184:187], v[50:53]
	v_mfma_f32_16x16x32_bf16 v[38:41], v[168:171], v[192:195], v[38:41]
	v_mfma_f32_16x16x32_bf16 v[34:37], v[176:179], v[192:195], v[34:37]
	v_mfma_f32_16x16x32_bf16 v[22:25], v[168:171], v[200:203], v[22:25]
	v_mfma_f32_16x16x32_bf16 v[18:21], v[176:179], v[200:203], v[18:21]
	v_mfma_f32_16x16x32_bf16 v[6:9], v[168:171], v[208:211], v[6:9]
	s_setprio 2
	s_barrier
	v_mfma_f32_16x16x32_bf16 v[2:5], v[176:179], v[208:211], v[2:5]
	s_setprio 0
	s_add_i32 s69, s69, 2
	s_add_u32 s53, s53, 0x100
	s_addc_u32 s58, s58, 0
	s_add_u32 s59, s59, 0x100
	s_addc_u32 s68, s68, 0
	s_add_u32 s42, s42, 0x100
	s_addc_u32 s43, s43, 0
	s_cmp_gt_u32 s69, 61
	s_cbranch_scc0 .LBB0_698
	s_and_b64 vcc, exec, s[14:15]
	s_cbranch_vccz .LBB0_701
	s_barrier

; #define PG8_STAGE(bufoff, gbase, voff) do { _Pragma("unroll") for (int _i = 0; _i < 2; ++_i) \
;         asm volatile("s_mov_b32 m0, %2\n\ts_nop 0\n\tglobal_load_lds_dwordx4 %0, %1" :: "v"((voff)[_i]), "s"((const char*)(gbase)), "s"(ldsbase + (unsigned)(bufoff) + ldsw + (unsigned)_i * 8192u) : "memory", "m0"); } while (0)
; #define PG8_LDA(dst, b, h) do { _Pragma("unroll") for (int m = 0; m < 4; ++m) _Pragma("unroll") for (int k = 0; k < 2; ++k) dst[m][k] = *(const PG8_LAS bf16x8*)(lds + PG8_SA(b, h) + aoff + m * 2048 + k * 1024); } while (0)
; #define PG8_LDB(dst, b, h) do { _Pragma("unroll") for (int n = 0; n < 2; ++n) _Pragma("unroll") for (int k = 0; k < 2; ++k) dst[n][k] = *(const PG8_LAS bf16x8*)(lds + PG8_SB(b, h) + boff + n * 2048 + k * 1024); } while (0)
; #define PG8_MMA(ai, bj, At, Bt) do { __builtin_amdgcn_s_setprio(1); _Pragma("unroll") for (int m = 0; m < 4; ++m) _Pragma("unroll") for (int n = 0; n < 2; ++n) _Pragma("unroll") for (int k = 0; k < 2; ++k) \
;         acc[ai][bj][m][n] = __builtin_amdgcn_mfma_f32_16x16x32_bf16(Bt[n][k], At[m][k], acc[ai][bj][m][n], 0, 0, 0); __builtin_amdgcn_s_setprio(0); } while (0)
; template <class Epi, class Sched, bool ALIGN_EPI = false, bool SP2 = false>
; __device__ __forceinline__ void gemm_phase(PG8_LAS unsigned char* lds, const Gemm g, const Sched& S, const Epi& E) {
;     ...
;             PG8_LDB(B0, 0, 0); PG8_LDB(B1, 0, 1); PG8_SCHED; PG8_LDA(At, 0, 0); PG8_STAGE(PG8_SA(1, 1), a1 + hstep, voffA);
;             PG8_WAIT_V(8); PG8_WAIT_L(0); PG8_BAR; PG8_MMA(0, 0, At, B0); PG8_MMA(0, 1, At, B1); PG8_BAR; PG8_SCHED;
;             PG8_LDA(At, 0, 1); PG8_STAGE(PG8_SB(0, 0), b2, voffB); PG8_STAGE(PG8_SB(0, 1), b2 + hstep, voffB); PG8_STAGE(PG8_SA(0, 0), a2, voffA);
;             PG8_WAIT_V(8); PG8_WAIT_L(0); PG8_BAR; PG8_MMA(1, 0, At, B0); PG8_MMA(1, 1, At, B1); PG8_BAR; PG8_SCHED;
;             PG8_LDB(B0, 1, 0); PG8_LDB(B1, 1, 1); PG8_SCHED; PG8_LDA(At, 1, 0); PG8_STAGE(PG8_SA(0, 1), a2 + hstep, voffA);
;             PG8_WAIT_V(8); PG8_WAIT_L(0); PG8_BAR; PG8_MMA(0, 0, At, B0); PG8_MMA(0, 1, At, B1); PG8_BAR; PG8_SCHED;
;             PG8_LDA(At, 1, 1); PG8_STAGE(PG8_SB(1, 0), b3, voffB); PG8_STAGE(PG8_SB(1, 1), b3 + hstep, voffB); PG8_STAGE(PG8_SA(1, 0), a3, voffA);
;             PG8_WAIT_V(8); PG8_WAIT_L(0); PG8_BAR; PG8_MMA(1, 0, At, B0); PG8_MMA(1, 1, At, B1); PG8_BAR; PG8_SCHED;
.LBB0_789:
	v_add_u32_e32 v164, 0x10000, v149
	v_add_u32_e32 v180, 0x14000, v149
	s_add_u32 s8, s40, 0x100
	s_waitcnt lgkmcnt(0)
	ds_read_b128 v[152:155], v164
	ds_read_b128 v[156:159], v164 offset:1024
	ds_read_b128 v[160:163], v164 offset:2048
	ds_read_b128 v[164:167], v164 offset:3072
	ds_read_b128 v[168:171], v180
	ds_read_b128 v[172:175], v180 offset:1024
	ds_read_b128 v[176:179], v180 offset:2048
	ds_read_b128 v[180:183], v180 offset:3072
	s_addc_u32 s9, s41, 0
	s_and_b64 s[38:39], s[38:39], exec
	s_cselect_b32 s46, s59, s8
	s_cselect_b32 s47, s17, s9
	s_cselect_b32 s39, s15, s75
	s_cselect_b32 s38, s71, s74
	s_add_u32 s42, s46, 0x80
	s_addc_u32 s43, s47, 0
	s_add_u32 s44, s38, 0x80
	s_addc_u32 s45, s39, 0
	ds_read_b128 v[184:187], v150
	ds_read_b128 v[188:191], v150 offset:1024
	ds_read_b128 v[192:195], v150 offset:2048
	ds_read_b128 v[196:199], v150 offset:3072
	ds_read_b128 v[200:203], v150 offset:4096
	ds_read_b128 v[204:207], v150 offset:5120
	ds_read_b128 v[208:211], v150 offset:6144
	ds_read_b128 v[212:215], v150 offset:7168
	s_add_u32 s40, s40, 0x100080
	s_addc_u32 s41, s41, 0
	s_mov_b32 m0, s64
	s_nop 0
	global_load_lds_dwordx4 v139, s[40:41]
	s_nop 0
	s_mov_b32 m0, s65
	s_nop 0
	global_load_lds_dwordx4 v141, s[40:41]
	s_waitcnt vmcnt(8)
	s_waitcnt lgkmcnt(0)
	s_setprio 1
	s_barrier
	v_mfma_f32_16x16x32_bf16 v[126:129], v[152:155], v[184:187], v[126:129]
	v_mfma_f32_16x16x32_bf16 v[122:125], v[160:163], v[184:187], v[122:125]
	s_waitcnt lgkmcnt(5)
	v_mfma_f32_16x16x32_bf16 v[110:113], v[152:155], v[192:195], v[110:113]
	v_mfma_f32_16x16x32_bf16 v[106:109], v[160:163], v[192:195], v[106:109]
	s_waitcnt lgkmcnt(3)
	v_mfma_f32_16x16x32_bf16 v[94:97], v[152:155], v[200:203], v[94:97]
	v_mfma_f32_16x16x32_bf16 v[90:93], v[160:163], v[200:203], v[90:93]
	s_waitcnt lgkmcnt(1)
	v_mfma_f32_16x16x32_bf16 v[78:81], v[152:155], v[208:211], v[78:81]
	v_mfma_f32_16x16x32_bf16 v[74:77], v[160:163], v[208:211], v[74:77]
	v_mfma_f32_16x16x32_bf16 v[126:129], v[156:159], v[188:191], v[126:129]
	v_mfma_f32_16x16x32_bf16 v[122:125], v[164:167], v[188:191], v[122:125]
	v_mfma_f32_16x16x32_bf16 v[110:113], v[156:159], v[196:199], v[110:113]
	v_mfma_f32_16x16x32_bf16 v[106:109], v[164:167], v[196:199], v[106:109]
	v_mfma_f32_16x16x32_bf16 v[94:97], v[156:159], v[204:207], v[94:97]
	v_mfma_f32_16x16x32_bf16 v[90:93], v[164:167], v[204:207], v[90:93]
	s_waitcnt lgkmcnt(0)
	v_mfma_f32_16x16x32_bf16 v[78:81], v[156:159], v[212:215], v[78:81]
	v_mfma_f32_16x16x32_bf16 v[74:77], v[164:167], v[212:215], v[74:77]
	s_setprio 0
	s_setprio 1
	v_mfma_f32_16x16x32_bf16 v[118:121], v[168:171], v[184:187], v[118:121]
	v_mfma_f32_16x16x32_bf16 v[114:117], v[176:179], v[184:187], v[114:117]
	v_mfma_f32_16x16x32_bf16 v[102:105], v[168:171], v[192:195], v[102:105]
	v_mfma_f32_16x16x32_bf16 v[98:101], v[176:179], v[192:195], v[98:101]
	v_mfma_f32_16x16x32_bf16 v[86:89], v[168:171], v[200:203], v[86:89]
	v_mfma_f32_16x16x32_bf16 v[82:85], v[176:179], v[200:203], v[82:85]
	v_mfma_f32_16x16x32_bf16 v[70:73], v[168:171], v[208:211], v[70:73]
	v_mfma_f32_16x16x32_bf16 v[66:69], v[176:179], v[208:211], v[66:69]
	v_mfma_f32_16x16x32_bf16 v[118:121], v[172:175], v[188:191], v[118:121]
	v_mfma_f32_16x16x32_bf16 v[114:117], v[180:183], v[188:191], v[114:117]
	v_mfma_f32_16x16x32_bf16 v[102:105], v[172:175], v[196:199], v[102:105]
	v_mfma_f32_16x16x32_bf16 v[98:101], v[180:183], v[196:199], v[98:101]
	v_mfma_f32_16x16x32_bf16 v[86:89], v[172:175], v[204:207], v[86:89]
	v_mfma_f32_16x16x32_bf16 v[82:85], v[180:183], v[204:207], v[82:85]
	v_mfma_f32_16x16x32_bf16 v[70:73], v[172:175], v[212:215], v[70:73]
	s_setprio 2
	s_barrier
	v_mfma_f32_16x16x32_bf16 v[66:69], v[180:183], v[212:215], v[66:69]
	s_setprio 0
	ds_read_b128 v[184:187], v150 offset:16384
	ds_read_b128 v[188:191], v150 offset:17408
	ds_read_b128 v[192:195], v150 offset:18432
	ds_read_b128 v[196:199], v150 offset:19456
	ds_read_b128 v[200:203], v150 offset:20480
	ds_read_b128 v[204:207], v150 offset:21504
	ds_read_b128 v[208:211], v150 offset:22528
	ds_read_b128 v[212:215], v150 offset:23552
	s_mov_b32 m0, s49
	s_nop 0
	global_load_lds_dwordx4 v140, s[38:39]
	s_add_u32 s40, s38, 0x100000
	s_mov_b32 m0, s50
	s_nop 0
	global_load_lds_dwordx4 v142, s[38:39]
	s_addc_u32 s41, s39, 0
	s_mov_b32 m0, s51
	s_nop 0
	global_load_lds_dwordx4 v140, s[40:41]
	s_nop 0
	s_mov_b32 m0, s52
	s_nop 0
	global_load_lds_dwordx4 v142, s[40:41]
	s_nop 0
	s_mov_b32 m0, s37
	s_nop 0
	global_load_lds_dwordx4 v139, s[46:47]
	s_nop 0
	s_mov_b32 m0, s53
	s_nop 0
	global_load_lds_dwordx4 v141, s[46:47]
	s_waitcnt vmcnt(8)
	s_waitcnt lgkmcnt(0)
	s_setprio 1
	s_barrier
; #define PG8_STAGE(bufoff, gbase, voff) do { _Pragma("unroll") for (int _i = 0; _i < 2; ++_i) \
;         asm volatile("s_mov_b32 m0, %2\n\ts_nop 0\n\tglobal_load_lds_dwordx4 %0, %1" :: "v"((voff)[_i]), "s"((const char*)(gbase)), "s"(ldsbase + (unsigned)(bufoff) + ldsw + (unsigned)_i * 8192u) : "memory", "m0"); } while (0)
; #define PG8_LDA(dst, b, h) do { _Pragma("unroll") for (int m = 0; m < 4; ++m) _Pragma("unroll") for (int k = 0; k < 2; ++k) dst[m][k] = *(const PG8_LAS bf16x8*)(lds + PG8_SA(b, h) + aoff + m * 2048 + k * 1024); } while (0)
; #define PG8_LDB(dst, b, h) do { _Pragma("unroll") for (int n = 0; n < 2; ++n) _Pragma("unroll") for (int k = 0; k < 2; ++k) dst[n][k] = *(const PG8_LAS bf16x8*)(lds + PG8_SB(b, h) + boff + n * 2048 + k * 1024); } while (0)
; #define PG8_MMA(ai, bj, At, Bt) do { __builtin_amdgcn_s_setprio(1); _Pragma("unroll") for (int m = 0; m < 4; ++m) _Pragma("unroll") for (int n = 0; n < 2; ++n) _Pragma("unroll") for (int k = 0; k < 2; ++k) \
;         acc[ai][bj][m][n] = __builtin_amdgcn_mfma_f32_16x16x32_bf16(Bt[n][k], At[m][k], acc[ai][bj][m][n], 0, 0, 0); __builtin_amdgcn_s_setprio(0); } while (0)
; template <class Epi, class Sched, bool ALIGN_EPI = false, bool SP2 = false>
; __device__ __forceinline__ void gemm_phase(PG8_LAS unsigned char* lds, const Gemm g, const Sched& S, const Epi& E) {
;     ...
;             PG8_LDB(B0, 0, 0); PG8_LDB(B1, 0, 1); PG8_SCHED; PG8_LDA(At, 0, 0); PG8_STAGE(PG8_SA(1, 1), a1 + hstep, voffA);
;             PG8_WAIT_V(8); PG8_WAIT_L(0); PG8_BAR; PG8_MMA(0, 0, At, B0); PG8_MMA(0, 1, At, B1); PG8_BAR; PG8_SCHED;
;             PG8_LDA(At, 0, 1); PG8_STAGE(PG8_SB(0, 0), b2, voffB); PG8_STAGE(PG8_SB(0, 1), b2 + hstep, voffB); PG8_STAGE(PG8_SA(0, 0), a2, voffA);
;             PG8_WAIT_V(8); PG8_WAIT_L(0); PG8_BAR; PG8_MMA(1, 0, At, B0); PG8_MMA(1, 1, At, B1); PG8_BAR; PG8_SCHED;
;             PG8_LDB(B0, 1, 0); PG8_LDB(B1, 1, 1); PG8_SCHED; PG8_LDA(At, 1, 0); PG8_STAGE(PG8_SA(0, 1), a2 + hstep, voffA);
;             PG8_WAIT_V(8); PG8_WAIT_L(0); PG8_BAR; PG8_MMA(0, 0, At, B0); PG8_MMA(0, 1, At, B1); PG8_BAR; PG8_SCHED;
;             PG8_LDA(At, 1, 1); PG8_STAGE(PG8_SB(1, 0), b3, voffB); PG8_STAGE(PG8_SB(1, 1), b3 + hstep, voffB); PG8_STAGE(PG8_SA(1, 0), a3, voffA);
;             PG8_WAIT_V(8); PG8_WAIT_L(0); PG8_BAR; PG8_MMA(1, 0, At, B0); PG8_MMA(1, 1, At, B1); PG8_BAR; PG8_SCHED;
	v_mfma_f32_16x16x32_bf16 v[62:65], v[152:155], v[184:187], v[62:65]
	v_mfma_f32_16x16x32_bf16 v[58:61], v[160:163], v[184:187], v[58:61]
	s_waitcnt lgkmcnt(5)
	v_mfma_f32_16x16x32_bf16 v[46:49], v[152:155], v[192:195], v[46:49]
	v_mfma_f32_16x16x32_bf16 v[42:45], v[160:163], v[192:195], v[42:45]
	s_waitcnt lgkmcnt(3)
	v_mfma_f32_16x16x32_bf16 v[30:33], v[152:155], v[200:203], v[30:33]
	v_mfma_f32_16x16x32_bf16 v[26:29], v[160:163], v[200:203], v[26:29]
	s_waitcnt lgkmcnt(1)
	v_mfma_f32_16x16x32_bf16 v[14:17], v[152:155], v[208:211], v[14:17]
	v_mfma_f32_16x16x32_bf16 v[10:13], v[160:163], v[208:211], v[10:13]
	v_mfma_f32_16x16x32_bf16 v[62:65], v[156:159], v[188:191], v[62:65]
	v_mfma_f32_16x16x32_bf16 v[58:61], v[164:167], v[188:191], v[58:61]
	v_mfma_f32_16x16x32_bf16 v[46:49], v[156:159], v[196:199], v[46:49]
	v_mfma_f32_16x16x32_bf16 v[42:45], v[164:167], v[196:199], v[42:45]
	v_mfma_f32_16x16x32_bf16 v[30:33], v[156:159], v[204:207], v[30:33]
	v_mfma_f32_16x16x32_bf16 v[26:29], v[164:167], v[204:207], v[26:29]
	s_waitcnt lgkmcnt(0)
	v_mfma_f32_16x16x32_bf16 v[14:17], v[156:159], v[212:215], v[14:17]
	v_mfma_f32_16x16x32_bf16 v[10:13], v[164:167], v[212:215], v[10:13]
	s_setprio 0
	s_setprio 1
	v_mfma_f32_16x16x32_bf16 v[54:57], v[168:171], v[184:187], v[54:57]
	v_mfma_f32_16x16x32_bf16 v[50:53], v[176:179], v[184:187], v[50:53]
	v_mfma_f32_16x16x32_bf16 v[38:41], v[168:171], v[192:195], v[38:41]
	v_mfma_f32_16x16x32_bf16 v[34:37], v[176:179], v[192:195], v[34:37]
	v_mfma_f32_16x16x32_bf16 v[22:25], v[168:171], v[200:203], v[22:25]
	v_mfma_f32_16x16x32_bf16 v[18:21], v[176:179], v[200:203], v[18:21]
	v_mfma_f32_16x16x32_bf16 v[6:9], v[168:171], v[208:211], v[6:9]
	v_mfma_f32_16x16x32_bf16 v[2:5], v[176:179], v[208:211], v[2:5]
	v_mfma_f32_16x16x32_bf16 v[54:57], v[172:175], v[188:191], v[54:57]
	v_mfma_f32_16x16x32_bf16 v[50:53], v[180:183], v[188:191], v[50:53]
	v_mfma_f32_16x16x32_bf16 v[38:41], v[172:175], v[196:199], v[38:41]
	v_mfma_f32_16x16x32_bf16 v[34:37], v[180:183], v[196:199], v[34:37]
	v_mfma_f32_16x16x32_bf16 v[22:25], v[172:175], v[204:207], v[22:25]
	v_mfma_f32_16x16x32_bf16 v[18:21], v[180:183], v[204:207], v[18:21]
	v_mfma_f32_16x16x32_bf16 v[6:9], v[172:175], v[212:215], v[6:9]
	s_setprio 2
	s_barrier
	v_mfma_f32_16x16x32_bf16 v[2:5], v[180:183], v[212:215], v[2:5]
	s_setprio 0
	v_add_u32_e32 v164, 0x18000, v149
	v_add_u32_e32 v180, 0x1c000, v149
	ds_read_b128 v[152:155], v164
	ds_read_b128 v[156:159], v164 offset:1024
	ds_read_b128 v[160:163], v164 offset:2048
	ds_read_b128 v[164:167], v164 offset:3072
	ds_read_b128 v[168:171], v180
	ds_read_b128 v[172:175], v180 offset:1024
	ds_read_b128 v[176:179], v180 offset:2048
	ds_read_b128 v[180:183], v180 offset:3072
	ds_read_b128 v[184:187], v150 offset:32768
	ds_read_b128 v[188:191], v150 offset:33792
	ds_read_b128 v[192:195], v150 offset:34816
	ds_read_b128 v[196:199], v150 offset:35840
	ds_read_b128 v[200:203], v150 offset:36864
	ds_read_b128 v[204:207], v150 offset:37888
	ds_read_b128 v[208:211], v150 offset:38912
	ds_read_b128 v[212:215], v150 offset:39936
	s_add_u32 s40, s46, 0x100000
	s_addc_u32 s41, s47, 0
	s_mov_b32 m0, s54
	s_nop 0
	global_load_lds_dwordx4 v139, s[40:41]
	s_nop 0
	s_mov_b32 m0, s55
	s_nop 0
	global_load_lds_dwordx4 v141, s[40:41]
	s_waitcnt vmcnt(8)
	s_waitcnt lgkmcnt(0)
	s_setprio 1
	s_barrier
	v_mfma_f32_16x16x32_bf16 v[126:129], v[152:155], v[184:187], v[126:129]
	v_mfma_f32_16x16x32_bf16 v[122:125], v[160:163], v[184:187], v[122:125]
	s_waitcnt lgkmcnt(5)
	v_mfma_f32_16x16x32_bf16 v[110:113], v[152:155], v[192:195], v[110:113]
	v_mfma_f32_16x16x32_bf16 v[106:109], v[160:163], v[192:195], v[106:109]
	s_waitcnt lgkmcnt(3)
	v_mfma_f32_16x16x32_bf16 v[94:97], v[152:155], v[200:203], v[94:97]
	v_mfma_f32_16x16x32_bf16 v[90:93], v[160:163], v[200:203], v[90:93]
	s_waitcnt lgkmcnt(1)
	v_mfma_f32_16x16x32_bf16 v[78:81], v[152:155], v[208:211], v[78:81]
	v_mfma_f32_16x16x32_bf16 v[74:77], v[160:163], v[208:211], v[74:77]
	v_mfma_f32_16x16x32_bf16 v[126:129], v[156:159], v[188:191], v[126:129]
	v_mfma_f32_16x16x32_bf16 v[122:125], v[164:167], v[188:191], v[122:125]
	v_mfma_f32_16x16x32_bf16 v[110:113], v[156:159], v[196:199], v[110:113]
	v_mfma_f32_16x16x32_bf16 v[106:109], v[164:167], v[196:199], v[106:109]
	v_mfma_f32_16x16x32_bf16 v[94:97], v[156:159], v[204:207], v[94:97]
	v_mfma_f32_16x16x32_bf16 v[90:93], v[164:167], v[204:207], v[90:93]
	s_waitcnt lgkmcnt(0)
	v_mfma_f32_16x16x32_bf16 v[78:81], v[156:159], v[212:215], v[78:81]
	v_mfma_f32_16x16x32_bf16 v[74:77], v[164:167], v[212:215], v[74:77]
	s_setprio 0
	s_setprio 1
	v_mfma_f32_16x16x32_bf16 v[118:121], v[168:171], v[184:187], v[118:121]
	v_mfma_f32_16x16x32_bf16 v[114:117], v[176:179], v[184:187], v[114:117]
	v_mfma_f32_16x16x32_bf16 v[102:105], v[168:171], v[192:195], v[102:105]
	v_mfma_f32_16x16x32_bf16 v[98:101], v[176:179], v[192:195], v[98:101]
	v_mfma_f32_16x16x32_bf16 v[86:89], v[168:171], v[200:203], v[86:89]
	v_mfma_f32_16x16x32_bf16 v[82:85], v[176:179], v[200:203], v[82:85]
	v_mfma_f32_16x16x32_bf16 v[70:73], v[168:171], v[208:211], v[70:73]
	v_mfma_f32_16x16x32_bf16 v[66:69], v[176:179], v[208:211], v[66:69]
	v_mfma_f32_16x16x32_bf16 v[118:121], v[172:175], v[188:191], v[118:121]
	v_mfma_f32_16x16x32_bf16 v[114:117], v[180:183], v[188:191], v[114:117]
	v_mfma_f32_16x16x32_bf16 v[102:105], v[172:175], v[196:199], v[102:105]
	v_mfma_f32_16x16x32_bf16 v[98:101], v[180:183], v[196:199], v[98:101]
	v_mfma_f32_16x16x32_bf16 v[86:89], v[172:175], v[204:207], v[86:89]
	v_mfma_f32_16x16x32_bf16 v[82:85], v[180:183], v[204:207], v[82:85]
	v_mfma_f32_16x16x32_bf16 v[70:73], v[172:175], v[212:215], v[70:73]
	s_setprio 2
	s_barrier
; #define PG8_STAGE(bufoff, gbase, voff) do { _Pragma("unroll") for (int _i = 0; _i < 2; ++_i) \
;         asm volatile("s_mov_b32 m0, %2\n\ts_nop 0\n\tglobal_load_lds_dwordx4 %0, %1" :: "v"((voff)[_i]), "s"((const char*)(gbase)), "s"(ldsbase + (unsigned)(bufoff) + ldsw + (unsigned)_i * 8192u) : "memory", "m0"); } while (0)
; #define PG8_LDA(dst, b, h) do { _Pragma("unroll") for (int m = 0; m < 4; ++m) _Pragma("unroll") for (int k = 0; k < 2; ++k) dst[m][k] = *(const PG8_LAS bf16x8*)(lds + PG8_SA(b, h) + aoff + m * 2048 + k * 1024); } while (0)
; #define PG8_LDB(dst, b, h) do { _Pragma("unroll") for (int n = 0; n < 2; ++n) _Pragma("unroll") for (int k = 0; k < 2; ++k) dst[n][k] = *(const PG8_LAS bf16x8*)(lds + PG8_SB(b, h) + boff + n * 2048 + k * 1024); } while (0)
; #define PG8_MMA(ai, bj, At, Bt) do { __builtin_amdgcn_s_setprio(1); _Pragma("unroll") for (int m = 0; m < 4; ++m) _Pragma("unroll") for (int n = 0; n < 2; ++n) _Pragma("unroll") for (int k = 0; k < 2; ++k) \
;         acc[ai][bj][m][n] = __builtin_amdgcn_mfma_f32_16x16x32_bf16(Bt[n][k], At[m][k], acc[ai][bj][m][n], 0, 0, 0); __builtin_amdgcn_s_setprio(0); } while (0)
; template <class Epi, class Sched, bool ALIGN_EPI = false, bool SP2 = false>
; __device__ __forceinline__ void gemm_phase(PG8_LAS unsigned char* lds, const Gemm g, const Sched& S, const Epi& E) {
;     ...
;             PG8_LDB(B0, 0, 0); PG8_LDB(B1, 0, 1); PG8_SCHED; PG8_LDA(At, 0, 0); PG8_STAGE(PG8_SA(1, 1), a1 + hstep, voffA);
;             PG8_WAIT_V(8); PG8_WAIT_L(0); PG8_BAR; PG8_MMA(0, 0, At, B0); PG8_MMA(0, 1, At, B1); PG8_BAR; PG8_SCHED;
;             PG8_LDA(At, 0, 1); PG8_STAGE(PG8_SB(0, 0), b2, voffB); PG8_STAGE(PG8_SB(0, 1), b2 + hstep, voffB); PG8_STAGE(PG8_SA(0, 0), a2, voffA);
;             PG8_WAIT_V(8); PG8_WAIT_L(0); PG8_BAR; PG8_MMA(1, 0, At, B0); PG8_MMA(1, 1, At, B1); PG8_BAR; PG8_SCHED;
;             PG8_LDB(B0, 1, 0); PG8_LDB(B1, 1, 1); PG8_SCHED; PG8_LDA(At, 1, 0); PG8_STAGE(PG8_SA(0, 1), a2 + hstep, voffA);
;             PG8_WAIT_V(8); PG8_WAIT_L(0); PG8_BAR; PG8_MMA(0, 0, At, B0); PG8_MMA(0, 1, At, B1); PG8_BAR; PG8_SCHED;
;             PG8_LDA(At, 1, 1); PG8_STAGE(PG8_SB(1, 0), b3, voffB); PG8_STAGE(PG8_SB(1, 1), b3 + hstep, voffB); PG8_STAGE(PG8_SA(1, 0), a3, voffA);
;             PG8_WAIT_V(8); PG8_WAIT_L(0); PG8_BAR; PG8_MMA(1, 0, At, B0); PG8_MMA(1, 1, At, B1); PG8_BAR; PG8_SCHED;
	v_mfma_f32_16x16x32_bf16 v[66:69], v[180:183], v[212:215], v[66:69]
	s_setprio 0
	ds_read_b128 v[184:187], v150 offset:49152
	ds_read_b128 v[188:191], v150 offset:50176
	ds_read_b128 v[192:195], v150 offset:51200
	ds_read_b128 v[196:199], v150 offset:52224
	ds_read_b128 v[200:203], v150 offset:53248
	ds_read_b128 v[204:207], v150 offset:54272
	ds_read_b128 v[208:211], v150 offset:55296
	ds_read_b128 v[212:215], v150 offset:56320
	s_mov_b32 m0, s56
	s_nop 0
	global_load_lds_dwordx4 v140, s[44:45]
	s_add_u32 s38, s38, 0x100080
	s_mov_b32 m0, s57
	s_nop 0
	global_load_lds_dwordx4 v142, s[44:45]
	s_addc_u32 s39, s39, 0
	s_mov_b32 m0, s62
	s_nop 0
	global_load_lds_dwordx4 v140, s[38:39]
	s_nop 0
	s_mov_b32 m0, s63
	s_nop 0
	global_load_lds_dwordx4 v142, s[38:39]
	s_nop 0
	s_mov_b32 m0, s60
	s_nop 0
	global_load_lds_dwordx4 v139, s[42:43]
	s_nop 0
	s_mov_b32 m0, s61
	s_nop 0
	global_load_lds_dwordx4 v141, s[42:43]
	s_waitcnt vmcnt(8)
	s_waitcnt lgkmcnt(0)
	s_setprio 1
	s_barrier
	v_mfma_f32_16x16x32_bf16 v[62:65], v[152:155], v[184:187], v[62:65]
	v_mfma_f32_16x16x32_bf16 v[58:61], v[160:163], v[184:187], v[58:61]
	s_waitcnt lgkmcnt(5)
	v_mfma_f32_16x16x32_bf16 v[46:49], v[152:155], v[192:195], v[46:49]
	v_mfma_f32_16x16x32_bf16 v[42:45], v[160:163], v[192:195], v[42:45]
	s_waitcnt lgkmcnt(3)
	v_mfma_f32_16x16x32_bf16 v[30:33], v[152:155], v[200:203], v[30:33]
	v_mfma_f32_16x16x32_bf16 v[26:29], v[160:163], v[200:203], v[26:29]
	s_waitcnt lgkmcnt(1)
	v_mfma_f32_16x16x32_bf16 v[14:17], v[152:155], v[208:211], v[14:17]
	v_mfma_f32_16x16x32_bf16 v[10:13], v[160:163], v[208:211], v[10:13]
	v_mfma_f32_16x16x32_bf16 v[62:65], v[156:159], v[188:191], v[62:65]
	v_mfma_f32_16x16x32_bf16 v[58:61], v[164:167], v[188:191], v[58:61]
	v_mfma_f32_16x16x32_bf16 v[46:49], v[156:159], v[196:199], v[46:49]
	v_mfma_f32_16x16x32_bf16 v[42:45], v[164:167], v[196:199], v[42:45]
	v_mfma_f32_16x16x32_bf16 v[30:33], v[156:159], v[204:207], v[30:33]
	v_mfma_f32_16x16x32_bf16 v[26:29], v[164:167], v[204:207], v[26:29]
	s_waitcnt lgkmcnt(0)
	v_mfma_f32_16x16x32_bf16 v[14:17], v[156:159], v[212:215], v[14:17]
	v_mfma_f32_16x16x32_bf16 v[10:13], v[164:167], v[212:215], v[10:13]
	s_setprio 0
	s_setprio 1
	v_mfma_f32_16x16x32_bf16 v[54:57], v[168:171], v[184:187], v[54:57]
	v_mfma_f32_16x16x32_bf16 v[50:53], v[176:179], v[184:187], v[50:53]
	v_mfma_f32_16x16x32_bf16 v[38:41], v[168:171], v[192:195], v[38:41]
	v_mfma_f32_16x16x32_bf16 v[34:37], v[176:179], v[192:195], v[34:37]
	v_mfma_f32_16x16x32_bf16 v[22:25], v[168:171], v[200:203], v[22:25]
	v_mfma_f32_16x16x32_bf16 v[18:21], v[176:179], v[200:203], v[18:21]
	v_mfma_f32_16x16x32_bf16 v[6:9], v[168:171], v[208:211], v[6:9]
	v_mfma_f32_16x16x32_bf16 v[2:5], v[176:179], v[208:211], v[2:5]
	v_mfma_f32_16x16x32_bf16 v[54:57], v[172:175], v[188:191], v[54:57]
	v_mfma_f32_16x16x32_bf16 v[50:53], v[180:183], v[188:191], v[50:53]
	v_mfma_f32_16x16x32_bf16 v[38:41], v[172:175], v[196:199], v[38:41]
	v_mfma_f32_16x16x32_bf16 v[34:37], v[180:183], v[196:199], v[34:37]
	v_mfma_f32_16x16x32_bf16 v[22:25], v[172:175], v[204:207], v[22:25]
	v_mfma_f32_16x16x32_bf16 v[18:21], v[180:183], v[204:207], v[18:21]
	v_mfma_f32_16x16x32_bf16 v[6:9], v[172:175], v[212:215], v[6:9]
	s_setprio 2
	s_barrier
	v_mfma_f32_16x16x32_bf16 v[2:5], v[180:183], v[212:215], v[2:5]
	s_setprio 0
	s_add_i32 s76, s76, 2
	s_add_u32 s74, s74, 0x100
	s_addc_u32 s75, s75, 0
	s_cmp_gt_u32 s76, 61
	s_cbranch_scc1 .LBB0_780
	s_mov_b64 s[40:41], s[8:9]
	s_branch .LBB0_784

; #define PG8_STAGE(bufoff, gbase, voff) do { _Pragma("unroll") for (int _i = 0; _i < 2; ++_i) \
;         asm volatile("s_mov_b32 m0, %2\n\ts_nop 0\n\tglobal_load_lds_dwordx4 %0, %1" :: "v"((voff)[_i]), "s"((const char*)(gbase)), "s"(ldsbase + (unsigned)(bufoff) + ldsw + (unsigned)_i * 8192u) : "memory", "m0"); } while (0)
; #define PG8_LDA(dst, b, h) do { _Pragma("unroll") for (int m = 0; m < 4; ++m) _Pragma("unroll") for (int k = 0; k < 2; ++k) dst[m][k] = *(const PG8_LAS bf16x8*)(lds + PG8_SA(b, h) + aoff + m * 2048 + k * 1024); } while (0)
; #define PG8_LDB(dst, b, h) do { _Pragma("unroll") for (int n = 0; n < 2; ++n) _Pragma("unroll") for (int k = 0; k < 2; ++k) dst[n][k] = *(const PG8_LAS bf16x8*)(lds + PG8_SB(b, h) + boff + n * 2048 + k * 1024); } while (0)
; #define PG8_MMA(ai, bj, At, Bt) do { __builtin_amdgcn_s_setprio(1); _Pragma("unroll") for (int m = 0; m < 4; ++m) _Pragma("unroll") for (int n = 0; n < 2; ++n) _Pragma("unroll") for (int k = 0; k < 2; ++k) \
;         acc[ai][bj][m][n] = __builtin_amdgcn_mfma_f32_16x16x32_bf16(Bt[n][k], At[m][k], acc[ai][bj][m][n], 0, 0, 0); __builtin_amdgcn_s_setprio(0); } while (0)
; template <class Epi, class Sched, bool ALIGN_EPI = false, bool SP2 = false>
; __device__ __forceinline__ void gemm_phase(PG8_LAS unsigned char* lds, const Gemm g, const Sched& S, const Epi& E) {
;     ...
;             PG8_LDB(B0, 0, 0); PG8_LDB(B1, 0, 1); PG8_SCHED; PG8_LDA(At, 0, 0); PG8_STAGE(PG8_SA(1, 1), a1 + hstep, voffA);
;             PG8_WAIT_V(8); PG8_WAIT_L(0); PG8_BAR; PG8_MMA(0, 0, At, B0); PG8_MMA(0, 1, At, B1); PG8_BAR; PG8_SCHED;
;             PG8_LDA(At, 0, 1); PG8_STAGE(PG8_SB(0, 0), b2, voffB); PG8_STAGE(PG8_SB(0, 1), b2 + hstep, voffB); PG8_STAGE(PG8_SA(0, 0), a2, voffA);
;             PG8_WAIT_V(8); PG8_WAIT_L(0); PG8_BAR; PG8_MMA(1, 0, At, B0); PG8_MMA(1, 1, At, B1); PG8_BAR; PG8_SCHED;
;             PG8_LDB(B0, 1, 0); PG8_LDB(B1, 1, 1); PG8_SCHED; PG8_LDA(At, 1, 0); PG8_STAGE(PG8_SA(0, 1), a2 + hstep, voffA);
;             PG8_WAIT_V(8); PG8_WAIT_L(0); PG8_BAR; PG8_MMA(0, 0, At, B0); PG8_MMA(0, 1, At, B1); PG8_BAR; PG8_SCHED;
;             PG8_LDA(At, 1, 1); PG8_STAGE(PG8_SB(1, 0), b3, voffB); PG8_STAGE(PG8_SB(1, 1), b3 + hstep, voffB); PG8_STAGE(PG8_SA(1, 0), a3, voffA);
;             PG8_WAIT_V(8); PG8_WAIT_L(0); PG8_BAR; PG8_MMA(1, 0, At, B0); PG8_MMA(1, 1, At, B1); PG8_BAR; PG8_SCHED;
.LBB0_873:
	ds_read_b128 v[134:137], v145
	ds_read_b128 v[150:153], v145 offset:1024
	ds_read_b128 v[154:157], v145 offset:2048
	ds_read_b128 v[158:161], v145 offset:3072
	ds_read_b128 v[162:165], v146
	ds_read_b128 v[166:169], v146 offset:1024
	ds_read_b128 v[170:173], v146 offset:2048
	ds_read_b128 v[174:177], v146 offset:3072
	s_add_u32 s38, s36, 0x100
	s_addc_u32 s39, s37, 0
	s_cmpk_eq_i32 s69, 0xa8
	s_cselect_b32 s44, s4, s38
	s_cselect_b32 s45, s5, s39
	s_cselect_b32 s42, s22, s67
	s_cselect_b32 s43, s23, s68
	s_add_u32 s40, s44, 0x80
	s_addc_u32 s41, s45, 0
	ds_read_b128 v[178:181], v147
	ds_read_b128 v[182:185], v147 offset:1024
	ds_read_b128 v[186:189], v147 offset:2048
	ds_read_b128 v[190:193], v147 offset:3072
	ds_read_b128 v[194:197], v147 offset:4096
	ds_read_b128 v[198:201], v147 offset:5120
	ds_read_b128 v[202:205], v147 offset:6144
	ds_read_b128 v[206:209], v147 offset:7168
	s_add_u32 s36, s36, 0x2b0080
	s_addc_u32 s37, s37, 0
	s_mov_b32 m0, s60
	s_nop 0
	global_load_lds_dwordx4 v1, s[36:37]
	s_nop 0
	s_mov_b32 m0, s61
	s_nop 0
	global_load_lds_dwordx4 v141, s[36:37]
	s_waitcnt vmcnt(8)
	s_waitcnt lgkmcnt(0)
	s_setprio 1
	s_barrier
	v_mfma_f32_16x16x32_bf16 v[126:129], v[134:137], v[178:181], v[126:129]
	v_mfma_f32_16x16x32_bf16 v[122:125], v[154:157], v[178:181], v[122:125]
	s_waitcnt lgkmcnt(5)
	v_mfma_f32_16x16x32_bf16 v[110:113], v[134:137], v[186:189], v[110:113]
	v_mfma_f32_16x16x32_bf16 v[106:109], v[154:157], v[186:189], v[106:109]
	s_waitcnt lgkmcnt(3)
	v_mfma_f32_16x16x32_bf16 v[94:97], v[134:137], v[194:197], v[94:97]
	v_mfma_f32_16x16x32_bf16 v[90:93], v[154:157], v[194:197], v[90:93]
	s_waitcnt lgkmcnt(1)
	v_mfma_f32_16x16x32_bf16 v[78:81], v[134:137], v[202:205], v[78:81]
	v_mfma_f32_16x16x32_bf16 v[74:77], v[154:157], v[202:205], v[74:77]
	v_mfma_f32_16x16x32_bf16 v[126:129], v[150:153], v[182:185], v[126:129]
	v_mfma_f32_16x16x32_bf16 v[122:125], v[158:161], v[182:185], v[122:125]
	v_mfma_f32_16x16x32_bf16 v[110:113], v[150:153], v[190:193], v[110:113]
	v_mfma_f32_16x16x32_bf16 v[106:109], v[158:161], v[190:193], v[106:109]
	v_mfma_f32_16x16x32_bf16 v[94:97], v[150:153], v[198:201], v[94:97]
	v_mfma_f32_16x16x32_bf16 v[90:93], v[158:161], v[198:201], v[90:93]
	s_waitcnt lgkmcnt(0)
	v_mfma_f32_16x16x32_bf16 v[78:81], v[150:153], v[206:209], v[78:81]
	v_mfma_f32_16x16x32_bf16 v[74:77], v[158:161], v[206:209], v[74:77]
	s_setprio 0
	s_setprio 1
	v_mfma_f32_16x16x32_bf16 v[118:121], v[162:165], v[178:181], v[118:121]
	v_mfma_f32_16x16x32_bf16 v[114:117], v[170:173], v[178:181], v[114:117]
	v_mfma_f32_16x16x32_bf16 v[102:105], v[162:165], v[186:189], v[102:105]
	v_mfma_f32_16x16x32_bf16 v[98:101], v[170:173], v[186:189], v[98:101]
	v_mfma_f32_16x16x32_bf16 v[86:89], v[162:165], v[194:197], v[86:89]
	v_mfma_f32_16x16x32_bf16 v[82:85], v[170:173], v[194:197], v[82:85]
	v_mfma_f32_16x16x32_bf16 v[70:73], v[162:165], v[202:205], v[70:73]
	v_mfma_f32_16x16x32_bf16 v[66:69], v[170:173], v[202:205], v[66:69]
	v_mfma_f32_16x16x32_bf16 v[118:121], v[166:169], v[182:185], v[118:121]
	v_mfma_f32_16x16x32_bf16 v[114:117], v[174:177], v[182:185], v[114:117]
	v_mfma_f32_16x16x32_bf16 v[102:105], v[166:169], v[190:193], v[102:105]
	v_mfma_f32_16x16x32_bf16 v[98:101], v[174:177], v[190:193], v[98:101]
	v_mfma_f32_16x16x32_bf16 v[86:89], v[166:169], v[198:201], v[86:89]
	v_mfma_f32_16x16x32_bf16 v[82:85], v[174:177], v[198:201], v[82:85]
	v_mfma_f32_16x16x32_bf16 v[70:73], v[166:169], v[206:209], v[70:73]
	s_setprio 2
	s_barrier
	v_mfma_f32_16x16x32_bf16 v[66:69], v[174:177], v[206:209], v[66:69]
	s_setprio 0
	ds_read_b128 v[178:181], v147 offset:16384
	ds_read_b128 v[182:185], v147 offset:17408
	ds_read_b128 v[186:189], v147 offset:18432
	ds_read_b128 v[190:193], v147 offset:19456
	ds_read_b128 v[194:197], v147 offset:20480
	ds_read_b128 v[198:201], v147 offset:21504
	ds_read_b128 v[202:205], v147 offset:22528
	ds_read_b128 v[206:209], v147 offset:23552
	s_mov_b32 m0, s47
	s_nop 0
	global_load_lds_dwordx4 v140, s[42:43]
	s_add_u32 s36, s42, 0x2b0000
	s_mov_b32 m0, s48
	s_nop 0
	global_load_lds_dwordx4 v142, s[42:43]
	s_addc_u32 s37, s43, 0
	s_mov_b32 m0, s49
	s_nop 0
	global_load_lds_dwordx4 v140, s[36:37]
	s_nop 0
	s_mov_b32 m0, s50
	s_nop 0
	global_load_lds_dwordx4 v142, s[36:37]
	s_nop 0
	s_mov_b32 m0, s46
	s_nop 0
	global_load_lds_dwordx4 v1, s[44:45]
	s_nop 0
	s_mov_b32 m0, s51
	s_nop 0
	global_load_lds_dwordx4 v141, s[44:45]
	s_waitcnt vmcnt(8)
	s_waitcnt lgkmcnt(0)
	s_setprio 1
	s_barrier
	v_mfma_f32_16x16x32_bf16 v[62:65], v[134:137], v[178:181], v[62:65]
	v_mfma_f32_16x16x32_bf16 v[58:61], v[154:157], v[178:181], v[58:61]
	s_waitcnt lgkmcnt(5)
	v_mfma_f32_16x16x32_bf16 v[46:49], v[134:137], v[186:189], v[46:49]
	v_mfma_f32_16x16x32_bf16 v[42:45], v[154:157], v[186:189], v[42:45]
	s_waitcnt lgkmcnt(3)
	v_mfma_f32_16x16x32_bf16 v[30:33], v[134:137], v[194:197], v[30:33]
	v_mfma_f32_16x16x32_bf16 v[26:29], v[154:157], v[194:197], v[26:29]
	s_waitcnt lgkmcnt(1)
	v_mfma_f32_16x16x32_bf16 v[14:17], v[134:137], v[202:205], v[14:17]
	v_mfma_f32_16x16x32_bf16 v[10:13], v[154:157], v[202:205], v[10:13]
	v_mfma_f32_16x16x32_bf16 v[62:65], v[150:153], v[182:185], v[62:65]
	v_mfma_f32_16x16x32_bf16 v[58:61], v[158:161], v[182:185], v[58:61]
	v_mfma_f32_16x16x32_bf16 v[46:49], v[150:153], v[190:193], v[46:49]
	v_mfma_f32_16x16x32_bf16 v[42:45], v[158:161], v[190:193], v[42:45]
	v_mfma_f32_16x16x32_bf16 v[30:33], v[150:153], v[198:201], v[30:33]
	v_mfma_f32_16x16x32_bf16 v[26:29], v[158:161], v[198:201], v[26:29]
	s_waitcnt lgkmcnt(0)
	v_mfma_f32_16x16x32_bf16 v[14:17], v[150:153], v[206:209], v[14:17]
	v_mfma_f32_16x16x32_bf16 v[10:13], v[158:161], v[206:209], v[10:13]
	s_setprio 0
	s_setprio 1
	v_mfma_f32_16x16x32_bf16 v[54:57], v[162:165], v[178:181], v[54:57]
	v_mfma_f32_16x16x32_bf16 v[50:53], v[170:173], v[178:181], v[50:53]
	v_mfma_f32_16x16x32_bf16 v[38:41], v[162:165], v[186:189], v[38:41]
	v_mfma_f32_16x16x32_bf16 v[34:37], v[170:173], v[186:189], v[34:37]
	v_mfma_f32_16x16x32_bf16 v[22:25], v[162:165], v[194:197], v[22:25]
	v_mfma_f32_16x16x32_bf16 v[18:21], v[170:173], v[194:197], v[18:21]
	v_mfma_f32_16x16x32_bf16 v[6:9], v[162:165], v[202:205], v[6:9]
	v_mfma_f32_16x16x32_bf16 v[2:5], v[170:173], v[202:205], v[2:5]
	v_mfma_f32_16x16x32_bf16 v[54:57], v[166:169], v[182:185], v[54:57]
	v_mfma_f32_16x16x32_bf16 v[50:53], v[174:177], v[182:185], v[50:53]
	v_mfma_f32_16x16x32_bf16 v[38:41], v[166:169], v[190:193], v[38:41]
	v_mfma_f32_16x16x32_bf16 v[34:37], v[174:177], v[190:193], v[34:37]
	v_mfma_f32_16x16x32_bf16 v[22:25], v[166:169], v[198:201], v[22:25]
	v_mfma_f32_16x16x32_bf16 v[18:21], v[174:177], v[198:201], v[18:21]
	v_mfma_f32_16x16x32_bf16 v[6:9], v[166:169], v[206:209], v[6:9]
	s_setprio 2
	s_barrier
; #define PG8_STAGE(bufoff, gbase, voff) do { _Pragma("unroll") for (int _i = 0; _i < 2; ++_i) \
;         asm volatile("s_mov_b32 m0, %2\n\ts_nop 0\n\tglobal_load_lds_dwordx4 %0, %1" :: "v"((voff)[_i]), "s"((const char*)(gbase)), "s"(ldsbase + (unsigned)(bufoff) + ldsw + (unsigned)_i * 8192u) : "memory", "m0"); } while (0)
; #define PG8_LDA(dst, b, h) do { _Pragma("unroll") for (int m = 0; m < 4; ++m) _Pragma("unroll") for (int k = 0; k < 2; ++k) dst[m][k] = *(const PG8_LAS bf16x8*)(lds + PG8_SA(b, h) + aoff + m * 2048 + k * 1024); } while (0)
; #define PG8_LDB(dst, b, h) do { _Pragma("unroll") for (int n = 0; n < 2; ++n) _Pragma("unroll") for (int k = 0; k < 2; ++k) dst[n][k] = *(const PG8_LAS bf16x8*)(lds + PG8_SB(b, h) + boff + n * 2048 + k * 1024); } while (0)
; #define PG8_MMA(ai, bj, At, Bt) do { __builtin_amdgcn_s_setprio(1); _Pragma("unroll") for (int m = 0; m < 4; ++m) _Pragma("unroll") for (int n = 0; n < 2; ++n) _Pragma("unroll") for (int k = 0; k < 2; ++k) \
;         acc[ai][bj][m][n] = __builtin_amdgcn_mfma_f32_16x16x32_bf16(Bt[n][k], At[m][k], acc[ai][bj][m][n], 0, 0, 0); __builtin_amdgcn_s_setprio(0); } while (0)
; template <class Epi, class Sched, bool ALIGN_EPI = false, bool SP2 = false>
; __device__ __forceinline__ void gemm_phase(PG8_LAS unsigned char* lds, const Gemm g, const Sched& S, const Epi& E) {
;     ...
;             PG8_LDB(B0, 0, 0); PG8_LDB(B1, 0, 1); PG8_SCHED; PG8_LDA(At, 0, 0); PG8_STAGE(PG8_SA(1, 1), a1 + hstep, voffA);
;             PG8_WAIT_V(8); PG8_WAIT_L(0); PG8_BAR; PG8_MMA(0, 0, At, B0); PG8_MMA(0, 1, At, B1); PG8_BAR; PG8_SCHED;
;             PG8_LDA(At, 0, 1); PG8_STAGE(PG8_SB(0, 0), b2, voffB); PG8_STAGE(PG8_SB(0, 1), b2 + hstep, voffB); PG8_STAGE(PG8_SA(0, 0), a2, voffA);
;             PG8_WAIT_V(8); PG8_WAIT_L(0); PG8_BAR; PG8_MMA(1, 0, At, B0); PG8_MMA(1, 1, At, B1); PG8_BAR; PG8_SCHED;
;             PG8_LDB(B0, 1, 0); PG8_LDB(B1, 1, 1); PG8_SCHED; PG8_LDA(At, 1, 0); PG8_STAGE(PG8_SA(0, 1), a2 + hstep, voffA);
;             PG8_WAIT_V(8); PG8_WAIT_L(0); PG8_BAR; PG8_MMA(0, 0, At, B0); PG8_MMA(0, 1, At, B1); PG8_BAR; PG8_SCHED;
;             PG8_LDA(At, 1, 1); PG8_STAGE(PG8_SB(1, 0), b3, voffB); PG8_STAGE(PG8_SB(1, 1), b3 + hstep, voffB); PG8_STAGE(PG8_SA(1, 0), a3, voffA);
;             PG8_WAIT_V(8); PG8_WAIT_L(0); PG8_BAR; PG8_MMA(1, 0, At, B0); PG8_MMA(1, 1, At, B1); PG8_BAR; PG8_SCHED;
	v_mfma_f32_16x16x32_bf16 v[2:5], v[174:177], v[206:209], v[2:5]
	s_setprio 0
	ds_read_b128 v[134:137], v148
	ds_read_b128 v[150:153], v148 offset:1024
	ds_read_b128 v[154:157], v148 offset:2048
	ds_read_b128 v[158:161], v148 offset:3072
	ds_read_b128 v[162:165], v149
	ds_read_b128 v[166:169], v149 offset:1024
	ds_read_b128 v[170:173], v149 offset:2048
	ds_read_b128 v[174:177], v149 offset:3072
	ds_read_b128 v[178:181], v147 offset:32768
	ds_read_b128 v[182:185], v147 offset:33792
	ds_read_b128 v[186:189], v147 offset:34816
	ds_read_b128 v[190:193], v147 offset:35840
	ds_read_b128 v[194:197], v147 offset:36864
	ds_read_b128 v[198:201], v147 offset:37888
	ds_read_b128 v[202:205], v147 offset:38912
	ds_read_b128 v[206:209], v147 offset:39936
	s_add_u32 s36, s44, 0x2b0000
	s_addc_u32 s37, s45, 0
	s_mov_b32 m0, s52
	s_nop 0
	global_load_lds_dwordx4 v1, s[36:37]
	s_nop 0
	s_mov_b32 m0, s53
	s_nop 0
	global_load_lds_dwordx4 v141, s[36:37]
	s_waitcnt vmcnt(8)
	s_waitcnt lgkmcnt(0)
	s_setprio 1
	s_barrier
	v_mfma_f32_16x16x32_bf16 v[126:129], v[134:137], v[178:181], v[126:129]
	v_mfma_f32_16x16x32_bf16 v[122:125], v[154:157], v[178:181], v[122:125]
	s_waitcnt lgkmcnt(5)
	v_mfma_f32_16x16x32_bf16 v[110:113], v[134:137], v[186:189], v[110:113]
	v_mfma_f32_16x16x32_bf16 v[106:109], v[154:157], v[186:189], v[106:109]
	s_waitcnt lgkmcnt(3)
	v_mfma_f32_16x16x32_bf16 v[94:97], v[134:137], v[194:197], v[94:97]
	v_mfma_f32_16x16x32_bf16 v[90:93], v[154:157], v[194:197], v[90:93]
	s_waitcnt lgkmcnt(1)
	v_mfma_f32_16x16x32_bf16 v[78:81], v[134:137], v[202:205], v[78:81]
	v_mfma_f32_16x16x32_bf16 v[74:77], v[154:157], v[202:205], v[74:77]
	v_mfma_f32_16x16x32_bf16 v[126:129], v[150:153], v[182:185], v[126:129]
	v_mfma_f32_16x16x32_bf16 v[122:125], v[158:161], v[182:185], v[122:125]
	v_mfma_f32_16x16x32_bf16 v[110:113], v[150:153], v[190:193], v[110:113]
	v_mfma_f32_16x16x32_bf16 v[106:109], v[158:161], v[190:193], v[106:109]
	v_mfma_f32_16x16x32_bf16 v[94:97], v[150:153], v[198:201], v[94:97]
	v_mfma_f32_16x16x32_bf16 v[90:93], v[158:161], v[198:201], v[90:93]
	s_waitcnt lgkmcnt(0)
	v_mfma_f32_16x16x32_bf16 v[78:81], v[150:153], v[206:209], v[78:81]
	v_mfma_f32_16x16x32_bf16 v[74:77], v[158:161], v[206:209], v[74:77]
	s_setprio 0
	s_setprio 1
	v_mfma_f32_16x16x32_bf16 v[118:121], v[162:165], v[178:181], v[118:121]
	v_mfma_f32_16x16x32_bf16 v[114:117], v[170:173], v[178:181], v[114:117]
	v_mfma_f32_16x16x32_bf16 v[102:105], v[162:165], v[186:189], v[102:105]
	v_mfma_f32_16x16x32_bf16 v[98:101], v[170:173], v[186:189], v[98:101]
	v_mfma_f32_16x16x32_bf16 v[86:89], v[162:165], v[194:197], v[86:89]
	v_mfma_f32_16x16x32_bf16 v[82:85], v[170:173], v[194:197], v[82:85]
	v_mfma_f32_16x16x32_bf16 v[70:73], v[162:165], v[202:205], v[70:73]
	v_mfma_f32_16x16x32_bf16 v[66:69], v[170:173], v[202:205], v[66:69]
	v_mfma_f32_16x16x32_bf16 v[118:121], v[166:169], v[182:185], v[118:121]
	v_mfma_f32_16x16x32_bf16 v[114:117], v[174:177], v[182:185], v[114:117]
	v_mfma_f32_16x16x32_bf16 v[102:105], v[166:169], v[190:193], v[102:105]
	v_mfma_f32_16x16x32_bf16 v[98:101], v[174:177], v[190:193], v[98:101]
	v_mfma_f32_16x16x32_bf16 v[86:89], v[166:169], v[198:201], v[86:89]
	v_mfma_f32_16x16x32_bf16 v[82:85], v[174:177], v[198:201], v[82:85]
	v_mfma_f32_16x16x32_bf16 v[70:73], v[166:169], v[206:209], v[70:73]
	s_setprio 2
	s_barrier
	v_mfma_f32_16x16x32_bf16 v[66:69], v[174:177], v[206:209], v[66:69]
	s_setprio 0
	ds_read_b128 v[178:181], v147 offset:49152
	ds_read_b128 v[182:185], v147 offset:50176
	ds_read_b128 v[186:189], v147 offset:51200
	ds_read_b128 v[190:193], v147 offset:52224
	ds_read_b128 v[194:197], v147 offset:53248
	ds_read_b128 v[198:201], v147 offset:54272
	ds_read_b128 v[202:205], v147 offset:55296
	ds_read_b128 v[206:209], v147 offset:56320
	s_add_u32 s36, s42, 0x80
	s_addc_u32 s37, s43, 0
	s_mov_b32 m0, s54
	s_nop 0
	global_load_lds_dwordx4 v140, s[36:37]
	s_nop 0
	s_mov_b32 m0, s55
	s_nop 0
	global_load_lds_dwordx4 v142, s[36:37]
	s_add_u32 s36, s42, 0x2b0080
	s_addc_u32 s37, s43, 0
	s_mov_b32 m0, s58
	s_nop 0
	global_load_lds_dwordx4 v140, s[36:37]
	s_nop 0
	s_mov_b32 m0, s59
	s_nop 0
	global_load_lds_dwordx4 v142, s[36:37]
	s_nop 0
	s_mov_b32 m0, s56
	s_nop 0
	global_load_lds_dwordx4 v1, s[40:41]
	s_nop 0
	s_mov_b32 m0, s57
	s_nop 0
	global_load_lds_dwordx4 v141, s[40:41]
	s_waitcnt vmcnt(8)
	s_waitcnt lgkmcnt(0)
	s_setprio 1
	s_barrier
	v_mfma_f32_16x16x32_bf16 v[62:65], v[134:137], v[178:181], v[62:65]
	v_mfma_f32_16x16x32_bf16 v[58:61], v[154:157], v[178:181], v[58:61]
	s_waitcnt lgkmcnt(5)
	v_mfma_f32_16x16x32_bf16 v[46:49], v[134:137], v[186:189], v[46:49]
	v_mfma_f32_16x16x32_bf16 v[42:45], v[154:157], v[186:189], v[42:45]
	s_waitcnt lgkmcnt(3)
	v_mfma_f32_16x16x32_bf16 v[30:33], v[134:137], v[194:197], v[30:33]
	v_mfma_f32_16x16x32_bf16 v[26:29], v[154:157], v[194:197], v[26:29]
	s_waitcnt lgkmcnt(1)
	v_mfma_f32_16x16x32_bf16 v[14:17], v[134:137], v[202:205], v[14:17]
	v_mfma_f32_16x16x32_bf16 v[10:13], v[154:157], v[202:205], v[10:13]
	v_mfma_f32_16x16x32_bf16 v[62:65], v[150:153], v[182:185], v[62:65]
	v_mfma_f32_16x16x32_bf16 v[58:61], v[158:161], v[182:185], v[58:61]
	v_mfma_f32_16x16x32_bf16 v[46:49], v[150:153], v[190:193], v[46:49]
	v_mfma_f32_16x16x32_bf16 v[42:45], v[158:161], v[190:193], v[42:45]
	v_mfma_f32_16x16x32_bf16 v[30:33], v[150:153], v[198:201], v[30:33]
	v_mfma_f32_16x16x32_bf16 v[26:29], v[158:161], v[198:201], v[26:29]
	s_waitcnt lgkmcnt(0)
	v_mfma_f32_16x16x32_bf16 v[14:17], v[150:153], v[206:209], v[14:17]
	v_mfma_f32_16x16x32_bf16 v[10:13], v[158:161], v[206:209], v[10:13]
	s_setprio 0
	s_setprio 1
	v_mfma_f32_16x16x32_bf16 v[54:57], v[162:165], v[178:181], v[54:57]
	v_mfma_f32_16x16x32_bf16 v[50:53], v[170:173], v[178:181], v[50:53]
	v_mfma_f32_16x16x32_bf16 v[38:41], v[162:165], v[186:189], v[38:41]
	v_mfma_f32_16x16x32_bf16 v[34:37], v[170:173], v[186:189], v[34:37]
	v_mfma_f32_16x16x32_bf16 v[22:25], v[162:165], v[194:197], v[22:25]
	v_mfma_f32_16x16x32_bf16 v[18:21], v[170:173], v[194:197], v[18:21]
	v_mfma_f32_16x16x32_bf16 v[6:9], v[162:165], v[202:205], v[6:9]
	v_mfma_f32_16x16x32_bf16 v[2:5], v[170:173], v[202:205], v[2:5]
	v_mfma_f32_16x16x32_bf16 v[54:57], v[166:169], v[182:185], v[54:57]
	v_mfma_f32_16x16x32_bf16 v[50:53], v[174:177], v[182:185], v[50:53]
	v_mfma_f32_16x16x32_bf16 v[38:41], v[166:169], v[190:193], v[38:41]
	v_mfma_f32_16x16x32_bf16 v[34:37], v[174:177], v[190:193], v[34:37]
	v_mfma_f32_16x16x32_bf16 v[22:25], v[166:169], v[198:201], v[22:25]
	v_mfma_f32_16x16x32_bf16 v[18:21], v[174:177], v[198:201], v[18:21]
	v_mfma_f32_16x16x32_bf16 v[6:9], v[166:169], v[206:209], v[6:9]
	s_setprio 2
	s_barrier
	v_mfma_f32_16x16x32_bf16 v[2:5], v[174:177], v[206:209], v[2:5]
	s_setprio 0
	s_add_i32 s69, s69, 2
	s_add_u32 s67, s67, 0x100
	s_addc_u32 s68, s68, 0
	s_cmpk_gt_u32 s69, 0xa9
	s_mov_b64 s[36:37], s[38:39]
	s_cbranch_scc0 .LBB0_873
	s_and_b64 vcc, exec, s[10:11]
	s_cbranch_vccz .LBB0_876
	s_barrier
